# attention: only first-chunk Q fragments loaded ahead of K(0) staging, first chunk wait counted (vmcnt 12)
# baseline (speedup 1.0000x reference)
.LBB0_868:
.LBB0_869:
	s_add_i32 s0, 0, 0x23f94
	s_waitcnt vmcnt(0)
	v_mov_b32_e32 v0, s0
	v_mbcnt_lo_u32_b32 v58, -1, 0
	v_mbcnt_hi_u32_b32 v58, -1, v58
	ds_read_b32 v0, v0
	v_lshlrev_b32_e32 v71, 4, v58
	v_and_b32_e32 v59, 15, v58
	s_mov_b32 s1, 0
	v_ashrrev_i32_e32 v70, 4, v58
	s_waitcnt lgkmcnt(0)
	v_readfirstlane_b32 s0, v0
	s_and_b32 s4, s0, 7
	s_mul_i32 s5, s4, 0x1400000
	s_add_u32 s5, s94, s5
	s_addc_u32 s6, s95, 0
	s_lshl_b32 s4, s4, 22
	s_sub_u32 s4, 0, s4
	s_subb_u32 s7, 0, 0
	s_add_u32 s4, s5, s4
	s_addc_u32 s5, s6, s7
	s_lshl_b32 s8, s88, 10
	v_add_u32_e32 v0, s8, v71
	v_ashrrev_i32_e32 v1, 31, v0
	v_lshrrev_b32_e32 v1, 22, v1
	v_add_u32_e32 v1, v0, v1
	v_ashrrev_i32_e32 v1, 10, v1
	v_mul_i32_i24_e32 v2, 0x400, v1
	v_sub_u32_e32 v2, v0, v2
	v_lshrrev_b32_e32 v3, 4, v2
	v_bitop3_b32 v2, v3, v2, 32 bitop3:0x6c
	v_ashrrev_i32_e32 v4, 31, v2
	v_lshrrev_b32_e32 v4, 26, v4
	v_lshlrev_b32_e32 v3, 3, v1
	v_add_u32_e32 v4, v2, v4
	v_and_b32_e32 v3, -16, v3
	v_ashrrev_i32_e32 v5, 6, v4
	v_add_u32_e32 v104, v5, v3
	v_and_b32_e32 v3, 0xc0, v4
	v_lshlrev_b32_e32 v1, 5, v1
	v_sub_u32_e32 v2, v2, v3
	v_mov_b32_e32 v3, 1
	v_and_b32_e32 v1, 32, v1
	v_ashrrev_i16_sdwa v2, v3, sext(v2) dst_sel:DWORD dst_unused:UNUSED_PAD src0_sel:DWORD src1_sel:BYTE_0
	v_add_u32_sdwa v1, v1, sext(v2) dst_sel:DWORD dst_unused:UNUSED_PAD src0_sel:DWORD src1_sel:WORD_0
	v_lshlrev_b32_e32 v2, 10, v104
	v_add_u32_e32 v0, 0x2000, v0
	v_lshl_add_u32 v62, v1, 1, v2
	v_ashrrev_i32_e32 v1, 31, v0
	v_lshrrev_b32_e32 v1, 22, v1
	v_add_u32_e32 v1, v0, v1
	v_ashrrev_i32_e32 v1, 10, v1
	v_mul_i32_i24_e32 v2, 0x400, v1
	v_sub_u32_e32 v0, v0, v2
	v_lshrrev_b32_e32 v2, 4, v0
	s_lshl_b32 s6, s0, 3
	v_bitop3_b32 v0, v2, v0, 32 bitop3:0x6c
	s_and_b32 s6, s6, 56
	s_ashr_i32 s7, s0, 5
	v_ashrrev_i32_e32 v4, 31, v0
	s_add_i32 s9, s6, s7
	v_lshrrev_b32_e32 v4, 26, v4
	s_ashr_i32 s12, s9, 5
	v_lshlrev_b32_e32 v2, 3, v1
	v_add_u32_e32 v4, v0, v4
	s_bfe_u32 s0, s0, 0x20003
	s_lshl_b32 s6, s12, 2
	v_and_b32_e32 v2, -16, v2
	v_ashrrev_i32_e32 v5, 6, v4
	s_or_b32 s6, s6, s0
	v_add_u32_e32 v108, v5, v2
	v_and_b32_e32 v2, 0xffc0, v4
	s_ashr_i32 s7, s6, 31
	v_sub_u32_e32 v0, v0, v2
	s_lshl_b64 s[6:7], s[6:7], 18
	v_lshrrev_b16_e32 v2, 7, v0
	s_add_u32 s10, s94, s6
	v_and_b32_e32 v2, 1, v2
	s_addc_u32 s11, s95, s7
	v_lshlrev_b32_e32 v1, 5, v1
	v_add_u16_e32 v0, v0, v2
	s_add_u32 s6, s10, 0x11400000
	v_and_b32_e32 v1, 32, v1
	v_ashrrev_i16_sdwa v0, v3, sext(v0) dst_sel:DWORD dst_unused:UNUSED_PAD src0_sel:DWORD src1_sel:BYTE_0
	s_addc_u32 s7, s11, 0
	s_lshl_b32 s9, s9, 7
	v_add_u32_sdwa v0, v1, sext(v0) dst_sel:DWORD dst_unused:UNUSED_PAD src0_sel:DWORD src1_sel:WORD_0
	v_lshlrev_b32_e32 v1, 10, v108
	s_lshl_b32 s12, s12, 12
	s_and_b32 s9, s9, 0xf80
	v_lshl_add_u32 v64, v0, 1, v1
	v_lshl_or_b32 v1, s88, 4, v59
	s_or_b32 s9, s12, s9
	v_add_u32_e32 v2, s9, v1
	v_ashrrev_i32_e32 v3, 31, v2
	v_lshlrev_b64 v[2:3], 12, v[2:3]
	s_lshl_b32 s0, s0, 10
	v_lshl_add_u64 v[2:3], s[4:5], 0, v[2:3]
	v_lshlrev_b32_e32 v0, 3, v70
	v_lshl_add_u64 v[2:3], v[2:3], 0, s[0:1]
	s_mov_b64 s[0:1], 0x13000000
	v_ashrrev_i32_e32 v1, 31, v0
	v_lshl_add_u64 v[60:61], v[2:3], 0, s[0:1]
	v_lshl_add_u64 v[0:1], v[0:1], 1, v[60:61]
	s_mov_b64 s[0:1], 0xc00000
	v_lshl_add_u64 v[2:3], v[0:1], 0, s[0:1]
	s_mov_b32 s0, 0xc00000
	v_add_co_u32_e32 v0, vcc, s0, v0
	s_add_i32 s22, s8, 0
	s_nop 0
	v_addc_co_u32_e32 v1, vcc, 0, v1, vcc
	v_mov_b32_e32 v63, 0
	s_mov_b32 m0, s22
	s_add_i32 s21, s22, 0x2000
	global_load_dwordx4 v[72:75], v[2:3], off offset:64
	global_load_dwordx4 v[52:55], v[2:3], off offset:128
	global_load_dwordx4 v[48:51], v[2:3], off offset:192
	global_load_dwordx4 v[76:79], v[0:1], off
	v_mov_b32_e32 v65, v63
	global_load_lds_dwordx4 v62, s[6:7]
	v_mov_b32_e32 v240, v62
	s_mov_b32 m0, s21
	v_lshl_add_u64 v[66:67], s[6:7], 0, v[62:63]
	v_lshl_add_u64 v[68:69], s[6:7], 0, v[64:65]
	global_load_lds_dwordx4 v64, s[6:7]
	s_add_i32 s20, s22, 0x4000
	s_mov_b64 s[6:7], 0x80
	s_add_i32 s23, s22, 0x6000
	v_lshl_add_u64 v[56:57], v[66:67], 0, s[6:7]
	s_mov_b32 m0, s20
	s_add_u32 s0, s10, 0x11420000
	global_load_lds_dwordx4 v[56:57], off
	v_lshl_add_u64 v[56:57], v[68:69], 0, s[6:7]
	s_mov_b32 m0, s23
	s_addc_u32 s1, s11, 0
	s_add_i32 s24, s22, 0x8000
	global_load_lds_dwordx4 v[56:57], off
	s_mov_b32 m0, s24
	s_add_i32 s25, s22, 0xa000
	global_load_lds_dwordx4 v62, s[0:1]
	s_mov_b32 m0, s25
	s_mov_b64 s[4:5], 0x180
	global_load_lds_dwordx4 v64, s[0:1]
	s_add_u32 s0, s10, 0x11420080
	s_addc_u32 s1, s11, 0
	s_add_i32 s26, s22, 0xc000
	s_mov_b32 m0, s26
	s_add_i32 s27, s22, 0xe000
	global_load_lds_dwordx4 v62, s[0:1]
	s_mov_b32 m0, s27
	s_add_u32 s8, s10, 0x11c00000
	global_load_lds_dwordx4 v64, s[0:1]
	s_addc_u32 s9, s11, 0
	s_add_i32 s19, s22, 0x10000
	s_mov_b64 s[0:1], 0x100
	v_lshl_add_u64 v[56:57], v[66:67], 0, s[0:1]
	s_mov_b32 m0, s19
	s_add_i32 s13, s22, 0x12000
	global_load_dwordx4 v[44:47], v[2:3], off offset:256
	global_load_dwordx4 v[40:43], v[2:3], off offset:320
	global_load_dwordx4 v[36:39], v[2:3], off offset:384
	global_load_dwordx4 v[32:35], v[2:3], off offset:448
	global_load_dwordx4 v[28:31], v[2:3], off offset:512
	global_load_dwordx4 v[24:27], v[2:3], off offset:576
	global_load_dwordx4 v[20:23], v[2:3], off offset:640
	global_load_dwordx4 v[16:19], v[2:3], off offset:704
	global_load_dwordx4 v[12:15], v[2:3], off offset:768
	global_load_dwordx4 v[8:11], v[2:3], off offset:832
	global_load_dwordx4 v[4:7], v[2:3], off offset:896
	s_nop 0
	global_load_dwordx4 v[0:3], v[2:3], off offset:960
	s_waitcnt vmcnt(12)
	s_waitcnt vmcnt(12) lgkmcnt(0)
	s_barrier
	global_load_lds_dwordx4 v[56:57], off
	v_lshl_add_u64 v[56:57], v[68:69], 0, s[0:1]
	s_mov_b32 m0, s13
	s_add_i32 s12, s22, 0x14000
	s_add_i32 s14, s22, 0x16000
	global_load_lds_dwordx4 v[56:57], off
	v_lshl_add_u64 v[56:57], v[66:67], 0, s[4:5]
	s_mov_b32 m0, s12
	s_add_u32 s28, s10, 0x11420100
	global_load_lds_dwordx4 v[56:57], off
	v_lshl_add_u64 v[56:57], v[68:69], 0, s[4:5]
	s_mov_b32 m0, s14
	s_addc_u32 s29, s11, 0
	s_add_i32 s15, s22, 0x18000
	global_load_lds_dwordx4 v[56:57], off
	s_mov_b32 m0, s15
	s_add_i32 s16, s22, 0x1a000
	global_load_lds_dwordx4 v62, s[28:29]
	s_mov_b32 m0, s16
	v_and_b32_e32 v57, 48, v58
	global_load_lds_dwordx4 v64, s[28:29]
	s_add_u32 s28, s10, 0x11420180
	s_addc_u32 s29, s11, 0
	s_add_i32 s17, s22, 0x1c000
	s_mov_b32 m0, s17
	s_add_i32 s18, s22, 0x1e000
	global_load_lds_dwordx4 v62, s[28:29]
	s_mov_b32 m0, s18
	v_lshlrev_b32_e32 v58, 2, v58
	global_load_lds_dwordx4 v64, s[28:29]
	v_lshlrev_b32_e32 v56, 6, v59
	v_and_b32_e32 v58, 32, v58
	v_bitop3_b32 v56, v56, v58, v57 bitop3:0x36
	v_and_b32_e32 v57, 0xfffffc00, v71
	v_add3_u32 v65, 0, v56, v57
	v_mov_b32_e32 v71, v65
	ds_read_b128 v[56:59], v71
	ds_read_b128 v[80:83], v71 offset:2048
	s_waitcnt lgkmcnt(0)
	v_mfma_f32_16x16x32_bf16 v[84:87], v[56:59], v[76:79], 0
	ds_read_b128 v[56:59], v71 offset:4096
	ds_read_b128 v[88:91], v71 offset:6144
	ds_read_b128 v[96:99], v71 offset:8192
	ds_read_b128 v[100:103], v71 offset:10240
	s_waitcnt lgkmcnt(0)
	v_mfma_f32_16x16x32_bf16 v[92:95], v[56:59], v[76:79], 0
	v_lshlrev_b32_e32 v56, 9, v104
	ds_read_b128 v[104:107], v71 offset:12288
	v_lshlrev_b32_e32 v57, 9, v108
	ds_read_b128 v[108:111], v71 offset:14336
	ds_read_b128 v[112:115], v71 offset:32768
	ds_read_b128 v[116:119], v71 offset:34816
	ds_read_b128 v[120:123], v71 offset:36864
	ds_read_b128 v[124:127], v71 offset:38912
	ds_read_b128 v[128:131], v71 offset:40960
	ds_read_b128 v[132:135], v71 offset:43008
	ds_read_b128 v[136:139], v71 offset:45056
	ds_read_b128 v[140:143], v71 offset:47104
	v_mfma_f32_16x16x32_bf16 v[80:83], v[80:83], v[76:79], 0
	v_sub_u32_e32 v56, v62, v56
	v_mov_b32_e32 v241, v56
	v_sub_u32_e32 v58, v64, v57
	v_mfma_f32_16x16x32_bf16 v[88:91], v[88:91], v[76:79], 0
	v_mfma_f32_16x16x32_bf16 v[96:99], v[96:99], v[76:79], 0
	v_mfma_f32_16x16x32_bf16 v[100:103], v[100:103], v[76:79], 0
	s_waitcnt lgkmcnt(0)
	v_mfma_f32_16x16x32_bf16 v[104:107], v[104:107], v[76:79], 0
	v_mfma_f32_16x16x32_bf16 v[108:111], v[108:111], v[76:79], 0
	ds_read_b128 v[144:147], v71 offset:15360
	ds_read_b128 v[148:151], v71 offset:13312
	ds_read_b128 v[152:155], v71 offset:11264
	ds_read_b128 v[156:159], v71 offset:9216
	ds_read_b128 v[160:163], v71 offset:7168
	ds_read_b128 v[164:167], v71 offset:5120
	ds_read_b128 v[168:171], v71 offset:3072
	ds_read_b128 v[172:175], v71 offset:1024
	v_mfma_f32_16x16x32_bf16 v[112:115], v[112:115], v[76:79], 0
	v_mfma_f32_16x16x32_bf16 v[116:119], v[116:119], v[76:79], 0
	v_mfma_f32_16x16x32_bf16 v[120:123], v[120:123], v[76:79], 0
	v_mfma_f32_16x16x32_bf16 v[124:127], v[124:127], v[76:79], 0
	v_mfma_f32_16x16x32_bf16 v[128:131], v[128:131], v[76:79], 0
	v_mfma_f32_16x16x32_bf16 v[132:135], v[132:135], v[76:79], 0
	v_mfma_f32_16x16x32_bf16 v[136:139], v[136:139], v[76:79], 0
	v_mfma_f32_16x16x32_bf16 v[76:79], v[140:143], v[76:79], 0
	s_waitcnt lgkmcnt(0)
	v_mfma_f32_16x16x32_bf16 v[84:87], v[172:175], v[72:75], v[84:87]
	v_mfma_f32_16x16x32_bf16 v[80:83], v[168:171], v[72:75], v[80:83]
	v_mfma_f32_16x16x32_bf16 v[92:95], v[164:167], v[72:75], v[92:95]
	v_mfma_f32_16x16x32_bf16 v[88:91], v[160:163], v[72:75], v[88:91]
	v_mfma_f32_16x16x32_bf16 v[96:99], v[156:159], v[72:75], v[96:99]
	v_mfma_f32_16x16x32_bf16 v[100:103], v[152:155], v[72:75], v[100:103]
	ds_read_b128 v[140:143], v71 offset:33792
	ds_read_b128 v[152:155], v71 offset:35840
	ds_read_b128 v[156:159], v71 offset:37888
	ds_read_b128 v[160:163], v71 offset:39936
	v_mfma_f32_16x16x32_bf16 v[104:107], v[148:151], v[72:75], v[104:107]
	ds_read_b128 v[148:151], v71 offset:41984
	ds_read_b128 v[164:167], v71 offset:44032
	ds_read_b128 v[168:171], v71 offset:46080
	ds_read_b128 v[172:175], v71 offset:48128
	v_mfma_f32_16x16x32_bf16 v[108:111], v[144:147], v[72:75], v[108:111]
	s_waitcnt lgkmcnt(0)
	v_mfma_f32_16x16x32_bf16 v[112:115], v[140:143], v[72:75], v[112:115]
	v_mfma_f32_16x16x32_bf16 v[116:119], v[152:155], v[72:75], v[116:119]
	v_mfma_f32_16x16x32_bf16 v[120:123], v[156:159], v[72:75], v[120:123]
	v_mfma_f32_16x16x32_bf16 v[124:127], v[160:163], v[72:75], v[124:127]
	v_mfma_f32_16x16x32_bf16 v[128:131], v[148:151], v[72:75], v[128:131]
	ds_read_b128 v[140:143], v71 offset:30720
	ds_read_b128 v[144:147], v71 offset:28672
	ds_read_b128 v[148:151], v71 offset:26624
	ds_read_b128 v[152:155], v71 offset:24576
	v_mfma_f32_16x16x32_bf16 v[132:135], v[164:167], v[72:75], v[132:135]
	v_mfma_f32_16x16x32_bf16 v[136:139], v[168:171], v[72:75], v[136:139]
	ds_read_b128 v[156:159], v71 offset:22528
	ds_read_b128 v[160:163], v71 offset:20480
	ds_read_b128 v[164:167], v71 offset:18432
	ds_read_b128 v[168:171], v71 offset:16384
	v_mfma_f32_16x16x32_bf16 v[72:75], v[172:175], v[72:75], v[76:79]
	s_waitcnt lgkmcnt(0)
	v_mfma_f32_16x16x32_bf16 v[76:79], v[168:171], v[52:55], v[84:87]
	v_mfma_f32_16x16x32_bf16 v[80:83], v[164:167], v[52:55], v[80:83]
	v_mfma_f32_16x16x32_bf16 v[84:87], v[160:163], v[52:55], v[92:95]
	v_mfma_f32_16x16x32_bf16 v[88:91], v[156:159], v[52:55], v[88:91]
	v_mfma_f32_16x16x32_bf16 v[92:95], v[152:155], v[52:55], v[96:99]
	v_mfma_f32_16x16x32_bf16 v[96:99], v[148:151], v[52:55], v[100:103]
	s_nop 2
	ds_read_b128 v[100:103], v71 offset:49152
	ds_read_b128 v[148:151], v71 offset:51200
	ds_read_b128 v[152:155], v71 offset:53248
	ds_read_b128 v[156:159], v71 offset:55296
	v_mfma_f32_16x16x32_bf16 v[104:107], v[144:147], v[52:55], v[104:107]
	ds_read_b128 v[144:147], v71 offset:57344
	ds_read_b128 v[160:163], v71 offset:59392
	ds_read_b128 v[164:167], v71 offset:61440
	ds_read_b128 v[168:171], v71 offset:63488
	v_mfma_f32_16x16x32_bf16 v[108:111], v[140:143], v[52:55], v[108:111]
	s_waitcnt lgkmcnt(0)
	v_mfma_f32_16x16x32_bf16 v[100:103], v[100:103], v[52:55], v[112:115]
	v_mfma_f32_16x16x32_bf16 v[112:115], v[148:151], v[52:55], v[116:119]
	v_mfma_f32_16x16x32_bf16 v[116:119], v[152:155], v[52:55], v[120:123]
	v_mfma_f32_16x16x32_bf16 v[120:123], v[156:159], v[52:55], v[124:127]
	v_mfma_f32_16x16x32_bf16 v[124:127], v[144:147], v[52:55], v[128:131]
	v_mfma_f32_16x16x32_bf16 v[128:131], v[160:163], v[52:55], v[132:135]
	s_nop 2
	ds_read_b128 v[132:135], v71 offset:31744
	ds_read_b128 v[140:143], v71 offset:29696
	ds_read_b128 v[144:147], v71 offset:27648
	ds_read_b128 v[148:151], v71 offset:25600
	v_mfma_f32_16x16x32_bf16 v[136:139], v[164:167], v[52:55], v[136:139]
	ds_read_b128 v[152:155], v71 offset:23552
	ds_read_b128 v[156:159], v71 offset:21504
	ds_read_b128 v[160:163], v71 offset:19456
	ds_read_b128 v[164:167], v71 offset:17408
	v_mfma_f32_16x16x32_bf16 v[52:55], v[168:171], v[52:55], v[72:75]
	s_waitcnt lgkmcnt(0)
	v_mfma_f32_16x16x32_bf16 v[72:75], v[164:167], v[48:51], v[76:79]
	v_mfma_f32_16x16x32_bf16 v[76:79], v[160:163], v[48:51], v[80:83]
	v_mfma_f32_16x16x32_bf16 v[80:83], v[156:159], v[48:51], v[84:87]
	v_mfma_f32_16x16x32_bf16 v[84:87], v[152:155], v[48:51], v[88:91]
	v_mfma_f32_16x16x32_bf16 v[88:91], v[148:151], v[48:51], v[92:95]
	v_mfma_f32_16x16x32_bf16 v[92:95], v[144:147], v[48:51], v[96:99]
	s_nop 2
	ds_read_b128 v[96:99], v71 offset:50176
	ds_read_b128 v[144:147], v71 offset:52224
	ds_read_b128 v[148:151], v71 offset:54272
	ds_read_b128 v[152:155], v71 offset:56320
	v_mfma_f32_16x16x32_bf16 v[104:107], v[140:143], v[48:51], v[104:107]
	ds_read_b128 v[140:143], v71 offset:58368
	ds_read_b128 v[156:159], v71 offset:60416
	ds_read_b128 v[160:163], v71 offset:62464
	ds_read_b128 v[164:167], v71 offset:64512
	v_mfma_f32_16x16x32_bf16 v[108:111], v[132:135], v[48:51], v[108:111]
	s_waitcnt lgkmcnt(0)
	v_mfma_f32_16x16x32_bf16 v[96:99], v[96:99], v[48:51], v[100:103]
	v_mfma_f32_16x16x32_bf16 v[100:103], v[144:147], v[48:51], v[112:115]
	v_mfma_f32_16x16x32_bf16 v[112:115], v[148:151], v[48:51], v[116:119]
	v_mfma_f32_16x16x32_bf16 v[116:119], v[152:155], v[48:51], v[120:123]
	v_mfma_f32_16x16x32_bf16 v[120:123], v[140:143], v[48:51], v[124:127]
	v_mfma_f32_16x16x32_bf16 v[124:127], v[156:159], v[48:51], v[128:131]
	v_mfma_f32_16x16x32_bf16 v[128:131], v[160:163], v[48:51], v[136:139]
	v_mfma_f32_16x16x32_bf16 v[50:53], v[164:167], v[48:51], v[52:55]
	s_waitcnt vmcnt(0)
	s_waitcnt vmcnt(0)
	s_barrier
	v_add_u32_e32 v48, 0x10000, v65
	v_mov_b32_e32 v49, v48
	ds_read_b128 v[132:135], v49
	ds_read_b128 v[136:139], v49 offset:2048
	s_waitcnt lgkmcnt(0)
	v_mfma_f32_16x16x32_bf16 v[72:75], v[132:135], v[44:47], v[72:75]
	ds_read_b128 v[132:135], v49 offset:4096
	v_mfma_f32_16x16x32_bf16 v[76:79], v[136:139], v[44:47], v[76:79]
	ds_read_b128 v[136:139], v49 offset:6144
	s_waitcnt lgkmcnt(0)
	v_mfma_f32_16x16x32_bf16 v[80:83], v[132:135], v[44:47], v[80:83]
	ds_read_b128 v[132:135], v49 offset:8192
	v_mfma_f32_16x16x32_bf16 v[84:87], v[136:139], v[44:47], v[84:87]
	ds_read_b128 v[136:139], v49 offset:10240
	s_waitcnt lgkmcnt(0)
	v_mfma_f32_16x16x32_bf16 v[88:91], v[132:135], v[44:47], v[88:91]
	ds_read_b128 v[132:135], v49 offset:12288
	ds_read_b128 v[140:143], v49 offset:14336
	v_mfma_f32_16x16x32_bf16 v[92:95], v[136:139], v[44:47], v[92:95]
	ds_read_b128 v[136:139], v49 offset:32768
	ds_read_b128 v[144:147], v49 offset:34816
	ds_read_b128 v[148:151], v49 offset:36864
	ds_read_b128 v[152:155], v49 offset:38912
	s_waitcnt lgkmcnt(0)
	v_mfma_f32_16x16x32_bf16 v[104:107], v[132:135], v[44:47], v[104:107]
	ds_read_b128 v[132:135], v49 offset:40960
	ds_read_b128 v[156:159], v49 offset:43008
	ds_read_b128 v[160:163], v49 offset:45056
	ds_read_b128 v[164:167], v49 offset:47104
	v_mfma_f32_16x16x32_bf16 v[108:111], v[140:143], v[44:47], v[108:111]
	s_add_u32 s100, s10, 0x11400200
	s_addc_u32 s101, s11, 0
	s_mov_b32 m0, s22
	s_nop 0
	global_load_lds_dwordx4 v240, s[100:101]
	v_mfma_f32_16x16x32_bf16 v[96:99], v[136:139], v[44:47], v[96:99]
	v_mfma_f32_16x16x32_bf16 v[100:103], v[144:147], v[44:47], v[100:103]
	v_mfma_f32_16x16x32_bf16 v[112:115], v[148:151], v[44:47], v[112:115]
	v_mfma_f32_16x16x32_bf16 v[116:119], v[152:155], v[44:47], v[116:119]
	s_waitcnt lgkmcnt(0)
	v_mfma_f32_16x16x32_bf16 v[120:123], v[132:135], v[44:47], v[120:123]
	ds_read_b128 v[132:135], v49 offset:15360
	ds_read_b128 v[136:139], v49 offset:13312
	ds_read_b128 v[140:143], v49 offset:11264
	ds_read_b128 v[144:147], v49 offset:9216
	v_mfma_f32_16x16x32_bf16 v[124:127], v[156:159], v[44:47], v[124:127]
	v_mfma_f32_16x16x32_bf16 v[128:131], v[160:163], v[44:47], v[128:131]
	ds_read_b128 v[148:151], v49 offset:7168
	ds_read_b128 v[152:155], v49 offset:5120
	ds_read_b128 v[156:159], v49 offset:3072
	ds_read_b128 v[160:163], v49 offset:1024
	v_mfma_f32_16x16x32_bf16 v[44:47], v[164:167], v[44:47], v[50:53]
	s_add_u32 s100, s10, 0x11410200
	s_addc_u32 s101, s11, 0
	s_mov_b32 m0, s21
	s_nop 0
	global_load_lds_dwordx4 v240, s[100:101]
	s_waitcnt lgkmcnt(0)
	v_mfma_f32_16x16x32_bf16 v[50:53], v[160:163], v[40:43], v[72:75]
	v_mfma_f32_16x16x32_bf16 v[72:75], v[156:159], v[40:43], v[76:79]
	v_mfma_f32_16x16x32_bf16 v[76:79], v[152:155], v[40:43], v[80:83]
	v_mfma_f32_16x16x32_bf16 v[80:83], v[148:151], v[40:43], v[84:87]
	v_mfma_f32_16x16x32_bf16 v[84:87], v[144:147], v[40:43], v[88:91]
	v_mfma_f32_16x16x32_bf16 v[88:91], v[140:143], v[40:43], v[92:95]
	s_nop 2
	ds_read_b128 v[92:95], v49 offset:33792
	ds_read_b128 v[140:143], v49 offset:35840
	ds_read_b128 v[144:147], v49 offset:37888
	ds_read_b128 v[148:151], v49 offset:39936
	v_mfma_f32_16x16x32_bf16 v[104:107], v[136:139], v[40:43], v[104:107]
	ds_read_b128 v[136:139], v49 offset:41984
	ds_read_b128 v[152:155], v49 offset:44032
	ds_read_b128 v[156:159], v49 offset:46080
	ds_read_b128 v[160:163], v49 offset:48128
	v_mfma_f32_16x16x32_bf16 v[108:111], v[132:135], v[40:43], v[108:111]
	s_add_u32 s100, s10, 0x11400280
	s_addc_u32 s101, s11, 0
	s_mov_b32 m0, s20
	s_nop 0
	global_load_lds_dwordx4 v240, s[100:101]
	s_waitcnt lgkmcnt(0)
	v_mfma_f32_16x16x32_bf16 v[92:95], v[92:95], v[40:43], v[96:99]
	v_mfma_f32_16x16x32_bf16 v[96:99], v[140:143], v[40:43], v[100:103]
	v_mfma_f32_16x16x32_bf16 v[100:103], v[144:147], v[40:43], v[112:115]
	v_mfma_f32_16x16x32_bf16 v[112:115], v[148:151], v[40:43], v[116:119]
	v_mfma_f32_16x16x32_bf16 v[116:119], v[136:139], v[40:43], v[120:123]
	v_mfma_f32_16x16x32_bf16 v[120:123], v[152:155], v[40:43], v[124:127]
	s_nop 2
	ds_read_b128 v[124:127], v49 offset:30720
	ds_read_b128 v[132:135], v49 offset:28672
	ds_read_b128 v[136:139], v49 offset:26624
	ds_read_b128 v[140:143], v49 offset:24576
	v_mfma_f32_16x16x32_bf16 v[128:131], v[156:159], v[40:43], v[128:131]
	ds_read_b128 v[144:147], v49 offset:22528
	ds_read_b128 v[148:151], v49 offset:20480
	ds_read_b128 v[152:155], v49 offset:18432
	ds_read_b128 v[156:159], v49 offset:16384
	v_mfma_f32_16x16x32_bf16 v[40:43], v[160:163], v[40:43], v[44:47]
	s_add_u32 s100, s10, 0x11410280
	s_addc_u32 s101, s11, 0
	s_mov_b32 m0, s23
	s_nop 0
	global_load_lds_dwordx4 v240, s[100:101]
	s_waitcnt lgkmcnt(0)
	v_mfma_f32_16x16x32_bf16 v[44:47], v[156:159], v[36:39], v[50:53]
	v_mfma_f32_16x16x32_bf16 v[50:53], v[152:155], v[36:39], v[72:75]
	v_mfma_f32_16x16x32_bf16 v[72:75], v[148:151], v[36:39], v[76:79]
	v_mfma_f32_16x16x32_bf16 v[76:79], v[144:147], v[36:39], v[80:83]
	v_mfma_f32_16x16x32_bf16 v[80:83], v[140:143], v[36:39], v[84:87]
	v_mfma_f32_16x16x32_bf16 v[84:87], v[136:139], v[36:39], v[88:91]
	s_nop 2
	ds_read_b128 v[88:91], v49 offset:49152
	ds_read_b128 v[136:139], v49 offset:51200
	ds_read_b128 v[140:143], v49 offset:53248
	ds_read_b128 v[144:147], v49 offset:55296
	v_mfma_f32_16x16x32_bf16 v[104:107], v[132:135], v[36:39], v[104:107]
	ds_read_b128 v[132:135], v49 offset:57344
	ds_read_b128 v[148:151], v49 offset:59392
	ds_read_b128 v[152:155], v49 offset:61440
	ds_read_b128 v[156:159], v49 offset:63488
	v_mfma_f32_16x16x32_bf16 v[108:111], v[124:127], v[36:39], v[108:111]
	s_add_u32 s100, s10, 0x11420200
	s_addc_u32 s101, s11, 0
	s_mov_b32 m0, s24
	s_nop 0
	global_load_lds_dwordx4 v240, s[100:101]
	s_waitcnt lgkmcnt(0)
	v_mfma_f32_16x16x32_bf16 v[88:91], v[88:91], v[36:39], v[92:95]
	v_mfma_f32_16x16x32_bf16 v[92:95], v[136:139], v[36:39], v[96:99]
	v_mfma_f32_16x16x32_bf16 v[96:99], v[140:143], v[36:39], v[100:103]
	v_mfma_f32_16x16x32_bf16 v[100:103], v[144:147], v[36:39], v[112:115]
	v_mfma_f32_16x16x32_bf16 v[112:115], v[132:135], v[36:39], v[116:119]
	v_mfma_f32_16x16x32_bf16 v[116:119], v[148:151], v[36:39], v[120:123]
	s_nop 2
	ds_read_b128 v[120:123], v49 offset:31744
	ds_read_b128 v[124:127], v49 offset:29696
	ds_read_b128 v[132:135], v49 offset:27648
	ds_read_b128 v[136:139], v49 offset:25600
	v_mfma_f32_16x16x32_bf16 v[128:131], v[152:155], v[36:39], v[128:131]
	ds_read_b128 v[140:143], v49 offset:23552
	ds_read_b128 v[144:147], v49 offset:21504
	ds_read_b128 v[148:151], v49 offset:19456
	ds_read_b128 v[152:155], v49 offset:17408
	v_mfma_f32_16x16x32_bf16 v[36:39], v[156:159], v[36:39], v[40:43]
	s_add_u32 s100, s10, 0x11430200
	s_addc_u32 s101, s11, 0
	s_mov_b32 m0, s25
	s_nop 0
	global_load_lds_dwordx4 v240, s[100:101]
	s_waitcnt lgkmcnt(0)
	v_mfma_f32_16x16x32_bf16 v[40:43], v[152:155], v[32:35], v[44:47]
	v_mfma_f32_16x16x32_bf16 v[44:47], v[148:151], v[32:35], v[50:53]
	v_mfma_f32_16x16x32_bf16 v[50:53], v[144:147], v[32:35], v[72:75]
	v_mfma_f32_16x16x32_bf16 v[72:75], v[140:143], v[32:35], v[76:79]
	v_mfma_f32_16x16x32_bf16 v[76:79], v[136:139], v[32:35], v[80:83]
	v_mfma_f32_16x16x32_bf16 v[80:83], v[132:135], v[32:35], v[84:87]
	s_nop 2
	ds_read_b128 v[84:87], v49 offset:50176
	ds_read_b128 v[132:135], v49 offset:52224
	ds_read_b128 v[136:139], v49 offset:54272
	ds_read_b128 v[140:143], v49 offset:56320
	v_mfma_f32_16x16x32_bf16 v[104:107], v[124:127], v[32:35], v[104:107]
	ds_read_b128 v[124:127], v49 offset:58368
	ds_read_b128 v[144:147], v49 offset:60416
	ds_read_b128 v[148:151], v49 offset:62464
	ds_read_b128 v[152:155], v49 offset:64512
	v_mfma_f32_16x16x32_bf16 v[108:111], v[120:123], v[32:35], v[108:111]
	s_add_u32 s100, s10, 0x11420280
	s_addc_u32 s101, s11, 0
	s_mov_b32 m0, s26
	s_nop 0
	global_load_lds_dwordx4 v240, s[100:101]
	s_waitcnt lgkmcnt(0)
	v_mfma_f32_16x16x32_bf16 v[84:87], v[84:87], v[32:35], v[88:91]
	v_mfma_f32_16x16x32_bf16 v[88:91], v[132:135], v[32:35], v[92:95]
	v_mfma_f32_16x16x32_bf16 v[92:95], v[136:139], v[32:35], v[96:99]
	v_mfma_f32_16x16x32_bf16 v[96:99], v[140:143], v[32:35], v[100:103]
	v_mfma_f32_16x16x32_bf16 v[100:103], v[124:127], v[32:35], v[112:115]
	v_mfma_f32_16x16x32_bf16 v[112:115], v[144:147], v[32:35], v[116:119]
	v_mfma_f32_16x16x32_bf16 v[116:119], v[148:151], v[32:35], v[128:131]
	v_mfma_f32_16x16x32_bf16 v[32:35], v[152:155], v[32:35], v[36:39]
	s_add_u32 s100, s10, 0x11430280
	s_addc_u32 s101, s11, 0
	s_mov_b32 m0, s27
	s_nop 0
	global_load_lds_dwordx4 v240, s[100:101]
	s_nop 0
	s_waitcnt vmcnt(0)
	s_waitcnt vmcnt(0)
	s_barrier
	v_mov_b32_e32 v49, v65
	ds_read_b128 v[36:39], v49
	ds_read_b128 v[66:69], v49 offset:2048
	s_waitcnt lgkmcnt(0)
	v_mfma_f32_16x16x32_bf16 v[36:39], v[36:39], v[28:31], v[40:43]
	s_nop 2
	ds_read_b128 v[40:43], v49 offset:4096
	v_mfma_f32_16x16x32_bf16 v[44:47], v[66:69], v[28:31], v[44:47]
	ds_read_b128 v[66:69], v49 offset:6144
	s_waitcnt lgkmcnt(0)
	v_mfma_f32_16x16x32_bf16 v[40:43], v[40:43], v[28:31], v[50:53]
	s_nop 2
	ds_read_b128 v[50:53], v49 offset:8192
	v_mfma_f32_16x16x32_bf16 v[66:69], v[66:69], v[28:31], v[72:75]
	s_nop 2
	ds_read_b128 v[72:75], v49 offset:10240
	s_waitcnt lgkmcnt(0)
	v_mfma_f32_16x16x32_bf16 v[50:53], v[50:53], v[28:31], v[76:79]
	s_nop 2
	ds_read_b128 v[76:79], v49 offset:12288
	ds_read_b128 v[120:123], v49 offset:14336
	v_mfma_f32_16x16x32_bf16 v[72:75], v[72:75], v[28:31], v[80:83]
	s_nop 2
	ds_read_b128 v[80:83], v49 offset:32768
	ds_read_b128 v[124:127], v49 offset:34816
	ds_read_b128 v[128:131], v49 offset:36864
	ds_read_b128 v[132:135], v49 offset:38912
	s_waitcnt lgkmcnt(0)
	v_mfma_f32_16x16x32_bf16 v[76:79], v[76:79], v[28:31], v[104:107]
	s_nop 2
	ds_read_b128 v[104:107], v49 offset:40960
	ds_read_b128 v[136:139], v49 offset:43008
	ds_read_b128 v[140:143], v49 offset:45056
	ds_read_b128 v[144:147], v49 offset:47104
	v_mfma_f32_16x16x32_bf16 v[108:111], v[120:123], v[28:31], v[108:111]
	s_add_u32 s100, s10, 0x11400300
	s_addc_u32 s101, s11, 0
	s_mov_b32 m0, s19
	s_nop 0
	global_load_lds_dwordx4 v240, s[100:101]
	v_mfma_f32_16x16x32_bf16 v[80:83], v[80:83], v[28:31], v[84:87]
	v_mfma_f32_16x16x32_bf16 v[84:87], v[124:127], v[28:31], v[88:91]
	v_mfma_f32_16x16x32_bf16 v[88:91], v[128:131], v[28:31], v[92:95]
	v_mfma_f32_16x16x32_bf16 v[92:95], v[132:135], v[28:31], v[96:99]
	s_waitcnt lgkmcnt(0)
	v_mfma_f32_16x16x32_bf16 v[96:99], v[104:107], v[28:31], v[100:103]
	v_mfma_f32_16x16x32_bf16 v[100:103], v[136:139], v[28:31], v[112:115]
	ds_read_b128 v[104:107], v49 offset:15360
	s_nop 1
	ds_read_b128 v[112:115], v49 offset:13312
	ds_read_b128 v[120:123], v49 offset:11264
	ds_read_b128 v[124:127], v49 offset:9216
	v_mfma_f32_16x16x32_bf16 v[116:119], v[140:143], v[28:31], v[116:119]
	ds_read_b128 v[128:131], v49 offset:7168
	ds_read_b128 v[132:135], v49 offset:5120
	ds_read_b128 v[136:139], v49 offset:3072
	ds_read_b128 v[140:143], v49 offset:1024
	v_mfma_f32_16x16x32_bf16 v[28:31], v[144:147], v[28:31], v[32:35]
	s_add_u32 s100, s10, 0x11410300
	s_addc_u32 s101, s11, 0
	s_mov_b32 m0, s13
	s_nop 0
	global_load_lds_dwordx4 v240, s[100:101]
	s_waitcnt lgkmcnt(0)
	v_mfma_f32_16x16x32_bf16 v[32:35], v[140:143], v[24:27], v[36:39]
	v_mfma_f32_16x16x32_bf16 v[36:39], v[136:139], v[24:27], v[44:47]
	v_mfma_f32_16x16x32_bf16 v[40:43], v[132:135], v[24:27], v[40:43]
	v_mfma_f32_16x16x32_bf16 v[44:47], v[128:131], v[24:27], v[66:69]
	v_mfma_f32_16x16x32_bf16 v[50:53], v[124:127], v[24:27], v[50:53]
	v_mfma_f32_16x16x32_bf16 v[66:69], v[120:123], v[24:27], v[72:75]
	s_nop 2
	ds_read_b128 v[72:75], v49 offset:33792
	ds_read_b128 v[120:123], v49 offset:35840
	ds_read_b128 v[124:127], v49 offset:37888
	ds_read_b128 v[128:131], v49 offset:39936
	v_mfma_f32_16x16x32_bf16 v[76:79], v[112:115], v[24:27], v[76:79]
	ds_read_b128 v[112:115], v49 offset:41984
	ds_read_b128 v[132:135], v49 offset:44032
	ds_read_b128 v[136:139], v49 offset:46080
	ds_read_b128 v[140:143], v49 offset:48128
	v_mfma_f32_16x16x32_bf16 v[104:107], v[104:107], v[24:27], v[108:111]
	s_add_u32 s100, s10, 0x11400380
	s_addc_u32 s101, s11, 0
	s_mov_b32 m0, s12
	s_nop 0
	global_load_lds_dwordx4 v240, s[100:101]
	s_waitcnt lgkmcnt(0)
	v_mfma_f32_16x16x32_bf16 v[72:75], v[72:75], v[24:27], v[80:83]
	v_mfma_f32_16x16x32_bf16 v[80:83], v[120:123], v[24:27], v[84:87]
	v_mfma_f32_16x16x32_bf16 v[84:87], v[124:127], v[24:27], v[88:91]
	v_mfma_f32_16x16x32_bf16 v[88:91], v[128:131], v[24:27], v[92:95]
	v_mfma_f32_16x16x32_bf16 v[92:95], v[112:115], v[24:27], v[96:99]
	v_mfma_f32_16x16x32_bf16 v[96:99], v[132:135], v[24:27], v[100:103]
	s_nop 2
	ds_read_b128 v[100:103], v49 offset:30720
	ds_read_b128 v[108:111], v49 offset:28672
	ds_read_b128 v[112:115], v49 offset:26624
	ds_read_b128 v[120:123], v49 offset:24576
	v_mfma_f32_16x16x32_bf16 v[116:119], v[136:139], v[24:27], v[116:119]
	ds_read_b128 v[124:127], v49 offset:22528
	ds_read_b128 v[128:131], v49 offset:20480
	ds_read_b128 v[132:135], v49 offset:18432
	ds_read_b128 v[136:139], v49 offset:16384
	v_mfma_f32_16x16x32_bf16 v[24:27], v[140:143], v[24:27], v[28:31]
	s_add_u32 s100, s10, 0x11410380
	s_addc_u32 s101, s11, 0
	s_mov_b32 m0, s14
	s_nop 0
	global_load_lds_dwordx4 v240, s[100:101]
	s_waitcnt lgkmcnt(0)
	v_mfma_f32_16x16x32_bf16 v[28:31], v[136:139], v[20:23], v[32:35]
	v_mfma_f32_16x16x32_bf16 v[32:35], v[132:135], v[20:23], v[36:39]
	v_mfma_f32_16x16x32_bf16 v[36:39], v[128:131], v[20:23], v[40:43]
	v_mfma_f32_16x16x32_bf16 v[40:43], v[124:127], v[20:23], v[44:47]
	v_mfma_f32_16x16x32_bf16 v[44:47], v[120:123], v[20:23], v[50:53]
	v_mfma_f32_16x16x32_bf16 v[50:53], v[112:115], v[20:23], v[66:69]
	s_nop 2
	ds_read_b128 v[66:69], v49 offset:49152
	ds_read_b128 v[112:115], v49 offset:51200
	ds_read_b128 v[120:123], v49 offset:53248
	ds_read_b128 v[124:127], v49 offset:55296
	v_mfma_f32_16x16x32_bf16 v[76:79], v[108:111], v[20:23], v[76:79]
	ds_read_b128 v[108:111], v49 offset:57344
	ds_read_b128 v[128:131], v49 offset:59392
	ds_read_b128 v[132:135], v49 offset:61440
	ds_read_b128 v[136:139], v49 offset:63488
	v_mfma_f32_16x16x32_bf16 v[100:103], v[100:103], v[20:23], v[104:107]
	s_add_u32 s100, s10, 0x11420300
	s_addc_u32 s101, s11, 0
	s_mov_b32 m0, s15
	s_nop 0
	global_load_lds_dwordx4 v240, s[100:101]
	s_waitcnt lgkmcnt(0)
	v_mfma_f32_16x16x32_bf16 v[66:69], v[66:69], v[20:23], v[72:75]
	v_mfma_f32_16x16x32_bf16 v[72:75], v[112:115], v[20:23], v[80:83]
	v_mfma_f32_16x16x32_bf16 v[80:83], v[120:123], v[20:23], v[84:87]
	v_mfma_f32_16x16x32_bf16 v[84:87], v[124:127], v[20:23], v[88:91]
	v_mfma_f32_16x16x32_bf16 v[88:91], v[108:111], v[20:23], v[92:95]
	v_mfma_f32_16x16x32_bf16 v[92:95], v[128:131], v[20:23], v[96:99]
	s_nop 2
	ds_read_b128 v[96:99], v49 offset:31744
	ds_read_b128 v[104:107], v49 offset:29696
	ds_read_b128 v[108:111], v49 offset:27648
	ds_read_b128 v[112:115], v49 offset:25600
	v_mfma_f32_16x16x32_bf16 v[116:119], v[132:135], v[20:23], v[116:119]
	ds_read_b128 v[120:123], v49 offset:23552
	ds_read_b128 v[124:127], v49 offset:21504
	ds_read_b128 v[128:131], v49 offset:19456
	ds_read_b128 v[132:135], v49 offset:17408
	v_mfma_f32_16x16x32_bf16 v[20:23], v[136:139], v[20:23], v[24:27]
	s_add_u32 s100, s10, 0x11430300
	s_addc_u32 s101, s11, 0
	s_mov_b32 m0, s16
	s_nop 0
	global_load_lds_dwordx4 v240, s[100:101]
	s_waitcnt lgkmcnt(0)
	v_mfma_f32_16x16x32_bf16 v[24:27], v[132:135], v[16:19], v[28:31]
	v_mfma_f32_16x16x32_bf16 v[28:31], v[128:131], v[16:19], v[32:35]
	v_mfma_f32_16x16x32_bf16 v[32:35], v[124:127], v[16:19], v[36:39]
	v_mfma_f32_16x16x32_bf16 v[36:39], v[120:123], v[16:19], v[40:43]
	v_mfma_f32_16x16x32_bf16 v[40:43], v[112:115], v[16:19], v[44:47]
	v_mfma_f32_16x16x32_bf16 v[50:53], v[108:111], v[16:19], v[50:53]
	s_nop 1
	ds_read_b128 v[44:47], v49 offset:50176
	ds_read_b128 v[108:111], v49 offset:52224
	ds_read_b128 v[112:115], v49 offset:54272
	ds_read_b128 v[120:123], v49 offset:56320
	v_mfma_f32_16x16x32_bf16 v[76:79], v[104:107], v[16:19], v[76:79]
	ds_read_b128 v[104:107], v49 offset:58368
	ds_read_b128 v[124:127], v49 offset:60416
	ds_read_b128 v[128:131], v49 offset:62464
	ds_read_b128 v[132:135], v49 offset:64512
	v_mfma_f32_16x16x32_bf16 v[96:99], v[96:99], v[16:19], v[100:103]
	s_add_u32 s100, s10, 0x11420380
	s_addc_u32 s101, s11, 0
	s_mov_b32 m0, s17
	s_nop 0
	global_load_lds_dwordx4 v240, s[100:101]
	s_waitcnt lgkmcnt(0)
	v_mfma_f32_16x16x32_bf16 v[66:69], v[44:47], v[16:19], v[66:69]
	v_mfma_f32_16x16x32_bf16 v[72:75], v[108:111], v[16:19], v[72:75]
	v_mfma_f32_16x16x32_bf16 v[80:83], v[112:115], v[16:19], v[80:83]
	v_mfma_f32_16x16x32_bf16 v[84:87], v[120:123], v[16:19], v[84:87]
	v_mfma_f32_16x16x32_bf16 v[88:91], v[104:107], v[16:19], v[88:91]
	v_mfma_f32_16x16x32_bf16 v[92:95], v[124:127], v[16:19], v[92:95]
	v_mfma_f32_16x16x32_bf16 v[100:103], v[128:131], v[16:19], v[116:119]
	v_mfma_f32_16x16x32_bf16 v[16:19], v[132:135], v[16:19], v[20:23]
	s_add_u32 s100, s10, 0x11430380
	s_addc_u32 s101, s11, 0
	s_mov_b32 m0, s18
	s_nop 0
	global_load_lds_dwordx4 v240, s[100:101]
	s_waitcnt vmcnt(0)
	s_waitcnt vmcnt(0)
	s_barrier
	v_mov_b32_e32 v49, v48
	ds_read_b128 v[20:23], v49
	ds_read_b128 v[104:107], v49 offset:2048
	s_waitcnt lgkmcnt(0)
	v_mfma_f32_16x16x32_bf16 v[20:23], v[20:23], v[12:15], v[24:27]
	s_nop 2
	ds_read_b128 v[24:27], v49 offset:4096
	v_mfma_f32_16x16x32_bf16 v[28:31], v[104:107], v[12:15], v[28:31]
	ds_read_b128 v[104:107], v49 offset:6144
	s_waitcnt lgkmcnt(0)
	v_mfma_f32_16x16x32_bf16 v[24:27], v[24:27], v[12:15], v[32:35]
	s_nop 2
	ds_read_b128 v[32:35], v49 offset:8192
	v_mfma_f32_16x16x32_bf16 v[36:39], v[104:107], v[12:15], v[36:39]
	ds_read_b128 v[104:107], v49 offset:10240
	s_waitcnt lgkmcnt(0)
	v_mfma_f32_16x16x32_bf16 v[32:35], v[32:35], v[12:15], v[40:43]
	s_nop 2
	ds_read_b128 v[40:43], v49 offset:12288
	ds_read_b128 v[108:111], v49 offset:14336
	v_mfma_f32_16x16x32_bf16 v[50:53], v[104:107], v[12:15], v[50:53]
	ds_read_b128 v[104:107], v49 offset:32768
	ds_read_b128 v[112:115], v49 offset:34816
	ds_read_b128 v[116:119], v49 offset:36864
	ds_read_b128 v[120:123], v49 offset:38912
	s_waitcnt lgkmcnt(0)
	v_mfma_f32_16x16x32_bf16 v[40:43], v[40:43], v[12:15], v[76:79]
	s_nop 2
	ds_read_b128 v[76:79], v49 offset:40960
	ds_read_b128 v[124:127], v49 offset:43008
	ds_read_b128 v[128:131], v49 offset:45056
	ds_read_b128 v[132:135], v49 offset:47104
	v_mfma_f32_16x16x32_bf16 v[96:99], v[108:111], v[12:15], v[96:99]
	s_add_u32 s100, s10, 0x11c00000
	s_addc_u32 s101, s11, 0
	s_mov_b32 m0, s22
	s_nop 0
	global_load_lds_dwordx4 v241, s[100:101]
	v_mfma_f32_16x16x32_bf16 v[66:69], v[104:107], v[12:15], v[66:69]
	v_mfma_f32_16x16x32_bf16 v[72:75], v[112:115], v[12:15], v[72:75]
	v_mfma_f32_16x16x32_bf16 v[80:83], v[116:119], v[12:15], v[80:83]
	v_mfma_f32_16x16x32_bf16 v[84:87], v[120:123], v[12:15], v[84:87]
	s_waitcnt lgkmcnt(0)
	v_mfma_f32_16x16x32_bf16 v[76:79], v[76:79], v[12:15], v[88:91]
	v_mfma_f32_16x16x32_bf16 v[88:91], v[124:127], v[12:15], v[92:95]
	s_nop 2
	ds_read_b128 v[92:95], v49 offset:15360
	ds_read_b128 v[104:107], v49 offset:13312
	ds_read_b128 v[108:111], v49 offset:11264
	ds_read_b128 v[112:115], v49 offset:9216
	v_mfma_f32_16x16x32_bf16 v[100:103], v[128:131], v[12:15], v[100:103]
	ds_read_b128 v[116:119], v49 offset:7168
	ds_read_b128 v[120:123], v49 offset:5120
	ds_read_b128 v[124:127], v49 offset:3072
	ds_read_b128 v[128:131], v49 offset:1024
	v_mfma_f32_16x16x32_bf16 v[12:15], v[132:135], v[12:15], v[16:19]
	s_add_u32 s100, s10, 0x11c08000
	s_addc_u32 s101, s11, 0
	s_mov_b32 m0, s21
	s_nop 0
	global_load_lds_dwordx4 v241, s[100:101]
	s_waitcnt lgkmcnt(0)
	v_mfma_f32_16x16x32_bf16 v[16:19], v[128:131], v[8:11], v[20:23]
	v_mfma_f32_16x16x32_bf16 v[20:23], v[124:127], v[8:11], v[28:31]
	v_mfma_f32_16x16x32_bf16 v[24:27], v[120:123], v[8:11], v[24:27]
	v_mfma_f32_16x16x32_bf16 v[28:31], v[116:119], v[8:11], v[36:39]
	v_mfma_f32_16x16x32_bf16 v[32:35], v[112:115], v[8:11], v[32:35]
	v_mfma_f32_16x16x32_bf16 v[36:39], v[108:111], v[8:11], v[50:53]
	s_nop 2
	ds_read_b128 v[50:53], v49 offset:33792
	ds_read_b128 v[108:111], v49 offset:35840
	ds_read_b128 v[112:115], v49 offset:37888
	ds_read_b128 v[116:119], v49 offset:39936
	v_mfma_f32_16x16x32_bf16 v[40:43], v[104:107], v[8:11], v[40:43]
	ds_read_b128 v[104:107], v49 offset:41984
	ds_read_b128 v[120:123], v49 offset:44032
	ds_read_b128 v[124:127], v49 offset:46080
	ds_read_b128 v[128:131], v49 offset:48128
	v_mfma_f32_16x16x32_bf16 v[92:95], v[92:95], v[8:11], v[96:99]
	s_add_u32 s100, s10, 0x11c00080
	s_addc_u32 s101, s11, 0
	s_mov_b32 m0, s20
	s_nop 0
	global_load_lds_dwordx4 v241, s[100:101]
	s_waitcnt lgkmcnt(0)
	v_mfma_f32_16x16x32_bf16 v[50:53], v[50:53], v[8:11], v[66:69]
	v_mfma_f32_16x16x32_bf16 v[66:69], v[108:111], v[8:11], v[72:75]
	v_mfma_f32_16x16x32_bf16 v[72:75], v[112:115], v[8:11], v[80:83]
	v_mfma_f32_16x16x32_bf16 v[80:83], v[116:119], v[8:11], v[84:87]
	v_mfma_f32_16x16x32_bf16 v[76:79], v[104:107], v[8:11], v[76:79]
	v_mfma_f32_16x16x32_bf16 v[84:87], v[120:123], v[8:11], v[88:91]
	s_nop 2
	ds_read_b128 v[88:91], v49 offset:30720
	ds_read_b128 v[96:99], v49 offset:28672
	ds_read_b128 v[104:107], v49 offset:26624
	ds_read_b128 v[108:111], v49 offset:24576
	v_mfma_f32_16x16x32_bf16 v[100:103], v[124:127], v[8:11], v[100:103]
	ds_read_b128 v[112:115], v49 offset:22528
	ds_read_b128 v[116:119], v49 offset:20480
	ds_read_b128 v[120:123], v49 offset:18432
	ds_read_b128 v[124:127], v49 offset:16384
	v_mfma_f32_16x16x32_bf16 v[8:11], v[128:131], v[8:11], v[12:15]
	s_add_u32 s100, s10, 0x11c08080
	s_addc_u32 s101, s11, 0
	s_mov_b32 m0, s23
	s_nop 0
	global_load_lds_dwordx4 v241, s[100:101]
	s_waitcnt lgkmcnt(0)
	v_mfma_f32_16x16x32_bf16 v[12:15], v[124:127], v[4:7], v[16:19]
	v_mfma_f32_16x16x32_bf16 v[16:19], v[120:123], v[4:7], v[20:23]
	v_mfma_f32_16x16x32_bf16 v[20:23], v[116:119], v[4:7], v[24:27]
	v_mfma_f32_16x16x32_bf16 v[24:27], v[112:115], v[4:7], v[28:31]
	v_mfma_f32_16x16x32_bf16 v[28:31], v[108:111], v[4:7], v[32:35]
	v_mfma_f32_16x16x32_bf16 v[32:35], v[104:107], v[4:7], v[36:39]
	s_nop 2
	ds_read_b128 v[36:39], v49 offset:49152
	ds_read_b128 v[104:107], v49 offset:51200
	ds_read_b128 v[108:111], v49 offset:53248
	ds_read_b128 v[112:115], v49 offset:55296
	v_mfma_f32_16x16x32_bf16 v[96:99], v[96:99], v[4:7], v[40:43]
	s_nop 2
	ds_read_b128 v[40:43], v49 offset:57344
	ds_read_b128 v[116:119], v49 offset:59392
	ds_read_b128 v[120:123], v49 offset:61440
	ds_read_b128 v[124:127], v49 offset:63488
	v_mfma_f32_16x16x32_bf16 v[88:91], v[88:91], v[4:7], v[92:95]
	s_add_u32 s100, s10, 0x11c10000
	s_addc_u32 s101, s11, 0
	s_mov_b32 m0, s24
	s_nop 0
	global_load_lds_dwordx4 v241, s[100:101]
	s_waitcnt lgkmcnt(0)
	v_mfma_f32_16x16x32_bf16 v[50:53], v[36:39], v[4:7], v[50:53]
	v_mfma_f32_16x16x32_bf16 v[66:69], v[104:107], v[4:7], v[66:69]
	v_mfma_f32_16x16x32_bf16 v[72:75], v[108:111], v[4:7], v[72:75]
	v_mfma_f32_16x16x32_bf16 v[80:83], v[112:115], v[4:7], v[80:83]
	v_mfma_f32_16x16x32_bf16 v[76:79], v[40:43], v[4:7], v[76:79]
	ds_read_b128 v[92:95], v49 offset:31744
	ds_read_b128 v[36:39], v49 offset:29696
	ds_read_b128 v[40:43], v49 offset:27648
	ds_read_b128 v[104:107], v49 offset:25600
	v_mfma_f32_16x16x32_bf16 v[84:87], v[116:119], v[4:7], v[84:87]
	v_mfma_f32_16x16x32_bf16 v[100:103], v[120:123], v[4:7], v[100:103]
	ds_read_b128 v[108:111], v49 offset:23552
	ds_read_b128 v[112:115], v49 offset:21504
	ds_read_b128 v[116:119], v49 offset:19456
	ds_read_b128 v[120:123], v49 offset:17408
	v_mfma_f32_16x16x32_bf16 v[124:127], v[124:127], v[4:7], v[8:11]
	s_add_u32 s100, s10, 0x11c18000
	s_addc_u32 s101, s11, 0
	s_mov_b32 m0, s25
	s_nop 0
	global_load_lds_dwordx4 v241, s[100:101]
	s_waitcnt lgkmcnt(0)
	v_mfma_f32_16x16x32_bf16 v[120:123], v[120:123], v[0:3], v[12:15]
	v_mfma_f32_16x16x32_bf16 v[116:119], v[116:119], v[0:3], v[16:19]
	ds_read_b128 v[4:7], v49 offset:50176
	ds_read_b128 v[8:11], v49 offset:52224
	ds_read_b128 v[12:15], v49 offset:54272
	ds_read_b128 v[16:19], v49 offset:56320
	v_mfma_f32_16x16x32_bf16 v[36:39], v[36:39], v[0:3], v[96:99]
	s_nop 2
	ds_read_b128 v[96:99], v49 offset:58368
	ds_read_b128 v[128:131], v49 offset:60416
	ds_read_b128 v[132:135], v49 offset:62464
	ds_read_b128 v[136:139], v49 offset:64512
	v_mfma_f32_16x16x32_bf16 v[112:115], v[112:115], v[0:3], v[20:23]
	v_mfma_f32_16x16x32_bf16 v[108:111], v[108:111], v[0:3], v[24:27]
	v_mfma_f32_16x16x32_bf16 v[104:107], v[104:107], v[0:3], v[28:31]
	v_mfma_f32_16x16x32_bf16 v[40:43], v[40:43], v[0:3], v[32:35]
	v_mfma_f32_16x16x32_bf16 v[32:35], v[92:95], v[0:3], v[88:91]
	s_add_u32 s100, s10, 0x11c10080
	s_addc_u32 s101, s11, 0
	s_mov_b32 m0, s26
	s_nop 0
	global_load_lds_dwordx4 v241, s[100:101]
	s_waitcnt lgkmcnt(0)
	v_mfma_f32_16x16x32_bf16 v[28:31], v[4:7], v[0:3], v[50:53]
	v_mfma_f32_16x16x32_bf16 v[24:27], v[8:11], v[0:3], v[66:69]
	v_mfma_f32_16x16x32_bf16 v[20:23], v[12:15], v[0:3], v[72:75]
	v_mfma_f32_16x16x32_bf16 v[16:19], v[16:19], v[0:3], v[80:83]
	v_mfma_f32_16x16x32_bf16 v[12:15], v[96:99], v[0:3], v[76:79]
	v_mfma_f32_16x16x32_bf16 v[8:11], v[128:131], v[0:3], v[84:87]
	v_mfma_f32_16x16x32_bf16 v[4:7], v[132:135], v[0:3], v[100:103]
	v_mfma_f32_16x16x32_bf16 v[0:3], v[136:139], v[0:3], v[124:127]
	s_add_u32 s100, s10, 0x11c18080
	s_addc_u32 s101, s11, 0
	s_mov_b32 m0, s27
	s_nop 0
	global_load_lds_dwordx4 v241, s[100:101]
	v_max_f32_e32 v49, v123, v123
	v_max_f32_e32 v50, v122, v122
	v_max_f32_e32 v49, v50, v49
	v_max_f32_e32 v50, v117, v117
	v_max_f32_e32 v51, v116, v116
	v_max_f32_e32 v50, v51, v50
	v_max_f32_e32 v51, v119, v119
	v_max_f32_e32 v52, v118, v118
	v_max3_f32 v49, v120, v121, v49
	v_max_f32_e32 v51, v52, v51
	v_max3_f32 v49, v49, v50, v51
	v_max_f32_e32 v50, v113, v113
	v_max_f32_e32 v51, v112, v112
	v_max_f32_e32 v50, v51, v50
	v_max_f32_e32 v51, v115, v115
	v_max_f32_e32 v52, v114, v114
	v_max_f32_e32 v51, v52, v51
	v_max3_f32 v49, v49, v50, v51
	v_max_f32_e32 v50, v109, v109
	v_max_f32_e32 v51, v108, v108
	v_max_f32_e32 v50, v51, v50
	v_max_f32_e32 v51, v111, v111
	v_max_f32_e32 v52, v110, v110
	v_max_f32_e32 v51, v52, v51
	v_max3_f32 v49, v49, v50, v51
	v_max_f32_e32 v50, v105, v105
	v_max_f32_e32 v51, v104, v104
	v_max_f32_e32 v50, v51, v50
	v_max_f32_e32 v51, v107, v107
	v_max_f32_e32 v52, v106, v106
	v_max_f32_e32 v51, v52, v51
	v_max3_f32 v49, v49, v50, v51
	v_max_f32_e32 v50, v41, v41
	v_max_f32_e32 v51, v40, v40
	v_max_f32_e32 v50, v51, v50
	v_max_f32_e32 v51, v43, v43
	v_max_f32_e32 v52, v42, v42
	v_max_f32_e32 v51, v52, v51
	v_max3_f32 v49, v49, v50, v51
	v_max_f32_e32 v50, v37, v37
	v_max_f32_e32 v51, v36, v36
	v_max_f32_e32 v50, v51, v50
	v_max_f32_e32 v51, v39, v39
	v_max_f32_e32 v52, v38, v38
	v_max_f32_e32 v51, v52, v51
	v_max3_f32 v49, v49, v50, v51
	v_max_f32_e32 v50, v33, v33
	v_max_f32_e32 v51, v32, v32
	v_max_f32_e32 v50, v51, v50
	v_max_f32_e32 v51, v35, v35
	v_max_f32_e32 v52, v34, v34
	v_max_f32_e32 v51, v52, v51
	v_max3_f32 v49, v49, v50, v51
	v_max_f32_e32 v50, v29, v29
	v_max_f32_e32 v51, v28, v28
	v_max_f32_e32 v50, v51, v50
	v_max_f32_e32 v51, v31, v31
	v_max_f32_e32 v52, v30, v30
	v_max_f32_e32 v51, v52, v51
	v_max3_f32 v49, v49, v50, v51
	v_max_f32_e32 v50, v25, v25
	v_max_f32_e32 v51, v24, v24
	v_max_f32_e32 v50, v51, v50
	v_max_f32_e32 v51, v27, v27
	v_max_f32_e32 v52, v26, v26
	v_max_f32_e32 v51, v52, v51
	v_max3_f32 v49, v49, v50, v51
	v_max_f32_e32 v50, v21, v21
	v_max_f32_e32 v51, v20, v20
	v_max_f32_e32 v50, v51, v50
	v_max_f32_e32 v51, v23, v23
	v_max_f32_e32 v52, v22, v22
	v_max_f32_e32 v51, v52, v51
	v_max3_f32 v49, v49, v50, v51
	v_max_f32_e32 v50, v17, v17
	v_max_f32_e32 v51, v16, v16
	v_max_f32_e32 v50, v51, v50
	v_max_f32_e32 v51, v19, v19
	v_max_f32_e32 v52, v18, v18
	v_max_f32_e32 v51, v52, v51
	v_max3_f32 v49, v49, v50, v51
	v_max_f32_e32 v50, v13, v13
	v_max_f32_e32 v51, v12, v12
	v_max_f32_e32 v50, v51, v50
	v_max_f32_e32 v51, v15, v15
	v_max_f32_e32 v52, v14, v14
	v_max_f32_e32 v51, v52, v51
	v_max3_f32 v49, v49, v50, v51
	v_max_f32_e32 v50, v9, v9
	v_max_f32_e32 v51, v8, v8
	v_max_f32_e32 v50, v51, v50
	v_max_f32_e32 v51, v11, v11
	v_max_f32_e32 v52, v10, v10
	v_max_f32_e32 v51, v52, v51
	v_max3_f32 v49, v49, v50, v51
	v_max_f32_e32 v50, v5, v5
	v_max_f32_e32 v51, v4, v4
	v_max_f32_e32 v50, v51, v50
	v_max_f32_e32 v51, v7, v7
	v_max_f32_e32 v52, v6, v6
	v_max_f32_e32 v51, v52, v51
	v_max3_f32 v49, v49, v50, v51
	v_max_f32_e32 v50, v1, v1
	v_max_f32_e32 v51, v0, v0
	v_max_f32_e32 v50, v51, v50
	v_max_f32_e32 v51, v3, v3
	v_max_f32_e32 v52, v2, v2
	v_max_f32_e32 v51, v52, v51
	v_max3_f32 v49, v49, v50, v51
	v_mbcnt_lo_u32_b32 v50, -1, 0
	v_mbcnt_hi_u32_b32 v50, -1, v50
	v_and_b32_e32 v52, 64, v50
	v_xor_b32_e32 v51, 16, v50
	v_add_u32_e32 v52, 64, v52
	v_cmp_lt_i32_e32 vcc, v51, v52
	s_nop 1
	v_cndmask_b32_e32 v51, v50, v51, vcc
	v_lshlrev_b32_e32 v51, 2, v51
	v_mov_b32_e32 v53, v49
	s_nop 1
	v_permlane16_swap_b32_e32 v53, v49
	s_waitcnt lgkmcnt(0)
	v_max_f32_e32 v53, v53, v53
	v_max_f32_e32 v49, v49, v53
	v_xor_b32_e32 v53, 32, v50
	v_cmp_lt_i32_e32 vcc, v53, v52
	s_nop 1
	v_cndmask_b32_e32 v50, v50, v53, vcc
	v_lshlrev_b32_e32 v50, 2, v50
	v_mov_b32_e32 v52, v49
	s_nop 1
	v_permlane32_swap_b32_e32 v52, v49
	s_waitcnt lgkmcnt(0)
	v_max_f32_e32 v52, v52, v52
	v_max_f32_e32 v49, v49, v52
	v_sub_f32_e32 v52, v120, v49
	v_exp_f32_e32 v52, v52
	v_sub_f32_e32 v53, v121, v49
	v_exp_f32_e32 v53, v53
	v_sub_f32_e32 v54, v122, v49
	v_exp_f32_e32 v54, v54
	v_sub_f32_e32 v55, v123, v49
	v_exp_f32_e32 v55, v55
	v_sub_f32_e32 v59, v116, v49
	v_add_f32_e32 v57, 0, v52
	v_exp_f32_e32 v59, v59
	v_sub_f32_e32 v62, v117, v49
	v_add_f32_e32 v57, v53, v57
	v_exp_f32_e32 v62, v62
	v_sub_f32_e32 v63, v118, v49
	v_add_f32_e32 v57, v54, v57
	v_exp_f32_e32 v63, v63
	v_sub_f32_e32 v64, v119, v49
	v_add_f32_e32 v57, v55, v57
	v_exp_f32_e32 v64, v64
	v_sub_f32_e32 v66, v112, v49
	v_add_f32_e32 v57, v59, v57
	v_exp_f32_e32 v66, v66
	v_sub_f32_e32 v67, v113, v49
	v_add_f32_e32 v57, v62, v57
	v_exp_f32_e32 v67, v67
	v_sub_f32_e32 v68, v114, v49
	v_add_f32_e32 v57, v63, v57
	v_exp_f32_e32 v68, v68
	v_sub_f32_e32 v69, v115, v49
	v_add_f32_e32 v57, v64, v57
	v_exp_f32_e32 v69, v69
	v_sub_f32_e32 v71, v108, v49
	v_add_f32_e32 v57, v66, v57
	v_exp_f32_e32 v71, v71
	v_sub_f32_e32 v72, v109, v49
	v_add_f32_e32 v57, v67, v57
	v_exp_f32_e32 v72, v72
	v_sub_f32_e32 v73, v110, v49
	v_add_f32_e32 v57, v68, v57
	v_exp_f32_e32 v73, v73
	v_sub_f32_e32 v74, v111, v49
	v_add_f32_e32 v57, v69, v57
	v_exp_f32_e32 v74, v74
	v_sub_f32_e32 v75, v104, v49
	v_add_f32_e32 v57, v71, v57
	v_exp_f32_e32 v75, v75
	v_sub_f32_e32 v76, v105, v49
	v_add_f32_e32 v57, v72, v57
	v_exp_f32_e32 v76, v76
	v_sub_f32_e32 v77, v106, v49
	v_add_f32_e32 v57, v73, v57
	v_exp_f32_e32 v77, v77
	v_sub_f32_e32 v78, v107, v49
	v_add_f32_e32 v57, v74, v57
	v_exp_f32_e32 v78, v78
	v_sub_f32_e32 v40, v40, v49
	v_add_f32_e32 v57, v75, v57
	v_exp_f32_e32 v40, v40
	v_sub_f32_e32 v41, v41, v49
	v_add_f32_e32 v57, v76, v57
	v_exp_f32_e32 v41, v41
	v_sub_f32_e32 v42, v42, v49
	v_add_f32_e32 v57, v77, v57
	v_exp_f32_e32 v42, v42
	v_sub_f32_e32 v43, v43, v49
	v_add_f32_e32 v57, v78, v57
	v_exp_f32_e32 v43, v43
	v_sub_f32_e32 v36, v36, v49
	v_add_f32_e32 v57, v40, v57
	v_exp_f32_e32 v36, v36
	v_sub_f32_e32 v37, v37, v49
	v_add_f32_e32 v57, v41, v57
	v_exp_f32_e32 v37, v37
	v_sub_f32_e32 v38, v38, v49
	v_add_f32_e32 v57, v42, v57
	v_exp_f32_e32 v38, v38
	v_sub_f32_e32 v39, v39, v49
	v_add_f32_e32 v57, v43, v57
	v_exp_f32_e32 v39, v39
	v_sub_f32_e32 v32, v32, v49
	v_add_f32_e32 v57, v36, v57
	v_exp_f32_e32 v32, v32
	v_sub_f32_e32 v33, v33, v49
	v_add_f32_e32 v57, v37, v57
	v_exp_f32_e32 v33, v33
	v_sub_f32_e32 v34, v34, v49
	v_add_f32_e32 v57, v38, v57
	v_exp_f32_e32 v34, v34
	v_sub_f32_e32 v35, v35, v49
	v_add_f32_e32 v57, v39, v57
	v_exp_f32_e32 v35, v35
	v_sub_f32_e32 v28, v28, v49
	v_add_f32_e32 v57, v32, v57
	v_exp_f32_e32 v79, v28
	v_sub_f32_e32 v28, v29, v49
	v_add_f32_e32 v57, v33, v57
	v_exp_f32_e32 v80, v28
	v_sub_f32_e32 v28, v30, v49
	v_add_f32_e32 v57, v34, v57
	v_exp_f32_e32 v81, v28
	v_sub_f32_e32 v28, v31, v49
	v_add_f32_e32 v57, v35, v57
	v_exp_f32_e32 v82, v28
	v_sub_f32_e32 v24, v24, v49
	v_add_f32_e32 v28, v79, v57
	v_exp_f32_e32 v57, v24
	v_sub_f32_e32 v24, v25, v49
	v_add_f32_e32 v28, v80, v28
	v_exp_f32_e32 v83, v24
	v_sub_f32_e32 v24, v26, v49
	v_add_f32_e32 v28, v81, v28
	v_exp_f32_e32 v84, v24
	v_sub_f32_e32 v24, v27, v49
	v_add_f32_e32 v28, v82, v28
	v_exp_f32_e32 v85, v24
	v_sub_f32_e32 v20, v20, v49
	v_add_f32_e32 v24, v57, v28
	v_exp_f32_e32 v86, v20
	v_sub_f32_e32 v20, v21, v49
	v_add_f32_e32 v24, v83, v24
	v_exp_f32_e32 v87, v20
	v_sub_f32_e32 v20, v22, v49
	v_add_f32_e32 v24, v84, v24
	v_exp_f32_e32 v88, v20
	v_sub_f32_e32 v20, v23, v49
	v_add_f32_e32 v24, v85, v24
	v_exp_f32_e32 v89, v20
	v_sub_f32_e32 v16, v16, v49
	v_add_f32_e32 v20, v86, v24
	v_exp_f32_e32 v90, v16
	v_sub_f32_e32 v16, v17, v49
	v_add_f32_e32 v20, v87, v20
	v_exp_f32_e32 v91, v16
	v_sub_f32_e32 v16, v18, v49
	v_add_f32_e32 v20, v88, v20
	v_exp_f32_e32 v92, v16
	v_sub_f32_e32 v16, v19, v49
	v_add_f32_e32 v20, v89, v20
	v_exp_f32_e32 v93, v16
	v_sub_f32_e32 v12, v12, v49
	v_add_f32_e32 v16, v90, v20
	v_exp_f32_e32 v94, v12
	v_sub_f32_e32 v12, v13, v49
	v_add_f32_e32 v16, v91, v16
	v_exp_f32_e32 v95, v12
	v_sub_f32_e32 v12, v14, v49
	v_add_f32_e32 v16, v92, v16
	v_exp_f32_e32 v96, v12
	v_sub_f32_e32 v12, v15, v49
	v_add_f32_e32 v16, v93, v16
	v_exp_f32_e32 v97, v12
	v_sub_f32_e32 v8, v8, v49
	v_add_f32_e32 v12, v94, v16
	v_exp_f32_e32 v98, v8
	v_sub_f32_e32 v8, v9, v49
	v_add_f32_e32 v12, v95, v12
	v_exp_f32_e32 v99, v8
	v_sub_f32_e32 v8, v10, v49
	v_add_f32_e32 v12, v96, v12
	v_exp_f32_e32 v100, v8
	v_sub_f32_e32 v8, v11, v49
	v_add_f32_e32 v12, v97, v12
	v_exp_f32_e32 v11, v8
	v_sub_f32_e32 v4, v4, v49
	v_add_f32_e32 v8, v98, v12
	v_exp_f32_e32 v101, v4
	v_sub_f32_e32 v4, v5, v49
	v_add_f32_e32 v8, v99, v8
	v_exp_f32_e32 v102, v4
	v_sub_f32_e32 v4, v6, v49
	v_add_f32_e32 v8, v100, v8
	v_exp_f32_e32 v103, v4
	v_sub_f32_e32 v4, v7, v49
	v_add_f32_e32 v8, v11, v8
	v_exp_f32_e32 v104, v4
	v_sub_f32_e32 v0, v0, v49
	v_add_f32_e32 v4, v101, v8
	v_exp_f32_e32 v105, v0
	v_sub_f32_e32 v0, v1, v49
	v_add_f32_e32 v4, v102, v4
	v_exp_f32_e32 v106, v0
	v_sub_f32_e32 v0, v2, v49
	v_add_f32_e32 v4, v103, v4
	v_exp_f32_e32 v107, v0
	v_sub_f32_e32 v0, v3, v49
	v_add_f32_e32 v4, v104, v4
	v_exp_f32_e32 v3, v0
	v_add_f32_e32 v0, v105, v4
	v_add_f32_e32 v0, v106, v0
	v_add_f32_e32 v0, v107, v0
	v_add_f32_e32 v0, v3, v0
	v_mov_b32_e32 v1, v0
	s_nop 1
	v_permlane16_swap_b32_e32 v1, v0
	v_cvt_pk_bf16_f32 v28, v52, v53
	v_cvt_pk_bf16_f32 v29, v54, v55
	v_cvt_pk_bf16_f32 v30, v59, v62
	v_cvt_pk_bf16_f32 v31, v63, v64
	s_waitcnt lgkmcnt(0)
	v_add_f32_e32 v0, v0, v1
	v_mov_b32_e32 v1, v0
	s_nop 1
	v_permlane32_swap_b32_e32 v1, v0
	v_cvt_pk_bf16_f32 v20, v66, v67
	v_cvt_pk_bf16_f32 v21, v68, v69
	v_cvt_pk_bf16_f32 v22, v71, v72
	v_cvt_pk_bf16_f32 v23, v73, v74
	s_waitcnt lgkmcnt(0)
	v_add_f32_e32 v49, v0, v1
	v_cvt_pk_bf16_f32 v24, v75, v76
	v_cvt_pk_bf16_f32 v25, v77, v78
	v_cvt_pk_bf16_f32 v26, v40, v41
	v_cvt_pk_bf16_f32 v27, v42, v43
	v_cvt_pk_bf16_f32 v16, v36, v37
	v_cvt_pk_bf16_f32 v17, v38, v39
	v_cvt_pk_bf16_f32 v18, v32, v33
	v_cvt_pk_bf16_f32 v19, v34, v35
	v_cvt_pk_bf16_f32 v12, v79, v80
	v_cvt_pk_bf16_f32 v13, v81, v82
	v_cvt_pk_bf16_f32 v14, v57, v83
	v_cvt_pk_bf16_f32 v15, v84, v85
	v_cvt_pk_bf16_f32 v4, v86, v87
	v_cvt_pk_bf16_f32 v5, v88, v89
	v_cvt_pk_bf16_f32 v6, v90, v91
	v_cvt_pk_bf16_f32 v7, v92, v93
	v_cvt_pk_bf16_f32 v8, v94, v95
	v_cvt_pk_bf16_f32 v9, v96, v97
	v_cvt_pk_bf16_f32 v10, v98, v99
	v_cvt_pk_bf16_f32 v11, v100, v11
	v_cvt_pk_bf16_f32 v0, v101, v102
	v_cvt_pk_bf16_f32 v1, v103, v104
	v_cvt_pk_bf16_f32 v2, v105, v106
	v_cvt_pk_bf16_f32 v3, v107, v3
	s_waitcnt vmcnt(0)
	s_waitcnt vmcnt(0)
	s_barrier
	v_mov_b32_e32 v64, v65
	v_div_scale_f32 v62, vcc, 1.0, v49, 1.0
	v_lshlrev_b32_e32 v54, 2, v70
	v_ashrrev_i32_e32 v55, 31, v54
	ds_read_b128 v[32:35], v64
	ds_read_b128 v[36:39], v64 offset:2048
	v_div_scale_f32 v57, s[0:1], v49, v49, 1.0
	v_rcp_f32_e32 v59, v57
	s_waitcnt lgkmcnt(0)
	v_mfma_f32_16x16x32_bf16 v[44:47], v[32:35], v[28:31], 0
	v_fma_f32 v40, -v57, v59, 1.0
	v_fmac_f32_e32 v59, v40, v59
	ds_read_b128 v[40:43], v64 offset:4096
	ds_read_b128 v[32:35], v64 offset:6144
	v_mul_f32_e32 v63, v62, v59
	v_fma_f32 v66, -v57, v63, v62
	v_fmac_f32_e32 v63, v66, v59
	v_mfma_f32_16x16x32_bf16 v[50:53], v[36:39], v[28:31], 0
	v_fma_f32 v36, -v57, v63, v62
	ds_read_b128 v[66:69], v64 offset:8192
	ds_read_b128 v[70:73], v64 offset:10240
	v_div_fmas_f32 v36, v36, v59, v63
	s_waitcnt lgkmcnt(0)
	v_mfma_f32_16x16x32_bf16 v[74:77], v[32:35], v[28:31], 0
	v_lshl_add_u64 v[34:35], v[54:55], 1, v[60:61]
	ds_read_b128 v[60:63], v64 offset:12288
	ds_read_b128 v[78:81], v64 offset:14336
	ds_read_b128 v[82:85], v64 offset:32768
	ds_read_b128 v[86:89], v64 offset:34816
	ds_read_b128 v[90:93], v64 offset:36864
	ds_read_b128 v[94:97], v64 offset:38912
	ds_read_b128 v[98:101], v64 offset:40960
	ds_read_b128 v[102:105], v64 offset:43008
	ds_read_b128 v[106:109], v64 offset:45056
	ds_read_b128 v[110:113], v64 offset:47104
	s_mov_b64 s[0:1], 0x1000000
	v_mfma_f32_16x16x32_bf16 v[38:41], v[40:43], v[28:31], 0
	v_div_fixup_f32 v36, v36, v49, 1.0
	v_lshl_add_u64 v[32:33], v[34:35], 0, s[0:1]
	v_mfma_f32_16x16x32_bf16 v[66:69], v[66:69], v[28:31], 0
	v_mfma_f32_16x16x32_bf16 v[70:73], v[70:73], v[28:31], 0
	s_waitcnt lgkmcnt(0)
	v_mfma_f32_16x16x32_bf16 v[60:63], v[60:63], v[28:31], 0
	v_mfma_f32_16x16x32_bf16 v[78:81], v[78:81], v[28:31], 0
	s_add_u32 s100, s10, 0x11c00100
	s_addc_u32 s101, s11, 0
	s_mov_b32 m0, s19
	s_nop 0
	global_load_lds_dwordx4 v241, s[100:101]
	ds_read_b128 v[114:117], v64 offset:30720
	ds_read_b128 v[118:121], v64 offset:28672
	ds_read_b128 v[122:125], v64 offset:26624
	ds_read_b128 v[126:129], v64 offset:24576
	ds_read_b128 v[130:133], v64 offset:22528
	ds_read_b128 v[134:137], v64 offset:20480
	ds_read_b128 v[138:141], v64 offset:18432
	ds_read_b128 v[142:145], v64 offset:16384
	v_mfma_f32_16x16x32_bf16 v[82:85], v[82:85], v[28:31], 0
	v_mfma_f32_16x16x32_bf16 v[86:89], v[86:89], v[28:31], 0
	v_mfma_f32_16x16x32_bf16 v[90:93], v[90:93], v[28:31], 0
	v_mfma_f32_16x16x32_bf16 v[94:97], v[94:97], v[28:31], 0
	v_mfma_f32_16x16x32_bf16 v[98:101], v[98:101], v[28:31], 0
	v_mfma_f32_16x16x32_bf16 v[102:105], v[102:105], v[28:31], 0
	v_mfma_f32_16x16x32_bf16 v[106:109], v[106:109], v[28:31], 0
	v_mfma_f32_16x16x32_bf16 v[110:113], v[110:113], v[28:31], 0
	s_add_u32 s100, s10, 0x11c08100
	s_addc_u32 s101, s11, 0
	s_mov_b32 m0, s13
	s_nop 0
	global_load_lds_dwordx4 v241, s[100:101]
	s_waitcnt lgkmcnt(0)
	v_mfma_f32_16x16x32_bf16 v[42:45], v[142:145], v[24:27], v[44:47]
	v_mfma_f32_16x16x32_bf16 v[50:53], v[138:141], v[24:27], v[50:53]
	v_mfma_f32_16x16x32_bf16 v[38:41], v[134:137], v[24:27], v[38:41]
	v_mfma_f32_16x16x32_bf16 v[74:77], v[130:133], v[24:27], v[74:77]
	v_mfma_f32_16x16x32_bf16 v[66:69], v[126:129], v[24:27], v[66:69]
	v_mfma_f32_16x16x32_bf16 v[70:73], v[122:125], v[24:27], v[70:73]
	ds_read_b128 v[122:125], v64 offset:49152
	ds_read_b128 v[126:129], v64 offset:51200
	ds_read_b128 v[130:133], v64 offset:53248
	ds_read_b128 v[134:137], v64 offset:55296
	v_mfma_f32_16x16x32_bf16 v[60:63], v[118:121], v[24:27], v[60:63]
	ds_read_b128 v[118:121], v64 offset:57344
	ds_read_b128 v[138:141], v64 offset:59392
	ds_read_b128 v[142:145], v64 offset:61440
	ds_read_b128 v[146:149], v64 offset:63488
	v_mfma_f32_16x16x32_bf16 v[78:81], v[114:117], v[24:27], v[78:81]
	s_add_u32 s100, s10, 0x11c00180
	s_addc_u32 s101, s11, 0
	s_mov_b32 m0, s12
	s_nop 0
	global_load_lds_dwordx4 v241, s[100:101]
	s_waitcnt lgkmcnt(0)
	v_mfma_f32_16x16x32_bf16 v[82:85], v[122:125], v[24:27], v[82:85]
	v_mfma_f32_16x16x32_bf16 v[86:89], v[126:129], v[24:27], v[86:89]
	v_mfma_f32_16x16x32_bf16 v[90:93], v[130:133], v[24:27], v[90:93]
	v_mfma_f32_16x16x32_bf16 v[94:97], v[134:137], v[24:27], v[94:97]
	v_mfma_f32_16x16x32_bf16 v[98:101], v[118:121], v[24:27], v[98:101]
	ds_read_b128 v[114:117], v64 offset:15360
	ds_read_b128 v[118:121], v64 offset:13312
	ds_read_b128 v[122:125], v64 offset:11264
	ds_read_b128 v[126:129], v64 offset:9216
	v_mfma_f32_16x16x32_bf16 v[102:105], v[138:141], v[24:27], v[102:105]
	v_mfma_f32_16x16x32_bf16 v[106:109], v[142:145], v[24:27], v[106:109]
	ds_read_b128 v[130:133], v64 offset:7168
	ds_read_b128 v[134:137], v64 offset:5120
	ds_read_b128 v[138:141], v64 offset:3072
	ds_read_b128 v[142:145], v64 offset:1024
	v_mfma_f32_16x16x32_bf16 v[110:113], v[146:149], v[24:27], v[110:113]
	s_add_u32 s100, s10, 0x11c08180
	s_addc_u32 s101, s11, 0
	s_mov_b32 m0, s14
	s_nop 0
	global_load_lds_dwordx4 v241, s[100:101]
	s_waitcnt lgkmcnt(0)
	v_mfma_f32_16x16x32_bf16 v[42:45], v[142:145], v[20:23], v[42:45]
	v_mfma_f32_16x16x32_bf16 v[50:53], v[138:141], v[20:23], v[50:53]
	v_mfma_f32_16x16x32_bf16 v[38:41], v[134:137], v[20:23], v[38:41]
	v_mfma_f32_16x16x32_bf16 v[74:77], v[130:133], v[20:23], v[74:77]
	v_mfma_f32_16x16x32_bf16 v[66:69], v[126:129], v[20:23], v[66:69]
	v_mfma_f32_16x16x32_bf16 v[70:73], v[122:125], v[20:23], v[70:73]
	ds_read_b128 v[122:125], v64 offset:33792
	ds_read_b128 v[126:129], v64 offset:35840
	ds_read_b128 v[130:133], v64 offset:37888
	ds_read_b128 v[134:137], v64 offset:39936
	v_mfma_f32_16x16x32_bf16 v[60:63], v[118:121], v[20:23], v[60:63]
	ds_read_b128 v[118:121], v64 offset:41984
	ds_read_b128 v[138:141], v64 offset:44032
	ds_read_b128 v[142:145], v64 offset:46080
	ds_read_b128 v[146:149], v64 offset:48128
	v_mfma_f32_16x16x32_bf16 v[78:81], v[114:117], v[20:23], v[78:81]
	s_add_u32 s100, s10, 0x11c10100
	s_addc_u32 s101, s11, 0
	s_mov_b32 m0, s15
	s_nop 0
	global_load_lds_dwordx4 v241, s[100:101]
	s_waitcnt lgkmcnt(0)
	v_mfma_f32_16x16x32_bf16 v[82:85], v[122:125], v[20:23], v[82:85]
	v_mfma_f32_16x16x32_bf16 v[86:89], v[126:129], v[20:23], v[86:89]
	v_mfma_f32_16x16x32_bf16 v[90:93], v[130:133], v[20:23], v[90:93]
	v_mfma_f32_16x16x32_bf16 v[94:97], v[134:137], v[20:23], v[94:97]
	v_mfma_f32_16x16x32_bf16 v[98:101], v[118:121], v[20:23], v[98:101]
	ds_read_b128 v[114:117], v64 offset:31744
	ds_read_b128 v[118:121], v64 offset:29696
	ds_read_b128 v[122:125], v64 offset:27648
	ds_read_b128 v[126:129], v64 offset:25600
	v_mfma_f32_16x16x32_bf16 v[102:105], v[138:141], v[20:23], v[102:105]
	v_mfma_f32_16x16x32_bf16 v[106:109], v[142:145], v[20:23], v[106:109]
	ds_read_b128 v[130:133], v64 offset:23552
	ds_read_b128 v[134:137], v64 offset:21504
	ds_read_b128 v[138:141], v64 offset:19456
	ds_read_b128 v[142:145], v64 offset:17408
	v_mfma_f32_16x16x32_bf16 v[110:113], v[146:149], v[20:23], v[110:113]
	s_add_u32 s100, s10, 0x11c18100
	s_addc_u32 s101, s11, 0
	s_mov_b32 m0, s16
	s_nop 0
	global_load_lds_dwordx4 v241, s[100:101]
	s_waitcnt lgkmcnt(0)
	v_mfma_f32_16x16x32_bf16 v[42:45], v[142:145], v[16:19], v[42:45]
	v_mfma_f32_16x16x32_bf16 v[50:53], v[138:141], v[16:19], v[50:53]
	v_mfma_f32_16x16x32_bf16 v[38:41], v[134:137], v[16:19], v[38:41]
	v_mfma_f32_16x16x32_bf16 v[74:77], v[130:133], v[16:19], v[74:77]
	v_mfma_f32_16x16x32_bf16 v[66:69], v[126:129], v[16:19], v[66:69]
	v_mfma_f32_16x16x32_bf16 v[70:73], v[122:125], v[16:19], v[70:73]
	ds_read_b128 v[122:125], v64 offset:50176
	ds_read_b128 v[126:129], v64 offset:52224
	ds_read_b128 v[130:133], v64 offset:54272
	ds_read_b128 v[134:137], v64 offset:56320
	v_mfma_f32_16x16x32_bf16 v[60:63], v[118:121], v[16:19], v[60:63]
	ds_read_b128 v[118:121], v64 offset:58368
	ds_read_b128 v[138:141], v64 offset:60416
	ds_read_b128 v[142:145], v64 offset:62464
	ds_read_b128 v[146:149], v64 offset:64512
	v_mfma_f32_16x16x32_bf16 v[78:81], v[114:117], v[16:19], v[78:81]
	s_add_u32 s100, s10, 0x11c10180
	s_addc_u32 s101, s11, 0
	s_mov_b32 m0, s17
	s_nop 0
	global_load_lds_dwordx4 v241, s[100:101]
	s_waitcnt lgkmcnt(0)
	v_mfma_f32_16x16x32_bf16 v[82:85], v[122:125], v[16:19], v[82:85]
	v_mfma_f32_16x16x32_bf16 v[86:89], v[126:129], v[16:19], v[86:89]
	v_mfma_f32_16x16x32_bf16 v[90:93], v[130:133], v[16:19], v[90:93]
	v_mfma_f32_16x16x32_bf16 v[94:97], v[134:137], v[16:19], v[94:97]
	v_mfma_f32_16x16x32_bf16 v[98:101], v[118:121], v[16:19], v[98:101]
	v_mfma_f32_16x16x32_bf16 v[102:105], v[138:141], v[16:19], v[102:105]
	v_mfma_f32_16x16x32_bf16 v[106:109], v[142:145], v[16:19], v[106:109]
	v_mfma_f32_16x16x32_bf16 v[110:113], v[146:149], v[16:19], v[110:113]
	s_add_u32 s100, s10, 0x11c18180
	s_addc_u32 s101, s11, 0
	s_mov_b32 m0, s18
	s_nop 0
	global_load_lds_dwordx4 v241, s[100:101]
	s_waitcnt vmcnt(0)
	s_waitcnt vmcnt(0)
	s_barrier
	v_mov_b32_e32 v37, v48
	ds_read_b128 v[114:117], v37
	ds_read_b128 v[118:121], v37 offset:2048
	s_waitcnt lgkmcnt(0)
	v_mfma_f32_16x16x32_bf16 v[42:45], v[114:117], v[12:15], v[42:45]
	ds_read_b128 v[114:117], v37 offset:4096
	v_mfma_f32_16x16x32_bf16 v[50:53], v[118:121], v[12:15], v[50:53]
	ds_read_b128 v[118:121], v37 offset:6144
	s_waitcnt lgkmcnt(0)
	v_mfma_f32_16x16x32_bf16 v[38:41], v[114:117], v[12:15], v[38:41]
	ds_read_b128 v[114:117], v37 offset:8192
	v_mfma_f32_16x16x32_bf16 v[74:77], v[118:121], v[12:15], v[74:77]
	ds_read_b128 v[118:121], v37 offset:10240
	s_waitcnt lgkmcnt(0)
	v_mfma_f32_16x16x32_bf16 v[66:69], v[114:117], v[12:15], v[66:69]
	ds_read_b128 v[114:117], v37 offset:12288
	ds_read_b128 v[122:125], v37 offset:14336
	v_mfma_f32_16x16x32_bf16 v[70:73], v[118:121], v[12:15], v[70:73]
	ds_read_b128 v[118:121], v37 offset:32768
	ds_read_b128 v[126:129], v37 offset:34816
	ds_read_b128 v[130:133], v37 offset:36864
	ds_read_b128 v[134:137], v37 offset:38912
	s_waitcnt lgkmcnt(0)
	v_mfma_f32_16x16x32_bf16 v[60:63], v[114:117], v[12:15], v[60:63]
	ds_read_b128 v[114:117], v37 offset:40960
	ds_read_b128 v[138:141], v37 offset:43008
	ds_read_b128 v[142:145], v37 offset:45056
	ds_read_b128 v[146:149], v37 offset:47104
	v_mfma_f32_16x16x32_bf16 v[78:81], v[122:125], v[12:15], v[78:81]
	s_add_u32 s100, s10, 0x11c20000
	s_addc_u32 s101, s11, 0
	s_mov_b32 m0, s22
	s_nop 0
	global_load_lds_dwordx4 v241, s[100:101]
	v_mfma_f32_16x16x32_bf16 v[82:85], v[118:121], v[12:15], v[82:85]
	v_mfma_f32_16x16x32_bf16 v[86:89], v[126:129], v[12:15], v[86:89]
	v_mfma_f32_16x16x32_bf16 v[90:93], v[130:133], v[12:15], v[90:93]
	v_mfma_f32_16x16x32_bf16 v[94:97], v[134:137], v[12:15], v[94:97]
	s_waitcnt lgkmcnt(0)
	v_mfma_f32_16x16x32_bf16 v[98:101], v[114:117], v[12:15], v[98:101]
	ds_read_b128 v[114:117], v37 offset:30720
	ds_read_b128 v[118:121], v37 offset:28672
	ds_read_b128 v[122:125], v37 offset:26624
	ds_read_b128 v[126:129], v37 offset:24576
	v_mfma_f32_16x16x32_bf16 v[102:105], v[138:141], v[12:15], v[102:105]
	v_mfma_f32_16x16x32_bf16 v[106:109], v[142:145], v[12:15], v[106:109]
	ds_read_b128 v[130:133], v37 offset:22528
	ds_read_b128 v[134:137], v37 offset:20480
	ds_read_b128 v[138:141], v37 offset:18432
	ds_read_b128 v[142:145], v37 offset:16384
	v_mfma_f32_16x16x32_bf16 v[110:113], v[146:149], v[12:15], v[110:113]
	s_add_u32 s100, s10, 0x11c28000
	s_addc_u32 s101, s11, 0
	s_mov_b32 m0, s21
	s_nop 0
	global_load_lds_dwordx4 v241, s[100:101]
	s_waitcnt lgkmcnt(0)
	v_mfma_f32_16x16x32_bf16 v[42:45], v[142:145], v[8:11], v[42:45]
	v_mfma_f32_16x16x32_bf16 v[50:53], v[138:141], v[8:11], v[50:53]
	v_mfma_f32_16x16x32_bf16 v[38:41], v[134:137], v[8:11], v[38:41]
	v_mfma_f32_16x16x32_bf16 v[74:77], v[130:133], v[8:11], v[74:77]
	v_mfma_f32_16x16x32_bf16 v[66:69], v[126:129], v[8:11], v[66:69]
	v_mfma_f32_16x16x32_bf16 v[70:73], v[122:125], v[8:11], v[70:73]
	ds_read_b128 v[122:125], v37 offset:49152
	ds_read_b128 v[126:129], v37 offset:51200
	ds_read_b128 v[130:133], v37 offset:53248
	ds_read_b128 v[134:137], v37 offset:55296
	v_mfma_f32_16x16x32_bf16 v[60:63], v[118:121], v[8:11], v[60:63]
	ds_read_b128 v[118:121], v37 offset:57344
	ds_read_b128 v[138:141], v37 offset:59392
	ds_read_b128 v[142:145], v37 offset:61440
	ds_read_b128 v[146:149], v37 offset:63488
	v_mfma_f32_16x16x32_bf16 v[78:81], v[114:117], v[8:11], v[78:81]
	s_add_u32 s100, s10, 0x11c20080
	s_addc_u32 s101, s11, 0
	s_mov_b32 m0, s20
	s_nop 0
	global_load_lds_dwordx4 v241, s[100:101]
	s_waitcnt lgkmcnt(0)
	v_mfma_f32_16x16x32_bf16 v[82:85], v[122:125], v[8:11], v[82:85]
	v_mfma_f32_16x16x32_bf16 v[86:89], v[126:129], v[8:11], v[86:89]
	v_mfma_f32_16x16x32_bf16 v[90:93], v[130:133], v[8:11], v[90:93]
	v_mfma_f32_16x16x32_bf16 v[94:97], v[134:137], v[8:11], v[94:97]
	v_mfma_f32_16x16x32_bf16 v[98:101], v[118:121], v[8:11], v[98:101]
	ds_read_b128 v[114:117], v37 offset:15360
	ds_read_b128 v[118:121], v37 offset:13312
	ds_read_b128 v[122:125], v37 offset:11264
	ds_read_b128 v[126:129], v37 offset:9216
	v_mfma_f32_16x16x32_bf16 v[102:105], v[138:141], v[8:11], v[102:105]
	v_mfma_f32_16x16x32_bf16 v[106:109], v[142:145], v[8:11], v[106:109]
	ds_read_b128 v[130:133], v37 offset:7168
	ds_read_b128 v[134:137], v37 offset:5120
	ds_read_b128 v[138:141], v37 offset:3072
	ds_read_b128 v[142:145], v37 offset:1024
	v_mfma_f32_16x16x32_bf16 v[110:113], v[146:149], v[8:11], v[110:113]
	s_add_u32 s100, s10, 0x11c28080
	s_addc_u32 s101, s11, 0
	s_mov_b32 m0, s23
	s_nop 0
	global_load_lds_dwordx4 v241, s[100:101]
	s_waitcnt lgkmcnt(0)
	v_mfma_f32_16x16x32_bf16 v[42:45], v[142:145], v[4:7], v[42:45]
	v_mfma_f32_16x16x32_bf16 v[50:53], v[138:141], v[4:7], v[50:53]
	v_mfma_f32_16x16x32_bf16 v[38:41], v[134:137], v[4:7], v[38:41]
	v_mfma_f32_16x16x32_bf16 v[74:77], v[130:133], v[4:7], v[74:77]
	v_mfma_f32_16x16x32_bf16 v[66:69], v[126:129], v[4:7], v[66:69]
	v_mfma_f32_16x16x32_bf16 v[70:73], v[122:125], v[4:7], v[70:73]
	ds_read_b128 v[122:125], v37 offset:33792
	ds_read_b128 v[126:129], v37 offset:35840
	ds_read_b128 v[130:133], v37 offset:37888
	ds_read_b128 v[134:137], v37 offset:39936
	v_mfma_f32_16x16x32_bf16 v[60:63], v[118:121], v[4:7], v[60:63]
	ds_read_b128 v[118:121], v37 offset:41984
	ds_read_b128 v[138:141], v37 offset:44032
	ds_read_b128 v[142:145], v37 offset:46080
	ds_read_b128 v[146:149], v37 offset:48128
	v_mfma_f32_16x16x32_bf16 v[78:81], v[114:117], v[4:7], v[78:81]
	s_add_u32 s100, s10, 0x11c30000
	s_addc_u32 s101, s11, 0
	s_mov_b32 m0, s24
	s_nop 0
	global_load_lds_dwordx4 v241, s[100:101]
	s_waitcnt lgkmcnt(0)
	v_mfma_f32_16x16x32_bf16 v[82:85], v[122:125], v[4:7], v[82:85]
	v_mfma_f32_16x16x32_bf16 v[86:89], v[126:129], v[4:7], v[86:89]
	v_mfma_f32_16x16x32_bf16 v[90:93], v[130:133], v[4:7], v[90:93]
	v_mfma_f32_16x16x32_bf16 v[94:97], v[134:137], v[4:7], v[94:97]
	v_mfma_f32_16x16x32_bf16 v[98:101], v[118:121], v[4:7], v[98:101]
	ds_read_b128 v[114:117], v37 offset:31744
	ds_read_b128 v[118:121], v37 offset:29696
	ds_read_b128 v[122:125], v37 offset:27648
	ds_read_b128 v[126:129], v37 offset:25600
	v_mfma_f32_16x16x32_bf16 v[102:105], v[138:141], v[4:7], v[102:105]
	v_mfma_f32_16x16x32_bf16 v[106:109], v[142:145], v[4:7], v[106:109]
	ds_read_b128 v[130:133], v37 offset:23552
	ds_read_b128 v[134:137], v37 offset:21504
	ds_read_b128 v[138:141], v37 offset:19456
	ds_read_b128 v[142:145], v37 offset:17408
	v_mfma_f32_16x16x32_bf16 v[110:113], v[146:149], v[4:7], v[110:113]
	s_add_u32 s100, s10, 0x11c38000
	s_addc_u32 s101, s11, 0
	s_mov_b32 m0, s25
	s_nop 0
	global_load_lds_dwordx4 v241, s[100:101]
	s_waitcnt lgkmcnt(0)
	v_mfma_f32_16x16x32_bf16 v[42:45], v[142:145], v[0:3], v[42:45]
	v_mfma_f32_16x16x32_bf16 v[50:53], v[138:141], v[0:3], v[50:53]
	v_mfma_f32_16x16x32_bf16 v[38:41], v[134:137], v[0:3], v[38:41]
	v_mfma_f32_16x16x32_bf16 v[74:77], v[130:133], v[0:3], v[74:77]
	v_mfma_f32_16x16x32_bf16 v[66:69], v[126:129], v[0:3], v[66:69]
	v_mfma_f32_16x16x32_bf16 v[70:73], v[122:125], v[0:3], v[70:73]
	ds_read_b128 v[122:125], v37 offset:50176
	ds_read_b128 v[126:129], v37 offset:52224
	ds_read_b128 v[130:133], v37 offset:54272
	ds_read_b128 v[134:137], v37 offset:56320
	v_mfma_f32_16x16x32_bf16 v[60:63], v[118:121], v[0:3], v[60:63]
	ds_read_b128 v[118:121], v37 offset:58368
	ds_read_b128 v[138:141], v37 offset:60416
	ds_read_b128 v[142:145], v37 offset:62464
	ds_read_b128 v[146:149], v37 offset:64512
	v_mfma_f32_16x16x32_bf16 v[78:81], v[114:117], v[0:3], v[78:81]
	s_add_u32 s100, s10, 0x11c30080
	s_addc_u32 s101, s11, 0
	s_mov_b32 m0, s26
	s_nop 0
	global_load_lds_dwordx4 v241, s[100:101]
	s_waitcnt lgkmcnt(0)
	v_mfma_f32_16x16x32_bf16 v[82:85], v[122:125], v[0:3], v[82:85]
	v_mfma_f32_16x16x32_bf16 v[86:89], v[126:129], v[0:3], v[86:89]
	v_mfma_f32_16x16x32_bf16 v[90:93], v[130:133], v[0:3], v[90:93]
	v_mfma_f32_16x16x32_bf16 v[94:97], v[134:137], v[0:3], v[94:97]
	v_mfma_f32_16x16x32_bf16 v[98:101], v[118:121], v[0:3], v[98:101]
	v_mfma_f32_16x16x32_bf16 v[102:105], v[138:141], v[0:3], v[102:105]
	v_mfma_f32_16x16x32_bf16 v[106:109], v[142:145], v[0:3], v[106:109]
	v_mfma_f32_16x16x32_bf16 v[110:113], v[146:149], v[0:3], v[110:113]
	s_add_u32 s100, s10, 0x11c38080
	s_addc_u32 s101, s11, 0
	s_mov_b32 m0, s27
	s_nop 0
	global_load_lds_dwordx4 v241, s[100:101]
	s_mov_b32 s0, 0x1000000
	v_add_co_u32_e32 v34, vcc, s0, v34
	v_addc_co_u32_e32 v35, vcc, 0, v35, vcc
	v_mbcnt_lo_u32_b32 v212, -1, 0
	v_mbcnt_hi_u32_b32 v212, -1, v212
	v_lshrrev_b32_e32 v212, 4, v212
	v_and_b32_e32 v212, 1, v212
	v_mul_u32_u24_e32 v212, 24, v212
	v_mov_b32_e32 v213, 0
	v_lshl_add_u64 v[214:215], v[32:33], 0, v[212:213]
	v_mul_f32_e32 v200, v36, v42
	v_mul_f32_e32 v204, v36, v43
	v_cvt_pk_bf16_f32 v200, v200, v204
	v_mul_f32_e32 v201, v36, v44
	v_mul_f32_e32 v204, v36, v45
	v_cvt_pk_bf16_f32 v201, v201, v204
	v_mul_f32_e32 v202, v36, v50
	v_mul_f32_e32 v204, v36, v51
	v_cvt_pk_bf16_f32 v202, v202, v204
	v_mul_f32_e32 v203, v36, v52
	v_mul_f32_e32 v204, v36, v53
	v_cvt_pk_bf16_f32 v203, v203, v204
	s_nop 1
	v_permlane16_swap_b32_e32 v200, v202
	v_permlane16_swap_b32_e32 v201, v203
	global_store_dwordx4 v[214:215], v[200:203], off offset:0
	v_mul_f32_e32 v206, v36, v38
	v_mul_f32_e32 v210, v36, v39
	v_cvt_pk_bf16_f32 v206, v206, v210
	v_mul_f32_e32 v207, v36, v40
	v_mul_f32_e32 v210, v36, v41
	v_cvt_pk_bf16_f32 v207, v207, v210
	v_mul_f32_e32 v208, v36, v74
	v_mul_f32_e32 v210, v36, v75
	v_cvt_pk_bf16_f32 v208, v208, v210
	v_mul_f32_e32 v209, v36, v76
	v_mul_f32_e32 v210, v36, v77
	v_cvt_pk_bf16_f32 v209, v209, v210
	s_nop 1
	v_permlane16_swap_b32_e32 v206, v208
	v_permlane16_swap_b32_e32 v207, v209
	global_store_dwordx4 v[214:215], v[206:209], off offset:64
	v_mul_f32_e32 v200, v36, v66
	v_mul_f32_e32 v204, v36, v67
	v_cvt_pk_bf16_f32 v200, v200, v204
	v_mul_f32_e32 v201, v36, v68
	v_mul_f32_e32 v204, v36, v69
	v_cvt_pk_bf16_f32 v201, v201, v204
	v_mul_f32_e32 v202, v36, v70
	v_mul_f32_e32 v204, v36, v71
	v_cvt_pk_bf16_f32 v202, v202, v204
	v_mul_f32_e32 v203, v36, v72
	v_mul_f32_e32 v204, v36, v73
	v_cvt_pk_bf16_f32 v203, v203, v204
	s_nop 1
	v_permlane16_swap_b32_e32 v200, v202
	v_permlane16_swap_b32_e32 v201, v203
	global_store_dwordx4 v[214:215], v[200:203], off offset:128
	v_mul_f32_e32 v206, v36, v60
	v_mul_f32_e32 v210, v36, v61
	v_cvt_pk_bf16_f32 v206, v206, v210
	v_mul_f32_e32 v207, v36, v62
	v_mul_f32_e32 v210, v36, v63
	v_cvt_pk_bf16_f32 v207, v207, v210
	v_mul_f32_e32 v208, v36, v78
	v_mul_f32_e32 v210, v36, v79
	v_cvt_pk_bf16_f32 v208, v208, v210
	v_mul_f32_e32 v209, v36, v80
	v_mul_f32_e32 v210, v36, v81
	v_cvt_pk_bf16_f32 v209, v209, v210
	s_nop 1
	v_permlane16_swap_b32_e32 v206, v208
	v_permlane16_swap_b32_e32 v207, v209
	global_store_dwordx4 v[214:215], v[206:209], off offset:192
	v_mul_f32_e32 v200, v36, v82
	v_mul_f32_e32 v204, v36, v83
	v_cvt_pk_bf16_f32 v200, v200, v204
	v_mul_f32_e32 v201, v36, v84
	v_mul_f32_e32 v204, v36, v85
	v_cvt_pk_bf16_f32 v201, v201, v204
	v_mul_f32_e32 v202, v36, v86
	v_mul_f32_e32 v204, v36, v87
	v_cvt_pk_bf16_f32 v202, v202, v204
	v_mul_f32_e32 v203, v36, v88
	v_mul_f32_e32 v204, v36, v89
	v_cvt_pk_bf16_f32 v203, v203, v204
	s_nop 1
	v_permlane16_swap_b32_e32 v200, v202
	v_permlane16_swap_b32_e32 v201, v203
	global_store_dwordx4 v[214:215], v[200:203], off offset:256
	v_mul_f32_e32 v206, v36, v90
	v_mul_f32_e32 v210, v36, v91
	v_cvt_pk_bf16_f32 v206, v206, v210
	v_mul_f32_e32 v207, v36, v92
	v_mul_f32_e32 v210, v36, v93
	v_cvt_pk_bf16_f32 v207, v207, v210
	v_mul_f32_e32 v208, v36, v94
	v_mul_f32_e32 v210, v36, v95
	v_cvt_pk_bf16_f32 v208, v208, v210
	v_mul_f32_e32 v209, v36, v96
	v_mul_f32_e32 v210, v36, v97
	v_cvt_pk_bf16_f32 v209, v209, v210
	s_nop 1
	v_permlane16_swap_b32_e32 v206, v208
	v_permlane16_swap_b32_e32 v207, v209
	global_store_dwordx4 v[214:215], v[206:209], off offset:320
	v_mul_f32_e32 v200, v36, v98
	v_mul_f32_e32 v204, v36, v99
	v_cvt_pk_bf16_f32 v200, v200, v204
	v_mul_f32_e32 v201, v36, v100
	v_mul_f32_e32 v204, v36, v101
	v_cvt_pk_bf16_f32 v201, v201, v204
	v_mul_f32_e32 v202, v36, v102
	v_mul_f32_e32 v204, v36, v103
	v_cvt_pk_bf16_f32 v202, v202, v204
	v_mul_f32_e32 v203, v36, v104
	v_mul_f32_e32 v204, v36, v105
	v_cvt_pk_bf16_f32 v203, v203, v204
	s_nop 1
	v_permlane16_swap_b32_e32 v200, v202
	v_permlane16_swap_b32_e32 v201, v203
	global_store_dwordx4 v[214:215], v[200:203], off offset:384
	v_mul_f32_e32 v206, v36, v106
	v_mul_f32_e32 v210, v36, v107
	v_cvt_pk_bf16_f32 v206, v206, v210
	v_mul_f32_e32 v207, v36, v108
	v_mul_f32_e32 v210, v36, v109
	v_cvt_pk_bf16_f32 v207, v207, v210
	v_mul_f32_e32 v208, v36, v110
	v_mul_f32_e32 v210, v36, v111
	v_cvt_pk_bf16_f32 v208, v208, v210
	v_mul_f32_e32 v209, v36, v112
	v_mul_f32_e32 v210, v36, v113
	v_cvt_pk_bf16_f32 v209, v209, v210
	s_nop 1
	v_permlane16_swap_b32_e32 v206, v208
	v_permlane16_swap_b32_e32 v207, v209
	global_store_dwordx4 v[214:215], v[206:209], off offset:448
	s_waitcnt vmcnt(8)
	s_waitcnt vmcnt(8)
	s_barrier
	ds_read_b128 v[38:41], v65
	ds_read_b128 v[42:45], v65 offset:2048
	ds_read_b128 v[50:53], v65 offset:4096
	ds_read_b128 v[54:57], v65 offset:6144
	ds_read_b128 v[58:61], v65 offset:8192
	ds_read_b128 v[66:69], v65 offset:10240
	ds_read_b128 v[70:73], v65 offset:12288
	ds_read_b128 v[74:77], v65 offset:14336
	ds_read_b128 v[78:81], v65 offset:32768
	ds_read_b128 v[82:85], v65 offset:34816
	ds_read_b128 v[86:89], v65 offset:36864
	ds_read_b128 v[90:93], v65 offset:38912
	ds_read_b128 v[94:97], v65 offset:40960
	ds_read_b128 v[98:101], v65 offset:43008
	ds_read_b128 v[102:105], v65 offset:45056
	ds_read_b128 v[106:109], v65 offset:47104
	s_waitcnt lgkmcnt(0)
	v_mfma_f32_16x16x32_bf16 v[38:41], v[38:41], v[28:31], 0
	v_mfma_f32_16x16x32_bf16 v[42:45], v[42:45], v[28:31], 0
	v_mfma_f32_16x16x32_bf16 v[50:53], v[50:53], v[28:31], 0
	v_mfma_f32_16x16x32_bf16 v[54:57], v[54:57], v[28:31], 0
	v_mfma_f32_16x16x32_bf16 v[58:61], v[58:61], v[28:31], 0
	v_mfma_f32_16x16x32_bf16 v[66:69], v[66:69], v[28:31], 0
	v_mfma_f32_16x16x32_bf16 v[70:73], v[70:73], v[28:31], 0
	v_mfma_f32_16x16x32_bf16 v[74:77], v[74:77], v[28:31], 0
	s_add_u32 s100, s10, 0x11c20100
	s_addc_u32 s101, s11, 0
	s_mov_b32 m0, s19
	s_nop 0
	global_load_lds_dwordx4 v241, s[100:101]
	ds_read_b128 v[110:113], v65 offset:30720
	ds_read_b128 v[114:117], v65 offset:28672
	ds_read_b128 v[118:121], v65 offset:26624
	ds_read_b128 v[122:125], v65 offset:24576
	ds_read_b128 v[126:129], v65 offset:22528
	ds_read_b128 v[130:133], v65 offset:20480
	ds_read_b128 v[134:137], v65 offset:18432
	ds_read_b128 v[138:141], v65 offset:16384
	v_mfma_f32_16x16x32_bf16 v[78:81], v[78:81], v[28:31], 0
	v_mfma_f32_16x16x32_bf16 v[82:85], v[82:85], v[28:31], 0
	v_mfma_f32_16x16x32_bf16 v[86:89], v[86:89], v[28:31], 0
	v_mfma_f32_16x16x32_bf16 v[90:93], v[90:93], v[28:31], 0
	v_mfma_f32_16x16x32_bf16 v[94:97], v[94:97], v[28:31], 0
	v_mfma_f32_16x16x32_bf16 v[98:101], v[98:101], v[28:31], 0
	v_mfma_f32_16x16x32_bf16 v[102:105], v[102:105], v[28:31], 0
	v_mfma_f32_16x16x32_bf16 v[28:31], v[106:109], v[28:31], 0
	s_add_u32 s100, s10, 0x11c28100
	s_addc_u32 s101, s11, 0
	s_mov_b32 m0, s13
	s_nop 0
	global_load_lds_dwordx4 v241, s[100:101]
	s_waitcnt lgkmcnt(0)
	v_mfma_f32_16x16x32_bf16 v[38:41], v[138:141], v[24:27], v[38:41]
	v_mfma_f32_16x16x32_bf16 v[42:45], v[134:137], v[24:27], v[42:45]
	v_mfma_f32_16x16x32_bf16 v[50:53], v[130:133], v[24:27], v[50:53]
	v_mfma_f32_16x16x32_bf16 v[54:57], v[126:129], v[24:27], v[54:57]
	v_mfma_f32_16x16x32_bf16 v[58:61], v[122:125], v[24:27], v[58:61]
	v_mfma_f32_16x16x32_bf16 v[66:69], v[118:121], v[24:27], v[66:69]
	ds_read_b128 v[106:109], v65 offset:49152
	ds_read_b128 v[118:121], v65 offset:51200
	ds_read_b128 v[122:125], v65 offset:53248
	ds_read_b128 v[126:129], v65 offset:55296
	v_mfma_f32_16x16x32_bf16 v[70:73], v[114:117], v[24:27], v[70:73]
	ds_read_b128 v[114:117], v65 offset:57344
	ds_read_b128 v[130:133], v65 offset:59392
	ds_read_b128 v[134:137], v65 offset:61440
	ds_read_b128 v[138:141], v65 offset:63488
	v_mfma_f32_16x16x32_bf16 v[74:77], v[110:113], v[24:27], v[74:77]
	s_add_u32 s100, s10, 0x11c20180
	s_addc_u32 s101, s11, 0
	s_mov_b32 m0, s12
	s_nop 0
	global_load_lds_dwordx4 v241, s[100:101]
	s_waitcnt lgkmcnt(0)
	v_mfma_f32_16x16x32_bf16 v[78:81], v[106:109], v[24:27], v[78:81]
	v_mfma_f32_16x16x32_bf16 v[82:85], v[118:121], v[24:27], v[82:85]
	v_mfma_f32_16x16x32_bf16 v[86:89], v[122:125], v[24:27], v[86:89]
	v_mfma_f32_16x16x32_bf16 v[90:93], v[126:129], v[24:27], v[90:93]
	v_mfma_f32_16x16x32_bf16 v[94:97], v[114:117], v[24:27], v[94:97]
	ds_read_b128 v[106:109], v65 offset:15360
	ds_read_b128 v[110:113], v65 offset:13312
	ds_read_b128 v[114:117], v65 offset:11264
	ds_read_b128 v[118:121], v65 offset:9216
	v_mfma_f32_16x16x32_bf16 v[98:101], v[130:133], v[24:27], v[98:101]
	v_mfma_f32_16x16x32_bf16 v[102:105], v[134:137], v[24:27], v[102:105]
	ds_read_b128 v[122:125], v65 offset:7168
	ds_read_b128 v[126:129], v65 offset:5120
	ds_read_b128 v[130:133], v65 offset:3072
	ds_read_b128 v[134:137], v65 offset:1024
	v_mfma_f32_16x16x32_bf16 v[24:27], v[138:141], v[24:27], v[28:31]
	s_add_u32 s100, s10, 0x11c28180
	s_addc_u32 s101, s11, 0
	s_mov_b32 m0, s14
	s_nop 0
	global_load_lds_dwordx4 v241, s[100:101]
	s_waitcnt lgkmcnt(0)
	v_mfma_f32_16x16x32_bf16 v[28:31], v[134:137], v[20:23], v[38:41]
	v_mfma_f32_16x16x32_bf16 v[38:41], v[130:133], v[20:23], v[42:45]
	v_mfma_f32_16x16x32_bf16 v[42:45], v[126:129], v[20:23], v[50:53]
	v_mfma_f32_16x16x32_bf16 v[50:53], v[122:125], v[20:23], v[54:57]
	v_mfma_f32_16x16x32_bf16 v[54:57], v[118:121], v[20:23], v[58:61]
	v_mfma_f32_16x16x32_bf16 v[58:61], v[114:117], v[20:23], v[66:69]
	s_nop 2
	ds_read_b128 v[66:69], v65 offset:33792
	ds_read_b128 v[114:117], v65 offset:35840
	ds_read_b128 v[118:121], v65 offset:37888
	ds_read_b128 v[122:125], v65 offset:39936
	v_mfma_f32_16x16x32_bf16 v[70:73], v[110:113], v[20:23], v[70:73]
	ds_read_b128 v[110:113], v65 offset:41984
	ds_read_b128 v[126:129], v65 offset:44032
	ds_read_b128 v[130:133], v65 offset:46080
	ds_read_b128 v[134:137], v65 offset:48128
	v_mfma_f32_16x16x32_bf16 v[74:77], v[106:109], v[20:23], v[74:77]
	s_add_u32 s100, s10, 0x11c30100
	s_addc_u32 s101, s11, 0
	s_mov_b32 m0, s15
	s_nop 0
	global_load_lds_dwordx4 v241, s[100:101]
	s_waitcnt lgkmcnt(0)
	v_mfma_f32_16x16x32_bf16 v[66:69], v[66:69], v[20:23], v[78:81]
	v_mfma_f32_16x16x32_bf16 v[78:81], v[114:117], v[20:23], v[82:85]
	v_mfma_f32_16x16x32_bf16 v[82:85], v[118:121], v[20:23], v[86:89]
	v_mfma_f32_16x16x32_bf16 v[86:89], v[122:125], v[20:23], v[90:93]
	v_mfma_f32_16x16x32_bf16 v[90:93], v[110:113], v[20:23], v[94:97]
	v_mfma_f32_16x16x32_bf16 v[94:97], v[126:129], v[20:23], v[98:101]
	s_nop 2
	ds_read_b128 v[98:101], v65 offset:31744
	ds_read_b128 v[106:109], v65 offset:29696
	ds_read_b128 v[110:113], v65 offset:27648
	ds_read_b128 v[114:117], v65 offset:25600
	v_mfma_f32_16x16x32_bf16 v[102:105], v[130:133], v[20:23], v[102:105]
	ds_read_b128 v[118:121], v65 offset:23552
	ds_read_b128 v[122:125], v65 offset:21504
	ds_read_b128 v[126:129], v65 offset:19456
	ds_read_b128 v[130:133], v65 offset:17408
	v_mfma_f32_16x16x32_bf16 v[20:23], v[134:137], v[20:23], v[24:27]
	s_add_u32 s100, s10, 0x11c38100
	s_addc_u32 s101, s11, 0
	s_mov_b32 m0, s16
	s_nop 0
	global_load_lds_dwordx4 v241, s[100:101]
	s_waitcnt lgkmcnt(0)
	v_mfma_f32_16x16x32_bf16 v[24:27], v[130:133], v[16:19], v[28:31]
	v_mfma_f32_16x16x32_bf16 v[28:31], v[126:129], v[16:19], v[38:41]
	v_mfma_f32_16x16x32_bf16 v[38:41], v[122:125], v[16:19], v[42:45]
	v_mfma_f32_16x16x32_bf16 v[42:45], v[118:121], v[16:19], v[50:53]
	v_mfma_f32_16x16x32_bf16 v[50:53], v[114:117], v[16:19], v[54:57]
	v_mfma_f32_16x16x32_bf16 v[54:57], v[110:113], v[16:19], v[58:61]
	s_nop 2
	ds_read_b128 v[58:61], v65 offset:50176
	ds_read_b128 v[110:113], v65 offset:52224
	ds_read_b128 v[114:117], v65 offset:54272
	ds_read_b128 v[118:121], v65 offset:56320
	v_mfma_f32_16x16x32_bf16 v[70:73], v[106:109], v[16:19], v[70:73]
	ds_read_b128 v[106:109], v65 offset:58368
	ds_read_b128 v[122:125], v65 offset:60416
	ds_read_b128 v[126:129], v65 offset:62464
	ds_read_b128 v[62:65], v65 offset:64512
	v_mfma_f32_16x16x32_bf16 v[74:77], v[98:101], v[16:19], v[74:77]
	s_add_u32 s100, s10, 0x11c30180
	s_addc_u32 s101, s11, 0
	s_mov_b32 m0, s17
	s_nop 0
	global_load_lds_dwordx4 v241, s[100:101]
	s_waitcnt lgkmcnt(0)
	v_mfma_f32_16x16x32_bf16 v[58:61], v[58:61], v[16:19], v[66:69]
	v_mfma_f32_16x16x32_bf16 v[66:69], v[110:113], v[16:19], v[78:81]
	v_mfma_f32_16x16x32_bf16 v[78:81], v[114:117], v[16:19], v[82:85]
	v_mfma_f32_16x16x32_bf16 v[82:85], v[118:121], v[16:19], v[86:89]
	v_mfma_f32_16x16x32_bf16 v[86:89], v[106:109], v[16:19], v[90:93]
	v_mfma_f32_16x16x32_bf16 v[90:93], v[122:125], v[16:19], v[94:97]
	v_mfma_f32_16x16x32_bf16 v[94:97], v[126:129], v[16:19], v[102:105]
	v_mfma_f32_16x16x32_bf16 v[16:19], v[62:65], v[16:19], v[20:23]
	s_add_u32 s100, s10, 0x11c38180
	s_addc_u32 s101, s11, 0
	s_mov_b32 m0, s18
	s_nop 0
	global_load_lds_dwordx4 v241, s[100:101]
	s_waitcnt vmcnt(0)
	s_waitcnt vmcnt(0)
	s_barrier
	s_nop 0
	ds_read_b128 v[20:23], v48
	ds_read_b128 v[62:65], v48 offset:2048
	s_waitcnt lgkmcnt(1)
	v_mfma_f32_16x16x32_bf16 v[20:23], v[20:23], v[12:15], v[24:27]
	s_nop 2
	ds_read_b128 v[24:27], v48 offset:4096
	s_waitcnt lgkmcnt(1)
	v_mfma_f32_16x16x32_bf16 v[28:31], v[62:65], v[12:15], v[28:31]
	ds_read_b128 v[62:65], v48 offset:6144
	s_waitcnt lgkmcnt(1)
	v_mfma_f32_16x16x32_bf16 v[24:27], v[24:27], v[12:15], v[38:41]
	s_nop 2
	ds_read_b128 v[38:41], v48 offset:8192
	s_waitcnt lgkmcnt(1)
	v_mfma_f32_16x16x32_bf16 v[42:45], v[62:65], v[12:15], v[42:45]
	ds_read_b128 v[62:65], v48 offset:10240
	s_waitcnt lgkmcnt(1)
	v_mfma_f32_16x16x32_bf16 v[38:41], v[38:41], v[12:15], v[50:53]
	s_nop 2
	ds_read_b128 v[50:53], v48 offset:12288
	ds_read_b128 v[98:101], v48 offset:14336
	s_waitcnt lgkmcnt(2)
	v_mfma_f32_16x16x32_bf16 v[54:57], v[62:65], v[12:15], v[54:57]
	ds_read_b128 v[62:65], v48 offset:32768
	ds_read_b128 v[102:105], v48 offset:34816
	ds_read_b128 v[106:109], v48 offset:36864
	ds_read_b128 v[110:113], v48 offset:38912
	s_waitcnt lgkmcnt(5)
	v_mfma_f32_16x16x32_bf16 v[50:53], v[50:53], v[12:15], v[70:73]
	s_nop 2
	ds_read_b128 v[70:73], v48 offset:40960
	ds_read_b128 v[114:117], v48 offset:43008
	ds_read_b128 v[118:121], v48 offset:45056
	ds_read_b128 v[122:125], v48 offset:47104
	s_waitcnt lgkmcnt(8)
	v_mfma_f32_16x16x32_bf16 v[74:77], v[98:101], v[12:15], v[74:77]
	s_waitcnt lgkmcnt(7)
	v_mfma_f32_16x16x32_bf16 v[58:61], v[62:65], v[12:15], v[58:61]
	s_waitcnt lgkmcnt(6)
	v_mfma_f32_16x16x32_bf16 v[62:65], v[102:105], v[12:15], v[66:69]
	s_waitcnt lgkmcnt(5)
	v_mfma_f32_16x16x32_bf16 v[66:69], v[106:109], v[12:15], v[78:81]
	s_waitcnt lgkmcnt(4)
	v_mfma_f32_16x16x32_bf16 v[78:81], v[110:113], v[12:15], v[82:85]
	s_waitcnt lgkmcnt(3)
	v_mfma_f32_16x16x32_bf16 v[70:73], v[70:73], v[12:15], v[86:89]
	s_waitcnt lgkmcnt(2)
	v_mfma_f32_16x16x32_bf16 v[82:85], v[114:117], v[12:15], v[90:93]
	s_nop 0
	ds_read_b128 v[86:89], v48 offset:30720
	s_nop 0
	ds_read_b128 v[90:93], v48 offset:28672
	ds_read_b128 v[98:101], v48 offset:26624
	ds_read_b128 v[102:105], v48 offset:24576
	s_waitcnt lgkmcnt(5)
	v_mfma_f32_16x16x32_bf16 v[94:97], v[118:121], v[12:15], v[94:97]
	ds_read_b128 v[106:109], v48 offset:22528
	ds_read_b128 v[110:113], v48 offset:20480
	ds_read_b128 v[114:117], v48 offset:18432
	ds_read_b128 v[118:121], v48 offset:16384
	s_waitcnt lgkmcnt(8)
	v_mfma_f32_16x16x32_bf16 v[12:15], v[122:125], v[12:15], v[16:19]
	s_waitcnt lgkmcnt(0)
	v_mfma_f32_16x16x32_bf16 v[16:19], v[118:121], v[8:11], v[20:23]
	v_mfma_f32_16x16x32_bf16 v[20:23], v[114:117], v[8:11], v[28:31]
	v_mfma_f32_16x16x32_bf16 v[24:27], v[110:113], v[8:11], v[24:27]
	v_mfma_f32_16x16x32_bf16 v[28:31], v[106:109], v[8:11], v[42:45]
	v_mfma_f32_16x16x32_bf16 v[38:41], v[102:105], v[8:11], v[38:41]
	v_mfma_f32_16x16x32_bf16 v[42:45], v[98:101], v[8:11], v[54:57]
	s_nop 2
	ds_read_b128 v[54:57], v48 offset:49152
	ds_read_b128 v[98:101], v48 offset:51200
	ds_read_b128 v[102:105], v48 offset:53248
	ds_read_b128 v[106:109], v48 offset:55296
	v_mfma_f32_16x16x32_bf16 v[50:53], v[90:93], v[8:11], v[50:53]
	ds_read_b128 v[90:93], v48 offset:57344
	ds_read_b128 v[110:113], v48 offset:59392
	ds_read_b128 v[114:117], v48 offset:61440
	ds_read_b128 v[118:121], v48 offset:63488
	v_mfma_f32_16x16x32_bf16 v[74:77], v[86:89], v[8:11], v[74:77]
	s_waitcnt lgkmcnt(7)
	v_mfma_f32_16x16x32_bf16 v[54:57], v[54:57], v[8:11], v[58:61]
	s_waitcnt lgkmcnt(6)
	v_mfma_f32_16x16x32_bf16 v[58:61], v[98:101], v[8:11], v[62:65]
	s_waitcnt lgkmcnt(5)
	v_mfma_f32_16x16x32_bf16 v[62:65], v[102:105], v[8:11], v[66:69]
	s_waitcnt lgkmcnt(4)
	v_mfma_f32_16x16x32_bf16 v[66:69], v[106:109], v[8:11], v[78:81]
	s_waitcnt lgkmcnt(3)
	v_mfma_f32_16x16x32_bf16 v[70:73], v[90:93], v[8:11], v[70:73]
	s_waitcnt lgkmcnt(2)
	v_mfma_f32_16x16x32_bf16 v[78:81], v[110:113], v[8:11], v[82:85]
	s_nop 2
	ds_read_b128 v[82:85], v48 offset:15360
	ds_read_b128 v[86:89], v48 offset:13312
	ds_read_b128 v[90:93], v48 offset:11264
	ds_read_b128 v[98:101], v48 offset:9216
	s_waitcnt lgkmcnt(5)
	v_mfma_f32_16x16x32_bf16 v[94:97], v[114:117], v[8:11], v[94:97]
	ds_read_b128 v[102:105], v48 offset:7168
	ds_read_b128 v[106:109], v48 offset:5120
	ds_read_b128 v[110:113], v48 offset:3072
	ds_read_b128 v[114:117], v48 offset:1024
	s_waitcnt lgkmcnt(8)
	v_mfma_f32_16x16x32_bf16 v[8:11], v[118:121], v[8:11], v[12:15]
	s_waitcnt lgkmcnt(0)
	v_mfma_f32_16x16x32_bf16 v[12:15], v[114:117], v[4:7], v[16:19]
	v_mfma_f32_16x16x32_bf16 v[16:19], v[110:113], v[4:7], v[20:23]
	v_mfma_f32_16x16x32_bf16 v[20:23], v[106:109], v[4:7], v[24:27]
	v_mfma_f32_16x16x32_bf16 v[24:27], v[102:105], v[4:7], v[28:31]
	v_mfma_f32_16x16x32_bf16 v[28:31], v[98:101], v[4:7], v[38:41]
	v_mfma_f32_16x16x32_bf16 v[38:41], v[90:93], v[4:7], v[42:45]
	s_nop 2
	ds_read_b128 v[42:45], v48 offset:33792
	ds_read_b128 v[90:93], v48 offset:35840
	ds_read_b128 v[98:101], v48 offset:37888
	ds_read_b128 v[102:105], v48 offset:39936
	v_mfma_f32_16x16x32_bf16 v[50:53], v[86:89], v[4:7], v[50:53]
	ds_read_b128 v[86:89], v48 offset:41984
	ds_read_b128 v[106:109], v48 offset:44032
	ds_read_b128 v[110:113], v48 offset:46080
	ds_read_b128 v[114:117], v48 offset:48128
	v_mfma_f32_16x16x32_bf16 v[74:77], v[82:85], v[4:7], v[74:77]
	s_waitcnt lgkmcnt(7)
	v_mfma_f32_16x16x32_bf16 v[42:45], v[42:45], v[4:7], v[54:57]
	s_waitcnt lgkmcnt(6)
	v_mfma_f32_16x16x32_bf16 v[54:57], v[90:93], v[4:7], v[58:61]
	s_waitcnt lgkmcnt(5)
	v_mfma_f32_16x16x32_bf16 v[58:61], v[98:101], v[4:7], v[62:65]
	s_waitcnt lgkmcnt(4)
	v_mfma_f32_16x16x32_bf16 v[62:65], v[102:105], v[4:7], v[66:69]
	s_waitcnt lgkmcnt(3)
	v_mfma_f32_16x16x32_bf16 v[66:69], v[86:89], v[4:7], v[70:73]
	s_waitcnt lgkmcnt(2)
	v_mfma_f32_16x16x32_bf16 v[70:73], v[106:109], v[4:7], v[78:81]
	s_nop 2
	ds_read_b128 v[78:81], v48 offset:31744
	ds_read_b128 v[82:85], v48 offset:29696
	ds_read_b128 v[86:89], v48 offset:27648
	ds_read_b128 v[90:93], v48 offset:25600
	s_waitcnt lgkmcnt(5)
	v_mfma_f32_16x16x32_bf16 v[94:97], v[110:113], v[4:7], v[94:97]
	ds_read_b128 v[98:101], v48 offset:23552
	ds_read_b128 v[102:105], v48 offset:21504
	ds_read_b128 v[106:109], v48 offset:19456
	ds_read_b128 v[110:113], v48 offset:17408
	s_waitcnt lgkmcnt(8)
	v_mfma_f32_16x16x32_bf16 v[4:7], v[114:117], v[4:7], v[8:11]
	s_waitcnt lgkmcnt(0)
	v_mfma_f32_16x16x32_bf16 v[8:11], v[110:113], v[0:3], v[12:15]
	v_mfma_f32_16x16x32_bf16 v[12:15], v[106:109], v[0:3], v[16:19]
	v_mfma_f32_16x16x32_bf16 v[16:19], v[102:105], v[0:3], v[20:23]
	v_mfma_f32_16x16x32_bf16 v[20:23], v[98:101], v[0:3], v[24:27]
	v_mfma_f32_16x16x32_bf16 v[24:27], v[90:93], v[0:3], v[28:31]
	v_mfma_f32_16x16x32_bf16 v[28:31], v[86:89], v[0:3], v[38:41]
	s_nop 2
	ds_read_b128 v[38:41], v48 offset:50176
	ds_read_b128 v[86:89], v48 offset:52224
	ds_read_b128 v[90:93], v48 offset:54272
	ds_read_b128 v[98:101], v48 offset:56320
	v_mfma_f32_16x16x32_bf16 v[50:53], v[82:85], v[0:3], v[50:53]
	ds_read_b128 v[82:85], v48 offset:58368
	ds_read_b128 v[102:105], v48 offset:60416
	ds_read_b128 v[106:109], v48 offset:62464
	ds_read_b128 v[46:49], v48 offset:64512
	v_mfma_f32_16x16x32_bf16 v[74:77], v[78:81], v[0:3], v[74:77]
	s_waitcnt lgkmcnt(7)
	v_mfma_f32_16x16x32_bf16 v[38:41], v[38:41], v[0:3], v[42:45]
	s_waitcnt lgkmcnt(6)
	v_mfma_f32_16x16x32_bf16 v[42:45], v[86:89], v[0:3], v[54:57]
	s_waitcnt lgkmcnt(5)
	v_mfma_f32_16x16x32_bf16 v[54:57], v[90:93], v[0:3], v[58:61]
	s_waitcnt lgkmcnt(4)
	v_mfma_f32_16x16x32_bf16 v[58:61], v[98:101], v[0:3], v[62:65]
	s_waitcnt lgkmcnt(3)
	v_mfma_f32_16x16x32_bf16 v[62:65], v[82:85], v[0:3], v[66:69]
	s_waitcnt lgkmcnt(2)
	v_mfma_f32_16x16x32_bf16 v[66:69], v[102:105], v[0:3], v[70:73]
	s_waitcnt lgkmcnt(1)
	v_mfma_f32_16x16x32_bf16 v[70:73], v[106:109], v[0:3], v[94:97]
	s_waitcnt lgkmcnt(0)
	v_mfma_f32_16x16x32_bf16 v[0:3], v[46:49], v[0:3], v[4:7]
	s_nop 2
	v_mul_f32_e32 v200, v36, v8
	v_mul_f32_e32 v204, v36, v9
	v_cvt_pk_bf16_f32 v200, v200, v204
	v_mul_f32_e32 v201, v36, v10
	v_mul_f32_e32 v204, v36, v11
	v_cvt_pk_bf16_f32 v201, v201, v204
	v_mul_f32_e32 v202, v36, v12
	v_mul_f32_e32 v204, v36, v13
	v_cvt_pk_bf16_f32 v202, v202, v204
	v_mul_f32_e32 v203, v36, v14
	v_mul_f32_e32 v204, v36, v15
	v_cvt_pk_bf16_f32 v203, v203, v204
	s_nop 1
	v_permlane16_swap_b32_e32 v200, v202
	v_permlane16_swap_b32_e32 v201, v203
	global_store_dwordx4 v[214:215], v[200:203], off offset:512
	v_mul_f32_e32 v206, v36, v16
	v_mul_f32_e32 v210, v36, v17
	v_cvt_pk_bf16_f32 v206, v206, v210
	v_mul_f32_e32 v207, v36, v18
	v_mul_f32_e32 v210, v36, v19
	v_cvt_pk_bf16_f32 v207, v207, v210
	v_mul_f32_e32 v208, v36, v20
	v_mul_f32_e32 v210, v36, v21
	v_cvt_pk_bf16_f32 v208, v208, v210
	v_mul_f32_e32 v209, v36, v22
	v_mul_f32_e32 v210, v36, v23
	v_cvt_pk_bf16_f32 v209, v209, v210
	s_nop 1
	v_permlane16_swap_b32_e32 v206, v208
	v_permlane16_swap_b32_e32 v207, v209
	global_store_dwordx4 v[214:215], v[206:209], off offset:576
	v_mul_f32_e32 v200, v36, v24
	v_mul_f32_e32 v204, v36, v25
	v_cvt_pk_bf16_f32 v200, v200, v204
	v_mul_f32_e32 v201, v36, v26
	v_mul_f32_e32 v204, v36, v27
	v_cvt_pk_bf16_f32 v201, v201, v204
	v_mul_f32_e32 v202, v36, v28
	v_mul_f32_e32 v204, v36, v29
	v_cvt_pk_bf16_f32 v202, v202, v204
	v_mul_f32_e32 v203, v36, v30
	v_mul_f32_e32 v204, v36, v31
	v_cvt_pk_bf16_f32 v203, v203, v204
	s_nop 1
	v_permlane16_swap_b32_e32 v200, v202
	v_permlane16_swap_b32_e32 v201, v203
	global_store_dwordx4 v[214:215], v[200:203], off offset:640
	v_mul_f32_e32 v206, v36, v50
	v_mul_f32_e32 v210, v36, v51
	v_cvt_pk_bf16_f32 v206, v206, v210
	v_mul_f32_e32 v207, v36, v52
	v_mul_f32_e32 v210, v36, v53
	v_cvt_pk_bf16_f32 v207, v207, v210
	v_mul_f32_e32 v208, v36, v74
	v_mul_f32_e32 v210, v36, v75
	v_cvt_pk_bf16_f32 v208, v208, v210
	v_mul_f32_e32 v209, v36, v76
	v_mul_f32_e32 v210, v36, v77
	v_cvt_pk_bf16_f32 v209, v209, v210
	s_nop 1
	v_permlane16_swap_b32_e32 v206, v208
	v_permlane16_swap_b32_e32 v207, v209
	global_store_dwordx4 v[214:215], v[206:209], off offset:704
	v_mul_f32_e32 v200, v36, v38
	v_mul_f32_e32 v204, v36, v39
	v_cvt_pk_bf16_f32 v200, v200, v204
	v_mul_f32_e32 v201, v36, v40
	v_mul_f32_e32 v204, v36, v41
	v_cvt_pk_bf16_f32 v201, v201, v204
	v_mul_f32_e32 v202, v36, v42
	v_mul_f32_e32 v204, v36, v43
	v_cvt_pk_bf16_f32 v202, v202, v204
	v_mul_f32_e32 v203, v36, v44
	v_mul_f32_e32 v204, v36, v45
	v_cvt_pk_bf16_f32 v203, v203, v204
	s_nop 1
	v_permlane16_swap_b32_e32 v200, v202
	v_permlane16_swap_b32_e32 v201, v203
	global_store_dwordx4 v[214:215], v[200:203], off offset:768
	v_mul_f32_e32 v206, v36, v54
	v_mul_f32_e32 v210, v36, v55
	v_cvt_pk_bf16_f32 v206, v206, v210
	v_mul_f32_e32 v207, v36, v56
	v_mul_f32_e32 v210, v36, v57
	v_cvt_pk_bf16_f32 v207, v207, v210
	v_mul_f32_e32 v208, v36, v58
	v_mul_f32_e32 v210, v36, v59
	v_cvt_pk_bf16_f32 v208, v208, v210
	v_mul_f32_e32 v209, v36, v60
	v_mul_f32_e32 v210, v36, v61
	v_cvt_pk_bf16_f32 v209, v209, v210
	s_nop 1
	v_permlane16_swap_b32_e32 v206, v208
	v_permlane16_swap_b32_e32 v207, v209
	global_store_dwordx4 v[214:215], v[206:209], off offset:832
	v_mul_f32_e32 v200, v36, v62
	v_mul_f32_e32 v204, v36, v63
	v_cvt_pk_bf16_f32 v200, v200, v204
	v_mul_f32_e32 v201, v36, v64
	v_mul_f32_e32 v204, v36, v65
	v_cvt_pk_bf16_f32 v201, v201, v204
	v_mul_f32_e32 v202, v36, v66
	v_mul_f32_e32 v204, v36, v67
	v_cvt_pk_bf16_f32 v202, v202, v204
	v_mul_f32_e32 v203, v36, v68
	v_mul_f32_e32 v204, v36, v69
	v_cvt_pk_bf16_f32 v203, v203, v204
	s_nop 1
	v_permlane16_swap_b32_e32 v200, v202
	v_permlane16_swap_b32_e32 v201, v203
	global_store_dwordx4 v[214:215], v[200:203], off offset:896
	v_mul_f32_e32 v206, v36, v70
	v_mul_f32_e32 v210, v36, v71
	v_cvt_pk_bf16_f32 v206, v206, v210
	v_mul_f32_e32 v207, v36, v72
	v_mul_f32_e32 v210, v36, v73
	v_cvt_pk_bf16_f32 v207, v207, v210
	v_mul_f32_e32 v208, v36, v0
	v_mul_f32_e32 v210, v36, v1
	v_cvt_pk_bf16_f32 v208, v208, v210
	v_mul_f32_e32 v209, v36, v2
	v_mul_f32_e32 v210, v36, v3
	v_cvt_pk_bf16_f32 v209, v209, v210
	s_nop 1
	v_permlane16_swap_b32_e32 v206, v208
	v_permlane16_swap_b32_e32 v207, v209
	global_store_dwordx4 v[214:215], v[206:209], off offset:960
	s_waitcnt vmcnt(0)
	s_barrier

.LBB0_1739:
.LBB0_1740:
	s_add_i32 s0, 0, 0x23f94
	s_waitcnt vmcnt(0)
	v_mov_b32_e32 v0, s0
	v_mbcnt_lo_u32_b32 v58, -1, 0
	v_mbcnt_hi_u32_b32 v58, -1, v58
	ds_read_b32 v0, v0
	v_lshlrev_b32_e32 v71, 4, v58
	v_and_b32_e32 v59, 15, v58
	s_mov_b32 s1, 0
	v_ashrrev_i32_e32 v70, 4, v58
	s_waitcnt lgkmcnt(0)
	v_readfirstlane_b32 s0, v0
	s_and_b32 s4, s0, 7
	s_mul_i32 s5, s4, 0x1400000
	s_add_u32 s5, s94, s5
	s_addc_u32 s6, s95, 0
	s_lshl_b32 s4, s4, 22
	s_sub_u32 s4, 0, s4
	s_subb_u32 s7, 0, 0
	s_add_u32 s4, s5, s4
	s_addc_u32 s5, s6, s7
	s_lshl_b32 s8, s88, 10
	v_add_u32_e32 v0, s8, v71
	v_ashrrev_i32_e32 v1, 31, v0
	v_lshrrev_b32_e32 v1, 22, v1
	v_add_u32_e32 v1, v0, v1
	v_ashrrev_i32_e32 v1, 10, v1
	v_mul_i32_i24_e32 v2, 0x400, v1
	v_sub_u32_e32 v2, v0, v2
	v_lshrrev_b32_e32 v3, 4, v2
	v_bitop3_b32 v2, v3, v2, 32 bitop3:0x6c
	v_ashrrev_i32_e32 v4, 31, v2
	v_lshrrev_b32_e32 v4, 26, v4
	v_lshlrev_b32_e32 v3, 3, v1
	v_add_u32_e32 v4, v2, v4
	v_and_b32_e32 v3, -16, v3
	v_ashrrev_i32_e32 v5, 6, v4
	v_add_u32_e32 v104, v5, v3
	v_and_b32_e32 v3, 0xc0, v4
	v_lshlrev_b32_e32 v1, 5, v1
	v_sub_u32_e32 v2, v2, v3
	v_mov_b32_e32 v3, 1
	v_and_b32_e32 v1, 32, v1
	v_ashrrev_i16_sdwa v2, v3, sext(v2) dst_sel:DWORD dst_unused:UNUSED_PAD src0_sel:DWORD src1_sel:BYTE_0
	v_add_u32_sdwa v1, v1, sext(v2) dst_sel:DWORD dst_unused:UNUSED_PAD src0_sel:DWORD src1_sel:WORD_0
	v_lshlrev_b32_e32 v2, 10, v104
	v_add_u32_e32 v0, 0x2000, v0
	v_lshl_add_u32 v62, v1, 1, v2
	v_ashrrev_i32_e32 v1, 31, v0
	v_lshrrev_b32_e32 v1, 22, v1
	v_add_u32_e32 v1, v0, v1
	v_ashrrev_i32_e32 v1, 10, v1
	v_mul_i32_i24_e32 v2, 0x400, v1
	v_sub_u32_e32 v0, v0, v2
	v_lshrrev_b32_e32 v2, 4, v0
	s_lshl_b32 s6, s0, 3
	v_bitop3_b32 v0, v2, v0, 32 bitop3:0x6c
	s_and_b32 s6, s6, 56
	s_ashr_i32 s7, s0, 5
	v_ashrrev_i32_e32 v4, 31, v0
	s_add_i32 s9, s6, s7
	v_lshrrev_b32_e32 v4, 26, v4
	s_ashr_i32 s12, s9, 5
	v_lshlrev_b32_e32 v2, 3, v1
	v_add_u32_e32 v4, v0, v4
	s_bfe_u32 s0, s0, 0x20003
	s_lshl_b32 s6, s12, 2
	v_and_b32_e32 v2, -16, v2
	v_ashrrev_i32_e32 v5, 6, v4
	s_or_b32 s6, s6, s0
	v_add_u32_e32 v108, v5, v2
	v_and_b32_e32 v2, 0xffc0, v4
	s_ashr_i32 s7, s6, 31
	v_sub_u32_e32 v0, v0, v2
	s_lshl_b64 s[6:7], s[6:7], 18
	v_lshrrev_b16_e32 v2, 7, v0
	s_add_u32 s10, s94, s6
	v_and_b32_e32 v2, 1, v2
	s_addc_u32 s11, s95, s7
	v_lshlrev_b32_e32 v1, 5, v1
	v_add_u16_e32 v0, v0, v2
	s_add_u32 s6, s10, 0x11600000
	v_and_b32_e32 v1, 32, v1
	v_ashrrev_i16_sdwa v0, v3, sext(v0) dst_sel:DWORD dst_unused:UNUSED_PAD src0_sel:DWORD src1_sel:BYTE_0
	s_addc_u32 s7, s11, 0
	s_lshl_b32 s9, s9, 7
	v_add_u32_sdwa v0, v1, sext(v0) dst_sel:DWORD dst_unused:UNUSED_PAD src0_sel:DWORD src1_sel:WORD_0
	v_lshlrev_b32_e32 v1, 10, v108
	s_lshl_b32 s12, s12, 12
	s_and_b32 s9, s9, 0xf80
	v_lshl_add_u32 v64, v0, 1, v1
	v_lshl_or_b32 v1, s88, 4, v59
	s_or_b32 s9, s12, s9
	v_add_u32_e32 v2, s9, v1
	v_ashrrev_i32_e32 v3, 31, v2
	v_lshlrev_b64 v[2:3], 12, v[2:3]
	s_lshl_b32 s0, s0, 10
	v_lshl_add_u64 v[2:3], s[4:5], 0, v[2:3]
	v_lshlrev_b32_e32 v0, 3, v70
	v_lshl_add_u64 v[2:3], v[2:3], 0, s[0:1]
	s_mov_b64 s[0:1], 0x13000000
	v_ashrrev_i32_e32 v1, 31, v0
	v_lshl_add_u64 v[60:61], v[2:3], 0, s[0:1]
	v_lshl_add_u64 v[0:1], v[0:1], 1, v[60:61]
	s_mov_b64 s[0:1], 0xc00000
	v_lshl_add_u64 v[2:3], v[0:1], 0, s[0:1]
	s_mov_b32 s0, 0xc00000
	v_add_co_u32_e32 v0, vcc, s0, v0
	s_add_i32 s22, s8, 0
	s_nop 0
	v_addc_co_u32_e32 v1, vcc, 0, v1, vcc
	v_mov_b32_e32 v63, 0
	s_mov_b32 m0, s22
	s_add_i32 s21, s22, 0x2000
	global_load_dwordx4 v[72:75], v[2:3], off offset:64
	global_load_dwordx4 v[52:55], v[2:3], off offset:128
	global_load_dwordx4 v[48:51], v[2:3], off offset:192
	global_load_dwordx4 v[76:79], v[0:1], off
	v_mov_b32_e32 v65, v63
	global_load_lds_dwordx4 v62, s[6:7]
	v_mov_b32_e32 v240, v62
	s_mov_b32 m0, s21
	v_lshl_add_u64 v[66:67], s[6:7], 0, v[62:63]
	v_lshl_add_u64 v[68:69], s[6:7], 0, v[64:65]
	global_load_lds_dwordx4 v64, s[6:7]
	s_add_i32 s20, s22, 0x4000
	s_mov_b64 s[6:7], 0x80
	s_add_i32 s23, s22, 0x6000
	v_lshl_add_u64 v[56:57], v[66:67], 0, s[6:7]
	s_mov_b32 m0, s20
	s_add_u32 s0, s10, 0x11620000
	global_load_lds_dwordx4 v[56:57], off
	v_lshl_add_u64 v[56:57], v[68:69], 0, s[6:7]
	s_mov_b32 m0, s23
	s_addc_u32 s1, s11, 0
	s_add_i32 s24, s22, 0x8000
	global_load_lds_dwordx4 v[56:57], off
	s_mov_b32 m0, s24
	s_add_i32 s25, s22, 0xa000
	global_load_lds_dwordx4 v62, s[0:1]
	s_mov_b32 m0, s25
	s_mov_b64 s[4:5], 0x180
	global_load_lds_dwordx4 v64, s[0:1]
	s_add_u32 s0, s10, 0x11620080
	s_addc_u32 s1, s11, 0
	s_add_i32 s26, s22, 0xc000
	s_mov_b32 m0, s26
	s_add_i32 s27, s22, 0xe000
	global_load_lds_dwordx4 v62, s[0:1]
	s_mov_b32 m0, s27
	s_add_u32 s8, s10, 0x11e00000
	global_load_lds_dwordx4 v64, s[0:1]
	s_addc_u32 s9, s11, 0
	s_add_i32 s19, s22, 0x10000
	s_mov_b64 s[0:1], 0x100
	v_lshl_add_u64 v[56:57], v[66:67], 0, s[0:1]
	s_mov_b32 m0, s19
	s_add_i32 s13, s22, 0x12000
	global_load_dwordx4 v[44:47], v[2:3], off offset:256
	global_load_dwordx4 v[40:43], v[2:3], off offset:320
	global_load_dwordx4 v[36:39], v[2:3], off offset:384
	global_load_dwordx4 v[32:35], v[2:3], off offset:448
	global_load_dwordx4 v[28:31], v[2:3], off offset:512
	global_load_dwordx4 v[24:27], v[2:3], off offset:576
	global_load_dwordx4 v[20:23], v[2:3], off offset:640
	global_load_dwordx4 v[16:19], v[2:3], off offset:704
	global_load_dwordx4 v[12:15], v[2:3], off offset:768
	global_load_dwordx4 v[8:11], v[2:3], off offset:832
	global_load_dwordx4 v[4:7], v[2:3], off offset:896
	s_nop 0
	global_load_dwordx4 v[0:3], v[2:3], off offset:960
	s_waitcnt vmcnt(12)
	s_waitcnt vmcnt(12) lgkmcnt(0)
	s_barrier
	global_load_lds_dwordx4 v[56:57], off
	v_lshl_add_u64 v[56:57], v[68:69], 0, s[0:1]
	s_mov_b32 m0, s13
	s_add_i32 s12, s22, 0x14000
	s_add_i32 s14, s22, 0x16000
	global_load_lds_dwordx4 v[56:57], off
	v_lshl_add_u64 v[56:57], v[66:67], 0, s[4:5]
	s_mov_b32 m0, s12
	s_add_u32 s28, s10, 0x11620100
	global_load_lds_dwordx4 v[56:57], off
	v_lshl_add_u64 v[56:57], v[68:69], 0, s[4:5]
	s_mov_b32 m0, s14
	s_addc_u32 s29, s11, 0
	s_add_i32 s15, s22, 0x18000
	global_load_lds_dwordx4 v[56:57], off
	s_mov_b32 m0, s15
	s_add_i32 s16, s22, 0x1a000
	global_load_lds_dwordx4 v62, s[28:29]
	s_mov_b32 m0, s16
	v_and_b32_e32 v57, 48, v58
	global_load_lds_dwordx4 v64, s[28:29]
	s_add_u32 s28, s10, 0x11620180
	s_addc_u32 s29, s11, 0
	s_add_i32 s17, s22, 0x1c000
	s_mov_b32 m0, s17
	s_add_i32 s18, s22, 0x1e000
	global_load_lds_dwordx4 v62, s[28:29]
	s_mov_b32 m0, s18
	v_lshlrev_b32_e32 v58, 2, v58
	global_load_lds_dwordx4 v64, s[28:29]
	v_lshlrev_b32_e32 v56, 6, v59
	v_and_b32_e32 v58, 32, v58
	v_bitop3_b32 v56, v56, v58, v57 bitop3:0x36
	v_and_b32_e32 v57, 0xfffffc00, v71
	v_add3_u32 v65, 0, v56, v57
	v_mov_b32_e32 v71, v65
	ds_read_b128 v[56:59], v71
	ds_read_b128 v[80:83], v71 offset:2048
	s_waitcnt lgkmcnt(0)
	v_mfma_f32_16x16x32_bf16 v[84:87], v[56:59], v[76:79], 0
	ds_read_b128 v[56:59], v71 offset:4096
	ds_read_b128 v[88:91], v71 offset:6144
	ds_read_b128 v[96:99], v71 offset:8192
	ds_read_b128 v[100:103], v71 offset:10240
	s_waitcnt lgkmcnt(0)
	v_mfma_f32_16x16x32_bf16 v[92:95], v[56:59], v[76:79], 0
	v_lshlrev_b32_e32 v56, 9, v104
	ds_read_b128 v[104:107], v71 offset:12288
	v_lshlrev_b32_e32 v57, 9, v108
	ds_read_b128 v[108:111], v71 offset:14336
	ds_read_b128 v[112:115], v71 offset:32768
	ds_read_b128 v[116:119], v71 offset:34816
	ds_read_b128 v[120:123], v71 offset:36864
	ds_read_b128 v[124:127], v71 offset:38912
	ds_read_b128 v[128:131], v71 offset:40960
	ds_read_b128 v[132:135], v71 offset:43008
	ds_read_b128 v[136:139], v71 offset:45056
	ds_read_b128 v[140:143], v71 offset:47104
	v_mfma_f32_16x16x32_bf16 v[80:83], v[80:83], v[76:79], 0
	v_sub_u32_e32 v56, v62, v56
	v_mov_b32_e32 v241, v56
	v_sub_u32_e32 v58, v64, v57
	v_mfma_f32_16x16x32_bf16 v[88:91], v[88:91], v[76:79], 0
	v_mfma_f32_16x16x32_bf16 v[96:99], v[96:99], v[76:79], 0
	v_mfma_f32_16x16x32_bf16 v[100:103], v[100:103], v[76:79], 0
	s_waitcnt lgkmcnt(0)
	v_mfma_f32_16x16x32_bf16 v[104:107], v[104:107], v[76:79], 0
	v_mfma_f32_16x16x32_bf16 v[108:111], v[108:111], v[76:79], 0
	ds_read_b128 v[144:147], v71 offset:15360
	ds_read_b128 v[148:151], v71 offset:13312
	ds_read_b128 v[152:155], v71 offset:11264
	ds_read_b128 v[156:159], v71 offset:9216
	ds_read_b128 v[160:163], v71 offset:7168
	ds_read_b128 v[164:167], v71 offset:5120
	ds_read_b128 v[168:171], v71 offset:3072
	ds_read_b128 v[172:175], v71 offset:1024
	v_mfma_f32_16x16x32_bf16 v[112:115], v[112:115], v[76:79], 0
	v_mfma_f32_16x16x32_bf16 v[116:119], v[116:119], v[76:79], 0
	v_mfma_f32_16x16x32_bf16 v[120:123], v[120:123], v[76:79], 0
	v_mfma_f32_16x16x32_bf16 v[124:127], v[124:127], v[76:79], 0
	v_mfma_f32_16x16x32_bf16 v[128:131], v[128:131], v[76:79], 0
	v_mfma_f32_16x16x32_bf16 v[132:135], v[132:135], v[76:79], 0
	v_mfma_f32_16x16x32_bf16 v[136:139], v[136:139], v[76:79], 0
	v_mfma_f32_16x16x32_bf16 v[76:79], v[140:143], v[76:79], 0
	s_waitcnt lgkmcnt(0)
	v_mfma_f32_16x16x32_bf16 v[84:87], v[172:175], v[72:75], v[84:87]
	v_mfma_f32_16x16x32_bf16 v[80:83], v[168:171], v[72:75], v[80:83]
	v_mfma_f32_16x16x32_bf16 v[92:95], v[164:167], v[72:75], v[92:95]
	v_mfma_f32_16x16x32_bf16 v[88:91], v[160:163], v[72:75], v[88:91]
	v_mfma_f32_16x16x32_bf16 v[96:99], v[156:159], v[72:75], v[96:99]
	v_mfma_f32_16x16x32_bf16 v[100:103], v[152:155], v[72:75], v[100:103]
	ds_read_b128 v[140:143], v71 offset:33792
	ds_read_b128 v[152:155], v71 offset:35840
	ds_read_b128 v[156:159], v71 offset:37888
	ds_read_b128 v[160:163], v71 offset:39936
	v_mfma_f32_16x16x32_bf16 v[104:107], v[148:151], v[72:75], v[104:107]
	ds_read_b128 v[148:151], v71 offset:41984
	ds_read_b128 v[164:167], v71 offset:44032
	ds_read_b128 v[168:171], v71 offset:46080
	ds_read_b128 v[172:175], v71 offset:48128
	v_mfma_f32_16x16x32_bf16 v[108:111], v[144:147], v[72:75], v[108:111]
	s_waitcnt lgkmcnt(0)
	v_mfma_f32_16x16x32_bf16 v[112:115], v[140:143], v[72:75], v[112:115]
	v_mfma_f32_16x16x32_bf16 v[116:119], v[152:155], v[72:75], v[116:119]
	v_mfma_f32_16x16x32_bf16 v[120:123], v[156:159], v[72:75], v[120:123]
	v_mfma_f32_16x16x32_bf16 v[124:127], v[160:163], v[72:75], v[124:127]
	v_mfma_f32_16x16x32_bf16 v[128:131], v[148:151], v[72:75], v[128:131]
	ds_read_b128 v[140:143], v71 offset:30720
	ds_read_b128 v[144:147], v71 offset:28672
	ds_read_b128 v[148:151], v71 offset:26624
	ds_read_b128 v[152:155], v71 offset:24576
	v_mfma_f32_16x16x32_bf16 v[132:135], v[164:167], v[72:75], v[132:135]
	v_mfma_f32_16x16x32_bf16 v[136:139], v[168:171], v[72:75], v[136:139]
	ds_read_b128 v[156:159], v71 offset:22528
	ds_read_b128 v[160:163], v71 offset:20480
	ds_read_b128 v[164:167], v71 offset:18432
	ds_read_b128 v[168:171], v71 offset:16384
	v_mfma_f32_16x16x32_bf16 v[72:75], v[172:175], v[72:75], v[76:79]
	s_waitcnt lgkmcnt(0)
	v_mfma_f32_16x16x32_bf16 v[76:79], v[168:171], v[52:55], v[84:87]
	v_mfma_f32_16x16x32_bf16 v[80:83], v[164:167], v[52:55], v[80:83]
	v_mfma_f32_16x16x32_bf16 v[84:87], v[160:163], v[52:55], v[92:95]
	v_mfma_f32_16x16x32_bf16 v[88:91], v[156:159], v[52:55], v[88:91]
	v_mfma_f32_16x16x32_bf16 v[92:95], v[152:155], v[52:55], v[96:99]
	v_mfma_f32_16x16x32_bf16 v[96:99], v[148:151], v[52:55], v[100:103]
	s_nop 2
	ds_read_b128 v[100:103], v71 offset:49152
	ds_read_b128 v[148:151], v71 offset:51200
	ds_read_b128 v[152:155], v71 offset:53248
	ds_read_b128 v[156:159], v71 offset:55296
	v_mfma_f32_16x16x32_bf16 v[104:107], v[144:147], v[52:55], v[104:107]
	ds_read_b128 v[144:147], v71 offset:57344
	ds_read_b128 v[160:163], v71 offset:59392
	ds_read_b128 v[164:167], v71 offset:61440
	ds_read_b128 v[168:171], v71 offset:63488
	v_mfma_f32_16x16x32_bf16 v[108:111], v[140:143], v[52:55], v[108:111]
	s_waitcnt lgkmcnt(0)
	v_mfma_f32_16x16x32_bf16 v[100:103], v[100:103], v[52:55], v[112:115]
	v_mfma_f32_16x16x32_bf16 v[112:115], v[148:151], v[52:55], v[116:119]
	v_mfma_f32_16x16x32_bf16 v[116:119], v[152:155], v[52:55], v[120:123]
	v_mfma_f32_16x16x32_bf16 v[120:123], v[156:159], v[52:55], v[124:127]
	v_mfma_f32_16x16x32_bf16 v[124:127], v[144:147], v[52:55], v[128:131]
	v_mfma_f32_16x16x32_bf16 v[128:131], v[160:163], v[52:55], v[132:135]
	s_nop 2
	ds_read_b128 v[132:135], v71 offset:31744
	ds_read_b128 v[140:143], v71 offset:29696
	ds_read_b128 v[144:147], v71 offset:27648
	ds_read_b128 v[148:151], v71 offset:25600
	v_mfma_f32_16x16x32_bf16 v[136:139], v[164:167], v[52:55], v[136:139]
	ds_read_b128 v[152:155], v71 offset:23552
	ds_read_b128 v[156:159], v71 offset:21504
	ds_read_b128 v[160:163], v71 offset:19456
	ds_read_b128 v[164:167], v71 offset:17408
	v_mfma_f32_16x16x32_bf16 v[52:55], v[168:171], v[52:55], v[72:75]
	s_waitcnt lgkmcnt(0)
	v_mfma_f32_16x16x32_bf16 v[72:75], v[164:167], v[48:51], v[76:79]
	v_mfma_f32_16x16x32_bf16 v[76:79], v[160:163], v[48:51], v[80:83]
	v_mfma_f32_16x16x32_bf16 v[80:83], v[156:159], v[48:51], v[84:87]
	v_mfma_f32_16x16x32_bf16 v[84:87], v[152:155], v[48:51], v[88:91]
	v_mfma_f32_16x16x32_bf16 v[88:91], v[148:151], v[48:51], v[92:95]
	v_mfma_f32_16x16x32_bf16 v[92:95], v[144:147], v[48:51], v[96:99]
	s_nop 2
	ds_read_b128 v[96:99], v71 offset:50176
	ds_read_b128 v[144:147], v71 offset:52224
	ds_read_b128 v[148:151], v71 offset:54272
	ds_read_b128 v[152:155], v71 offset:56320
	v_mfma_f32_16x16x32_bf16 v[104:107], v[140:143], v[48:51], v[104:107]
	ds_read_b128 v[140:143], v71 offset:58368
	ds_read_b128 v[156:159], v71 offset:60416
	ds_read_b128 v[160:163], v71 offset:62464
	ds_read_b128 v[164:167], v71 offset:64512
	v_mfma_f32_16x16x32_bf16 v[108:111], v[132:135], v[48:51], v[108:111]
	s_waitcnt lgkmcnt(0)
	v_mfma_f32_16x16x32_bf16 v[96:99], v[96:99], v[48:51], v[100:103]
	v_mfma_f32_16x16x32_bf16 v[100:103], v[144:147], v[48:51], v[112:115]
	v_mfma_f32_16x16x32_bf16 v[112:115], v[148:151], v[48:51], v[116:119]
	v_mfma_f32_16x16x32_bf16 v[116:119], v[152:155], v[48:51], v[120:123]
	v_mfma_f32_16x16x32_bf16 v[120:123], v[140:143], v[48:51], v[124:127]
	v_mfma_f32_16x16x32_bf16 v[124:127], v[156:159], v[48:51], v[128:131]
	v_mfma_f32_16x16x32_bf16 v[128:131], v[160:163], v[48:51], v[136:139]
	v_mfma_f32_16x16x32_bf16 v[50:53], v[164:167], v[48:51], v[52:55]
	s_waitcnt vmcnt(0)
	s_waitcnt vmcnt(0)
	s_barrier
	v_add_u32_e32 v48, 0x10000, v65
	v_mov_b32_e32 v49, v48
	ds_read_b128 v[132:135], v49
	ds_read_b128 v[136:139], v49 offset:2048
	s_waitcnt lgkmcnt(0)
	v_mfma_f32_16x16x32_bf16 v[72:75], v[132:135], v[44:47], v[72:75]
	ds_read_b128 v[132:135], v49 offset:4096
	v_mfma_f32_16x16x32_bf16 v[76:79], v[136:139], v[44:47], v[76:79]
	ds_read_b128 v[136:139], v49 offset:6144
	s_waitcnt lgkmcnt(0)
	v_mfma_f32_16x16x32_bf16 v[80:83], v[132:135], v[44:47], v[80:83]
	ds_read_b128 v[132:135], v49 offset:8192
	v_mfma_f32_16x16x32_bf16 v[84:87], v[136:139], v[44:47], v[84:87]
	ds_read_b128 v[136:139], v49 offset:10240
	s_waitcnt lgkmcnt(0)
	v_mfma_f32_16x16x32_bf16 v[88:91], v[132:135], v[44:47], v[88:91]
	ds_read_b128 v[132:135], v49 offset:12288
	ds_read_b128 v[140:143], v49 offset:14336
	v_mfma_f32_16x16x32_bf16 v[92:95], v[136:139], v[44:47], v[92:95]
	ds_read_b128 v[136:139], v49 offset:32768
	ds_read_b128 v[144:147], v49 offset:34816
	ds_read_b128 v[148:151], v49 offset:36864
	ds_read_b128 v[152:155], v49 offset:38912
	s_waitcnt lgkmcnt(0)
	v_mfma_f32_16x16x32_bf16 v[104:107], v[132:135], v[44:47], v[104:107]
	ds_read_b128 v[132:135], v49 offset:40960
	ds_read_b128 v[156:159], v49 offset:43008
	ds_read_b128 v[160:163], v49 offset:45056
	ds_read_b128 v[164:167], v49 offset:47104
	v_mfma_f32_16x16x32_bf16 v[108:111], v[140:143], v[44:47], v[108:111]
	s_add_u32 s100, s10, 0x11600200
	s_addc_u32 s101, s11, 0
	s_mov_b32 m0, s22
	s_nop 0
	global_load_lds_dwordx4 v240, s[100:101]
	v_mfma_f32_16x16x32_bf16 v[96:99], v[136:139], v[44:47], v[96:99]
	v_mfma_f32_16x16x32_bf16 v[100:103], v[144:147], v[44:47], v[100:103]
	v_mfma_f32_16x16x32_bf16 v[112:115], v[148:151], v[44:47], v[112:115]
	v_mfma_f32_16x16x32_bf16 v[116:119], v[152:155], v[44:47], v[116:119]
	s_waitcnt lgkmcnt(0)
	v_mfma_f32_16x16x32_bf16 v[120:123], v[132:135], v[44:47], v[120:123]
	ds_read_b128 v[132:135], v49 offset:15360
	ds_read_b128 v[136:139], v49 offset:13312
	ds_read_b128 v[140:143], v49 offset:11264
	ds_read_b128 v[144:147], v49 offset:9216
	v_mfma_f32_16x16x32_bf16 v[124:127], v[156:159], v[44:47], v[124:127]
	v_mfma_f32_16x16x32_bf16 v[128:131], v[160:163], v[44:47], v[128:131]
	ds_read_b128 v[148:151], v49 offset:7168
	ds_read_b128 v[152:155], v49 offset:5120
	ds_read_b128 v[156:159], v49 offset:3072
	ds_read_b128 v[160:163], v49 offset:1024
	v_mfma_f32_16x16x32_bf16 v[44:47], v[164:167], v[44:47], v[50:53]
	s_add_u32 s100, s10, 0x11610200
	s_addc_u32 s101, s11, 0
	s_mov_b32 m0, s21
	s_nop 0
	global_load_lds_dwordx4 v240, s[100:101]
	s_waitcnt lgkmcnt(0)
	v_mfma_f32_16x16x32_bf16 v[50:53], v[160:163], v[40:43], v[72:75]
	v_mfma_f32_16x16x32_bf16 v[72:75], v[156:159], v[40:43], v[76:79]
	v_mfma_f32_16x16x32_bf16 v[76:79], v[152:155], v[40:43], v[80:83]
	v_mfma_f32_16x16x32_bf16 v[80:83], v[148:151], v[40:43], v[84:87]
	v_mfma_f32_16x16x32_bf16 v[84:87], v[144:147], v[40:43], v[88:91]
	v_mfma_f32_16x16x32_bf16 v[88:91], v[140:143], v[40:43], v[92:95]
	s_nop 2
	ds_read_b128 v[92:95], v49 offset:33792
	ds_read_b128 v[140:143], v49 offset:35840
	ds_read_b128 v[144:147], v49 offset:37888
	ds_read_b128 v[148:151], v49 offset:39936
	v_mfma_f32_16x16x32_bf16 v[104:107], v[136:139], v[40:43], v[104:107]
	ds_read_b128 v[136:139], v49 offset:41984
	ds_read_b128 v[152:155], v49 offset:44032
	ds_read_b128 v[156:159], v49 offset:46080
	ds_read_b128 v[160:163], v49 offset:48128
	v_mfma_f32_16x16x32_bf16 v[108:111], v[132:135], v[40:43], v[108:111]
	s_add_u32 s100, s10, 0x11600280
	s_addc_u32 s101, s11, 0
	s_mov_b32 m0, s20
	s_nop 0
	global_load_lds_dwordx4 v240, s[100:101]
	s_waitcnt lgkmcnt(0)
	v_mfma_f32_16x16x32_bf16 v[92:95], v[92:95], v[40:43], v[96:99]
	v_mfma_f32_16x16x32_bf16 v[96:99], v[140:143], v[40:43], v[100:103]
	v_mfma_f32_16x16x32_bf16 v[100:103], v[144:147], v[40:43], v[112:115]
	v_mfma_f32_16x16x32_bf16 v[112:115], v[148:151], v[40:43], v[116:119]
	v_mfma_f32_16x16x32_bf16 v[116:119], v[136:139], v[40:43], v[120:123]
	v_mfma_f32_16x16x32_bf16 v[120:123], v[152:155], v[40:43], v[124:127]
	s_nop 2
	ds_read_b128 v[124:127], v49 offset:30720
	ds_read_b128 v[132:135], v49 offset:28672
	ds_read_b128 v[136:139], v49 offset:26624
	ds_read_b128 v[140:143], v49 offset:24576
	v_mfma_f32_16x16x32_bf16 v[128:131], v[156:159], v[40:43], v[128:131]
	ds_read_b128 v[144:147], v49 offset:22528
	ds_read_b128 v[148:151], v49 offset:20480
	ds_read_b128 v[152:155], v49 offset:18432
	ds_read_b128 v[156:159], v49 offset:16384
	v_mfma_f32_16x16x32_bf16 v[40:43], v[160:163], v[40:43], v[44:47]
	s_add_u32 s100, s10, 0x11610280
	s_addc_u32 s101, s11, 0
	s_mov_b32 m0, s23
	s_nop 0
	global_load_lds_dwordx4 v240, s[100:101]
	s_waitcnt lgkmcnt(0)
	v_mfma_f32_16x16x32_bf16 v[44:47], v[156:159], v[36:39], v[50:53]
	v_mfma_f32_16x16x32_bf16 v[50:53], v[152:155], v[36:39], v[72:75]
	v_mfma_f32_16x16x32_bf16 v[72:75], v[148:151], v[36:39], v[76:79]
	v_mfma_f32_16x16x32_bf16 v[76:79], v[144:147], v[36:39], v[80:83]
	v_mfma_f32_16x16x32_bf16 v[80:83], v[140:143], v[36:39], v[84:87]
	v_mfma_f32_16x16x32_bf16 v[84:87], v[136:139], v[36:39], v[88:91]
	s_nop 2
	ds_read_b128 v[88:91], v49 offset:49152
	ds_read_b128 v[136:139], v49 offset:51200
	ds_read_b128 v[140:143], v49 offset:53248
	ds_read_b128 v[144:147], v49 offset:55296
	v_mfma_f32_16x16x32_bf16 v[104:107], v[132:135], v[36:39], v[104:107]
	ds_read_b128 v[132:135], v49 offset:57344
	ds_read_b128 v[148:151], v49 offset:59392
	ds_read_b128 v[152:155], v49 offset:61440
	ds_read_b128 v[156:159], v49 offset:63488
	v_mfma_f32_16x16x32_bf16 v[108:111], v[124:127], v[36:39], v[108:111]
	s_add_u32 s100, s10, 0x11620200
	s_addc_u32 s101, s11, 0
	s_mov_b32 m0, s24
	s_nop 0
	global_load_lds_dwordx4 v240, s[100:101]
	s_waitcnt lgkmcnt(0)
	v_mfma_f32_16x16x32_bf16 v[88:91], v[88:91], v[36:39], v[92:95]
	v_mfma_f32_16x16x32_bf16 v[92:95], v[136:139], v[36:39], v[96:99]
	v_mfma_f32_16x16x32_bf16 v[96:99], v[140:143], v[36:39], v[100:103]
	v_mfma_f32_16x16x32_bf16 v[100:103], v[144:147], v[36:39], v[112:115]
	v_mfma_f32_16x16x32_bf16 v[112:115], v[132:135], v[36:39], v[116:119]
	v_mfma_f32_16x16x32_bf16 v[116:119], v[148:151], v[36:39], v[120:123]
	s_nop 2
	ds_read_b128 v[120:123], v49 offset:31744
	ds_read_b128 v[124:127], v49 offset:29696
	ds_read_b128 v[132:135], v49 offset:27648
	ds_read_b128 v[136:139], v49 offset:25600
	v_mfma_f32_16x16x32_bf16 v[128:131], v[152:155], v[36:39], v[128:131]
	ds_read_b128 v[140:143], v49 offset:23552
	ds_read_b128 v[144:147], v49 offset:21504
	ds_read_b128 v[148:151], v49 offset:19456
	ds_read_b128 v[152:155], v49 offset:17408
	v_mfma_f32_16x16x32_bf16 v[36:39], v[156:159], v[36:39], v[40:43]
	s_add_u32 s100, s10, 0x11630200
	s_addc_u32 s101, s11, 0
	s_mov_b32 m0, s25
	s_nop 0
	global_load_lds_dwordx4 v240, s[100:101]
	s_waitcnt lgkmcnt(0)
	v_mfma_f32_16x16x32_bf16 v[40:43], v[152:155], v[32:35], v[44:47]
	v_mfma_f32_16x16x32_bf16 v[44:47], v[148:151], v[32:35], v[50:53]
	v_mfma_f32_16x16x32_bf16 v[50:53], v[144:147], v[32:35], v[72:75]
	v_mfma_f32_16x16x32_bf16 v[72:75], v[140:143], v[32:35], v[76:79]
	v_mfma_f32_16x16x32_bf16 v[76:79], v[136:139], v[32:35], v[80:83]
	v_mfma_f32_16x16x32_bf16 v[80:83], v[132:135], v[32:35], v[84:87]
	s_nop 2
	ds_read_b128 v[84:87], v49 offset:50176
	ds_read_b128 v[132:135], v49 offset:52224
	ds_read_b128 v[136:139], v49 offset:54272
	ds_read_b128 v[140:143], v49 offset:56320
	v_mfma_f32_16x16x32_bf16 v[104:107], v[124:127], v[32:35], v[104:107]
	ds_read_b128 v[124:127], v49 offset:58368
	ds_read_b128 v[144:147], v49 offset:60416
	ds_read_b128 v[148:151], v49 offset:62464
	ds_read_b128 v[152:155], v49 offset:64512
	v_mfma_f32_16x16x32_bf16 v[108:111], v[120:123], v[32:35], v[108:111]
	s_add_u32 s100, s10, 0x11620280
	s_addc_u32 s101, s11, 0
	s_mov_b32 m0, s26
	s_nop 0
	global_load_lds_dwordx4 v240, s[100:101]
	s_waitcnt lgkmcnt(0)
	v_mfma_f32_16x16x32_bf16 v[84:87], v[84:87], v[32:35], v[88:91]
	v_mfma_f32_16x16x32_bf16 v[88:91], v[132:135], v[32:35], v[92:95]
	v_mfma_f32_16x16x32_bf16 v[92:95], v[136:139], v[32:35], v[96:99]
	v_mfma_f32_16x16x32_bf16 v[96:99], v[140:143], v[32:35], v[100:103]
	v_mfma_f32_16x16x32_bf16 v[100:103], v[124:127], v[32:35], v[112:115]
	v_mfma_f32_16x16x32_bf16 v[112:115], v[144:147], v[32:35], v[116:119]
	v_mfma_f32_16x16x32_bf16 v[116:119], v[148:151], v[32:35], v[128:131]
	v_mfma_f32_16x16x32_bf16 v[32:35], v[152:155], v[32:35], v[36:39]
	s_add_u32 s100, s10, 0x11630280
	s_addc_u32 s101, s11, 0
	s_mov_b32 m0, s27
	s_nop 0
	global_load_lds_dwordx4 v240, s[100:101]
	s_nop 0
	s_waitcnt vmcnt(0)
	s_waitcnt vmcnt(0)
	s_barrier
	v_mov_b32_e32 v49, v65
	ds_read_b128 v[36:39], v49
	ds_read_b128 v[66:69], v49 offset:2048
	s_waitcnt lgkmcnt(0)
	v_mfma_f32_16x16x32_bf16 v[36:39], v[36:39], v[28:31], v[40:43]
	s_nop 2
	ds_read_b128 v[40:43], v49 offset:4096
	v_mfma_f32_16x16x32_bf16 v[44:47], v[66:69], v[28:31], v[44:47]
	ds_read_b128 v[66:69], v49 offset:6144
	s_waitcnt lgkmcnt(0)
	v_mfma_f32_16x16x32_bf16 v[40:43], v[40:43], v[28:31], v[50:53]
	s_nop 2
	ds_read_b128 v[50:53], v49 offset:8192
	v_mfma_f32_16x16x32_bf16 v[66:69], v[66:69], v[28:31], v[72:75]
	s_nop 2
	ds_read_b128 v[72:75], v49 offset:10240
	s_waitcnt lgkmcnt(0)
	v_mfma_f32_16x16x32_bf16 v[50:53], v[50:53], v[28:31], v[76:79]
	s_nop 2
	ds_read_b128 v[76:79], v49 offset:12288
	ds_read_b128 v[120:123], v49 offset:14336
	v_mfma_f32_16x16x32_bf16 v[72:75], v[72:75], v[28:31], v[80:83]
	s_nop 2
	ds_read_b128 v[80:83], v49 offset:32768
	ds_read_b128 v[124:127], v49 offset:34816
	ds_read_b128 v[128:131], v49 offset:36864
	ds_read_b128 v[132:135], v49 offset:38912
	s_waitcnt lgkmcnt(0)
	v_mfma_f32_16x16x32_bf16 v[76:79], v[76:79], v[28:31], v[104:107]
	s_nop 2
	ds_read_b128 v[104:107], v49 offset:40960
	ds_read_b128 v[136:139], v49 offset:43008
	ds_read_b128 v[140:143], v49 offset:45056
	ds_read_b128 v[144:147], v49 offset:47104
	v_mfma_f32_16x16x32_bf16 v[108:111], v[120:123], v[28:31], v[108:111]
	s_add_u32 s100, s10, 0x11600300
	s_addc_u32 s101, s11, 0
	s_mov_b32 m0, s19
	s_nop 0
	global_load_lds_dwordx4 v240, s[100:101]
	v_mfma_f32_16x16x32_bf16 v[80:83], v[80:83], v[28:31], v[84:87]
	v_mfma_f32_16x16x32_bf16 v[84:87], v[124:127], v[28:31], v[88:91]
	v_mfma_f32_16x16x32_bf16 v[88:91], v[128:131], v[28:31], v[92:95]
	v_mfma_f32_16x16x32_bf16 v[92:95], v[132:135], v[28:31], v[96:99]
	s_waitcnt lgkmcnt(0)
	v_mfma_f32_16x16x32_bf16 v[96:99], v[104:107], v[28:31], v[100:103]
	v_mfma_f32_16x16x32_bf16 v[100:103], v[136:139], v[28:31], v[112:115]
	ds_read_b128 v[104:107], v49 offset:15360
	s_nop 1
	ds_read_b128 v[112:115], v49 offset:13312
	ds_read_b128 v[120:123], v49 offset:11264
	ds_read_b128 v[124:127], v49 offset:9216
	v_mfma_f32_16x16x32_bf16 v[116:119], v[140:143], v[28:31], v[116:119]
	ds_read_b128 v[128:131], v49 offset:7168
	ds_read_b128 v[132:135], v49 offset:5120
	ds_read_b128 v[136:139], v49 offset:3072
	ds_read_b128 v[140:143], v49 offset:1024
	v_mfma_f32_16x16x32_bf16 v[28:31], v[144:147], v[28:31], v[32:35]
	s_add_u32 s100, s10, 0x11610300
	s_addc_u32 s101, s11, 0
	s_mov_b32 m0, s13
	s_nop 0
	global_load_lds_dwordx4 v240, s[100:101]
	s_waitcnt lgkmcnt(0)
	v_mfma_f32_16x16x32_bf16 v[32:35], v[140:143], v[24:27], v[36:39]
	v_mfma_f32_16x16x32_bf16 v[36:39], v[136:139], v[24:27], v[44:47]
	v_mfma_f32_16x16x32_bf16 v[40:43], v[132:135], v[24:27], v[40:43]
	v_mfma_f32_16x16x32_bf16 v[44:47], v[128:131], v[24:27], v[66:69]
	v_mfma_f32_16x16x32_bf16 v[50:53], v[124:127], v[24:27], v[50:53]
	v_mfma_f32_16x16x32_bf16 v[66:69], v[120:123], v[24:27], v[72:75]
	s_nop 2
	ds_read_b128 v[72:75], v49 offset:33792
	ds_read_b128 v[120:123], v49 offset:35840
	ds_read_b128 v[124:127], v49 offset:37888
	ds_read_b128 v[128:131], v49 offset:39936
	v_mfma_f32_16x16x32_bf16 v[76:79], v[112:115], v[24:27], v[76:79]
	ds_read_b128 v[112:115], v49 offset:41984
	ds_read_b128 v[132:135], v49 offset:44032
	ds_read_b128 v[136:139], v49 offset:46080
	ds_read_b128 v[140:143], v49 offset:48128
	v_mfma_f32_16x16x32_bf16 v[104:107], v[104:107], v[24:27], v[108:111]
	s_add_u32 s100, s10, 0x11600380
	s_addc_u32 s101, s11, 0
	s_mov_b32 m0, s12
	s_nop 0
	global_load_lds_dwordx4 v240, s[100:101]
	s_waitcnt lgkmcnt(0)
	v_mfma_f32_16x16x32_bf16 v[72:75], v[72:75], v[24:27], v[80:83]
	v_mfma_f32_16x16x32_bf16 v[80:83], v[120:123], v[24:27], v[84:87]
	v_mfma_f32_16x16x32_bf16 v[84:87], v[124:127], v[24:27], v[88:91]
	v_mfma_f32_16x16x32_bf16 v[88:91], v[128:131], v[24:27], v[92:95]
	v_mfma_f32_16x16x32_bf16 v[92:95], v[112:115], v[24:27], v[96:99]
	v_mfma_f32_16x16x32_bf16 v[96:99], v[132:135], v[24:27], v[100:103]
	s_nop 2
	ds_read_b128 v[100:103], v49 offset:30720
	ds_read_b128 v[108:111], v49 offset:28672
	ds_read_b128 v[112:115], v49 offset:26624
	ds_read_b128 v[120:123], v49 offset:24576
	v_mfma_f32_16x16x32_bf16 v[116:119], v[136:139], v[24:27], v[116:119]
	ds_read_b128 v[124:127], v49 offset:22528
	ds_read_b128 v[128:131], v49 offset:20480
	ds_read_b128 v[132:135], v49 offset:18432
	ds_read_b128 v[136:139], v49 offset:16384
	v_mfma_f32_16x16x32_bf16 v[24:27], v[140:143], v[24:27], v[28:31]
	s_add_u32 s100, s10, 0x11610380
	s_addc_u32 s101, s11, 0
	s_mov_b32 m0, s14
	s_nop 0
	global_load_lds_dwordx4 v240, s[100:101]
	s_waitcnt lgkmcnt(0)
	v_mfma_f32_16x16x32_bf16 v[28:31], v[136:139], v[20:23], v[32:35]
	v_mfma_f32_16x16x32_bf16 v[32:35], v[132:135], v[20:23], v[36:39]
	v_mfma_f32_16x16x32_bf16 v[36:39], v[128:131], v[20:23], v[40:43]
	v_mfma_f32_16x16x32_bf16 v[40:43], v[124:127], v[20:23], v[44:47]
	v_mfma_f32_16x16x32_bf16 v[44:47], v[120:123], v[20:23], v[50:53]
	v_mfma_f32_16x16x32_bf16 v[50:53], v[112:115], v[20:23], v[66:69]
	s_nop 2
	ds_read_b128 v[66:69], v49 offset:49152
	ds_read_b128 v[112:115], v49 offset:51200
	ds_read_b128 v[120:123], v49 offset:53248
	ds_read_b128 v[124:127], v49 offset:55296
	v_mfma_f32_16x16x32_bf16 v[76:79], v[108:111], v[20:23], v[76:79]
	ds_read_b128 v[108:111], v49 offset:57344
	ds_read_b128 v[128:131], v49 offset:59392
	ds_read_b128 v[132:135], v49 offset:61440
	ds_read_b128 v[136:139], v49 offset:63488
	v_mfma_f32_16x16x32_bf16 v[100:103], v[100:103], v[20:23], v[104:107]
	s_add_u32 s100, s10, 0x11620300
	s_addc_u32 s101, s11, 0
	s_mov_b32 m0, s15
	s_nop 0
	global_load_lds_dwordx4 v240, s[100:101]
	s_waitcnt lgkmcnt(0)
	v_mfma_f32_16x16x32_bf16 v[66:69], v[66:69], v[20:23], v[72:75]
	v_mfma_f32_16x16x32_bf16 v[72:75], v[112:115], v[20:23], v[80:83]
	v_mfma_f32_16x16x32_bf16 v[80:83], v[120:123], v[20:23], v[84:87]
	v_mfma_f32_16x16x32_bf16 v[84:87], v[124:127], v[20:23], v[88:91]
	v_mfma_f32_16x16x32_bf16 v[88:91], v[108:111], v[20:23], v[92:95]
	v_mfma_f32_16x16x32_bf16 v[92:95], v[128:131], v[20:23], v[96:99]
	s_nop 2
	ds_read_b128 v[96:99], v49 offset:31744
	ds_read_b128 v[104:107], v49 offset:29696
	ds_read_b128 v[108:111], v49 offset:27648
	ds_read_b128 v[112:115], v49 offset:25600
	v_mfma_f32_16x16x32_bf16 v[116:119], v[132:135], v[20:23], v[116:119]
	ds_read_b128 v[120:123], v49 offset:23552
	ds_read_b128 v[124:127], v49 offset:21504
	ds_read_b128 v[128:131], v49 offset:19456
	ds_read_b128 v[132:135], v49 offset:17408
	v_mfma_f32_16x16x32_bf16 v[20:23], v[136:139], v[20:23], v[24:27]
	s_add_u32 s100, s10, 0x11630300
	s_addc_u32 s101, s11, 0
	s_mov_b32 m0, s16
	s_nop 0
	global_load_lds_dwordx4 v240, s[100:101]
	s_waitcnt lgkmcnt(0)
	v_mfma_f32_16x16x32_bf16 v[24:27], v[132:135], v[16:19], v[28:31]
	v_mfma_f32_16x16x32_bf16 v[28:31], v[128:131], v[16:19], v[32:35]
	v_mfma_f32_16x16x32_bf16 v[32:35], v[124:127], v[16:19], v[36:39]
	v_mfma_f32_16x16x32_bf16 v[36:39], v[120:123], v[16:19], v[40:43]
	v_mfma_f32_16x16x32_bf16 v[40:43], v[112:115], v[16:19], v[44:47]
	v_mfma_f32_16x16x32_bf16 v[50:53], v[108:111], v[16:19], v[50:53]
	s_nop 1
	ds_read_b128 v[44:47], v49 offset:50176
	ds_read_b128 v[108:111], v49 offset:52224
	ds_read_b128 v[112:115], v49 offset:54272
	ds_read_b128 v[120:123], v49 offset:56320
	v_mfma_f32_16x16x32_bf16 v[76:79], v[104:107], v[16:19], v[76:79]
	ds_read_b128 v[104:107], v49 offset:58368
	ds_read_b128 v[124:127], v49 offset:60416
	ds_read_b128 v[128:131], v49 offset:62464
	ds_read_b128 v[132:135], v49 offset:64512
	v_mfma_f32_16x16x32_bf16 v[96:99], v[96:99], v[16:19], v[100:103]
	s_add_u32 s100, s10, 0x11620380
	s_addc_u32 s101, s11, 0
	s_mov_b32 m0, s17
	s_nop 0
	global_load_lds_dwordx4 v240, s[100:101]
	s_waitcnt lgkmcnt(0)
	v_mfma_f32_16x16x32_bf16 v[66:69], v[44:47], v[16:19], v[66:69]
	v_mfma_f32_16x16x32_bf16 v[72:75], v[108:111], v[16:19], v[72:75]
	v_mfma_f32_16x16x32_bf16 v[80:83], v[112:115], v[16:19], v[80:83]
	v_mfma_f32_16x16x32_bf16 v[84:87], v[120:123], v[16:19], v[84:87]
	v_mfma_f32_16x16x32_bf16 v[88:91], v[104:107], v[16:19], v[88:91]
	v_mfma_f32_16x16x32_bf16 v[92:95], v[124:127], v[16:19], v[92:95]
	v_mfma_f32_16x16x32_bf16 v[100:103], v[128:131], v[16:19], v[116:119]
	v_mfma_f32_16x16x32_bf16 v[16:19], v[132:135], v[16:19], v[20:23]
	s_add_u32 s100, s10, 0x11630380
	s_addc_u32 s101, s11, 0
	s_mov_b32 m0, s18
	s_nop 0
	global_load_lds_dwordx4 v240, s[100:101]
	s_waitcnt vmcnt(0)
	s_waitcnt vmcnt(0)
	s_barrier
	v_mov_b32_e32 v49, v48
	ds_read_b128 v[20:23], v49
	ds_read_b128 v[104:107], v49 offset:2048
	s_waitcnt lgkmcnt(0)
	v_mfma_f32_16x16x32_bf16 v[20:23], v[20:23], v[12:15], v[24:27]
	s_nop 2
	ds_read_b128 v[24:27], v49 offset:4096
	v_mfma_f32_16x16x32_bf16 v[28:31], v[104:107], v[12:15], v[28:31]
	ds_read_b128 v[104:107], v49 offset:6144
	s_waitcnt lgkmcnt(0)
	v_mfma_f32_16x16x32_bf16 v[24:27], v[24:27], v[12:15], v[32:35]
	s_nop 2
	ds_read_b128 v[32:35], v49 offset:8192
	v_mfma_f32_16x16x32_bf16 v[36:39], v[104:107], v[12:15], v[36:39]
	ds_read_b128 v[104:107], v49 offset:10240
	s_waitcnt lgkmcnt(0)
	v_mfma_f32_16x16x32_bf16 v[32:35], v[32:35], v[12:15], v[40:43]
	s_nop 2
	ds_read_b128 v[40:43], v49 offset:12288
	ds_read_b128 v[108:111], v49 offset:14336
	v_mfma_f32_16x16x32_bf16 v[50:53], v[104:107], v[12:15], v[50:53]
	ds_read_b128 v[104:107], v49 offset:32768
	ds_read_b128 v[112:115], v49 offset:34816
	ds_read_b128 v[116:119], v49 offset:36864
	ds_read_b128 v[120:123], v49 offset:38912
	s_waitcnt lgkmcnt(0)
	v_mfma_f32_16x16x32_bf16 v[40:43], v[40:43], v[12:15], v[76:79]
	s_nop 2
	ds_read_b128 v[76:79], v49 offset:40960
	ds_read_b128 v[124:127], v49 offset:43008
	ds_read_b128 v[128:131], v49 offset:45056
	ds_read_b128 v[132:135], v49 offset:47104
	v_mfma_f32_16x16x32_bf16 v[96:99], v[108:111], v[12:15], v[96:99]
	s_add_u32 s100, s10, 0x11e00000
	s_addc_u32 s101, s11, 0
	s_mov_b32 m0, s22
	s_nop 0
	global_load_lds_dwordx4 v241, s[100:101]
	v_mfma_f32_16x16x32_bf16 v[66:69], v[104:107], v[12:15], v[66:69]
	v_mfma_f32_16x16x32_bf16 v[72:75], v[112:115], v[12:15], v[72:75]
	v_mfma_f32_16x16x32_bf16 v[80:83], v[116:119], v[12:15], v[80:83]
	v_mfma_f32_16x16x32_bf16 v[84:87], v[120:123], v[12:15], v[84:87]
	s_waitcnt lgkmcnt(0)
	v_mfma_f32_16x16x32_bf16 v[76:79], v[76:79], v[12:15], v[88:91]
	v_mfma_f32_16x16x32_bf16 v[88:91], v[124:127], v[12:15], v[92:95]
	s_nop 2
	ds_read_b128 v[92:95], v49 offset:15360
	ds_read_b128 v[104:107], v49 offset:13312
	ds_read_b128 v[108:111], v49 offset:11264
	ds_read_b128 v[112:115], v49 offset:9216
	v_mfma_f32_16x16x32_bf16 v[100:103], v[128:131], v[12:15], v[100:103]
	ds_read_b128 v[116:119], v49 offset:7168
	ds_read_b128 v[120:123], v49 offset:5120
	ds_read_b128 v[124:127], v49 offset:3072
	ds_read_b128 v[128:131], v49 offset:1024
	v_mfma_f32_16x16x32_bf16 v[12:15], v[132:135], v[12:15], v[16:19]
	s_add_u32 s100, s10, 0x11e08000
	s_addc_u32 s101, s11, 0
	s_mov_b32 m0, s21
	s_nop 0
	global_load_lds_dwordx4 v241, s[100:101]
	s_waitcnt lgkmcnt(0)
	v_mfma_f32_16x16x32_bf16 v[16:19], v[128:131], v[8:11], v[20:23]
	v_mfma_f32_16x16x32_bf16 v[20:23], v[124:127], v[8:11], v[28:31]
	v_mfma_f32_16x16x32_bf16 v[24:27], v[120:123], v[8:11], v[24:27]
	v_mfma_f32_16x16x32_bf16 v[28:31], v[116:119], v[8:11], v[36:39]
	v_mfma_f32_16x16x32_bf16 v[32:35], v[112:115], v[8:11], v[32:35]
	v_mfma_f32_16x16x32_bf16 v[36:39], v[108:111], v[8:11], v[50:53]
	s_nop 2
	ds_read_b128 v[50:53], v49 offset:33792
	ds_read_b128 v[108:111], v49 offset:35840
	ds_read_b128 v[112:115], v49 offset:37888
	ds_read_b128 v[116:119], v49 offset:39936
	v_mfma_f32_16x16x32_bf16 v[40:43], v[104:107], v[8:11], v[40:43]
	ds_read_b128 v[104:107], v49 offset:41984
	ds_read_b128 v[120:123], v49 offset:44032
	ds_read_b128 v[124:127], v49 offset:46080
	ds_read_b128 v[128:131], v49 offset:48128
	v_mfma_f32_16x16x32_bf16 v[92:95], v[92:95], v[8:11], v[96:99]
	s_add_u32 s100, s10, 0x11e00080
	s_addc_u32 s101, s11, 0
	s_mov_b32 m0, s20
	s_nop 0
	global_load_lds_dwordx4 v241, s[100:101]
	s_waitcnt lgkmcnt(0)
	v_mfma_f32_16x16x32_bf16 v[50:53], v[50:53], v[8:11], v[66:69]
	v_mfma_f32_16x16x32_bf16 v[66:69], v[108:111], v[8:11], v[72:75]
	v_mfma_f32_16x16x32_bf16 v[72:75], v[112:115], v[8:11], v[80:83]
	v_mfma_f32_16x16x32_bf16 v[80:83], v[116:119], v[8:11], v[84:87]
	v_mfma_f32_16x16x32_bf16 v[76:79], v[104:107], v[8:11], v[76:79]
	v_mfma_f32_16x16x32_bf16 v[84:87], v[120:123], v[8:11], v[88:91]
	s_nop 2
	ds_read_b128 v[88:91], v49 offset:30720
	ds_read_b128 v[96:99], v49 offset:28672
	ds_read_b128 v[104:107], v49 offset:26624
	ds_read_b128 v[108:111], v49 offset:24576
	v_mfma_f32_16x16x32_bf16 v[100:103], v[124:127], v[8:11], v[100:103]
	ds_read_b128 v[112:115], v49 offset:22528
	ds_read_b128 v[116:119], v49 offset:20480
	ds_read_b128 v[120:123], v49 offset:18432
	ds_read_b128 v[124:127], v49 offset:16384
	v_mfma_f32_16x16x32_bf16 v[8:11], v[128:131], v[8:11], v[12:15]
	s_add_u32 s100, s10, 0x11e08080
	s_addc_u32 s101, s11, 0
	s_mov_b32 m0, s23
	s_nop 0
	global_load_lds_dwordx4 v241, s[100:101]
	s_waitcnt lgkmcnt(0)
	v_mfma_f32_16x16x32_bf16 v[12:15], v[124:127], v[4:7], v[16:19]
	v_mfma_f32_16x16x32_bf16 v[16:19], v[120:123], v[4:7], v[20:23]
	v_mfma_f32_16x16x32_bf16 v[20:23], v[116:119], v[4:7], v[24:27]
	v_mfma_f32_16x16x32_bf16 v[24:27], v[112:115], v[4:7], v[28:31]
	v_mfma_f32_16x16x32_bf16 v[28:31], v[108:111], v[4:7], v[32:35]
	v_mfma_f32_16x16x32_bf16 v[32:35], v[104:107], v[4:7], v[36:39]
	s_nop 2
	ds_read_b128 v[36:39], v49 offset:49152
	ds_read_b128 v[104:107], v49 offset:51200
	ds_read_b128 v[108:111], v49 offset:53248
	ds_read_b128 v[112:115], v49 offset:55296
	v_mfma_f32_16x16x32_bf16 v[96:99], v[96:99], v[4:7], v[40:43]
	s_nop 2
	ds_read_b128 v[40:43], v49 offset:57344
	ds_read_b128 v[116:119], v49 offset:59392
	ds_read_b128 v[120:123], v49 offset:61440
	ds_read_b128 v[124:127], v49 offset:63488
	v_mfma_f32_16x16x32_bf16 v[88:91], v[88:91], v[4:7], v[92:95]
	s_add_u32 s100, s10, 0x11e10000
	s_addc_u32 s101, s11, 0
	s_mov_b32 m0, s24
	s_nop 0
	global_load_lds_dwordx4 v241, s[100:101]
	s_waitcnt lgkmcnt(0)
	v_mfma_f32_16x16x32_bf16 v[50:53], v[36:39], v[4:7], v[50:53]
	v_mfma_f32_16x16x32_bf16 v[66:69], v[104:107], v[4:7], v[66:69]
	v_mfma_f32_16x16x32_bf16 v[72:75], v[108:111], v[4:7], v[72:75]
	v_mfma_f32_16x16x32_bf16 v[80:83], v[112:115], v[4:7], v[80:83]
	v_mfma_f32_16x16x32_bf16 v[76:79], v[40:43], v[4:7], v[76:79]
	ds_read_b128 v[92:95], v49 offset:31744
	ds_read_b128 v[36:39], v49 offset:29696
	ds_read_b128 v[40:43], v49 offset:27648
	ds_read_b128 v[104:107], v49 offset:25600
	v_mfma_f32_16x16x32_bf16 v[84:87], v[116:119], v[4:7], v[84:87]
	v_mfma_f32_16x16x32_bf16 v[100:103], v[120:123], v[4:7], v[100:103]
	ds_read_b128 v[108:111], v49 offset:23552
	ds_read_b128 v[112:115], v49 offset:21504
	ds_read_b128 v[116:119], v49 offset:19456
	ds_read_b128 v[120:123], v49 offset:17408
	v_mfma_f32_16x16x32_bf16 v[124:127], v[124:127], v[4:7], v[8:11]
	s_add_u32 s100, s10, 0x11e18000
	s_addc_u32 s101, s11, 0
	s_mov_b32 m0, s25
	s_nop 0
	global_load_lds_dwordx4 v241, s[100:101]
	s_waitcnt lgkmcnt(0)
	v_mfma_f32_16x16x32_bf16 v[120:123], v[120:123], v[0:3], v[12:15]
	v_mfma_f32_16x16x32_bf16 v[116:119], v[116:119], v[0:3], v[16:19]
	ds_read_b128 v[4:7], v49 offset:50176
	ds_read_b128 v[8:11], v49 offset:52224
	ds_read_b128 v[12:15], v49 offset:54272
	ds_read_b128 v[16:19], v49 offset:56320
	v_mfma_f32_16x16x32_bf16 v[36:39], v[36:39], v[0:3], v[96:99]
	s_nop 2
	ds_read_b128 v[96:99], v49 offset:58368
	ds_read_b128 v[128:131], v49 offset:60416
	ds_read_b128 v[132:135], v49 offset:62464
	ds_read_b128 v[136:139], v49 offset:64512
	v_mfma_f32_16x16x32_bf16 v[112:115], v[112:115], v[0:3], v[20:23]
	v_mfma_f32_16x16x32_bf16 v[108:111], v[108:111], v[0:3], v[24:27]
	v_mfma_f32_16x16x32_bf16 v[104:107], v[104:107], v[0:3], v[28:31]
	v_mfma_f32_16x16x32_bf16 v[40:43], v[40:43], v[0:3], v[32:35]
	v_mfma_f32_16x16x32_bf16 v[32:35], v[92:95], v[0:3], v[88:91]
	s_add_u32 s100, s10, 0x11e10080
	s_addc_u32 s101, s11, 0
	s_mov_b32 m0, s26
	s_nop 0
	global_load_lds_dwordx4 v241, s[100:101]
	s_waitcnt lgkmcnt(0)
	v_mfma_f32_16x16x32_bf16 v[28:31], v[4:7], v[0:3], v[50:53]
	v_mfma_f32_16x16x32_bf16 v[24:27], v[8:11], v[0:3], v[66:69]
	v_mfma_f32_16x16x32_bf16 v[20:23], v[12:15], v[0:3], v[72:75]
	v_mfma_f32_16x16x32_bf16 v[16:19], v[16:19], v[0:3], v[80:83]
	v_mfma_f32_16x16x32_bf16 v[12:15], v[96:99], v[0:3], v[76:79]
	v_mfma_f32_16x16x32_bf16 v[8:11], v[128:131], v[0:3], v[84:87]
	v_mfma_f32_16x16x32_bf16 v[4:7], v[132:135], v[0:3], v[100:103]
	v_mfma_f32_16x16x32_bf16 v[0:3], v[136:139], v[0:3], v[124:127]
	s_add_u32 s100, s10, 0x11e18080
	s_addc_u32 s101, s11, 0
	s_mov_b32 m0, s27
	s_nop 0
	global_load_lds_dwordx4 v241, s[100:101]
	v_max_f32_e32 v49, v123, v123
	v_max_f32_e32 v50, v122, v122
	v_max_f32_e32 v49, v50, v49
	v_max_f32_e32 v50, v117, v117
	v_max_f32_e32 v51, v116, v116
	v_max_f32_e32 v50, v51, v50
	v_max_f32_e32 v51, v119, v119
	v_max_f32_e32 v52, v118, v118
	v_max3_f32 v49, v120, v121, v49
	v_max_f32_e32 v51, v52, v51
	v_max3_f32 v49, v49, v50, v51
	v_max_f32_e32 v50, v113, v113
	v_max_f32_e32 v51, v112, v112
	v_max_f32_e32 v50, v51, v50
	v_max_f32_e32 v51, v115, v115
	v_max_f32_e32 v52, v114, v114
	v_max_f32_e32 v51, v52, v51
	v_max3_f32 v49, v49, v50, v51
	v_max_f32_e32 v50, v109, v109
	v_max_f32_e32 v51, v108, v108
	v_max_f32_e32 v50, v51, v50
	v_max_f32_e32 v51, v111, v111
	v_max_f32_e32 v52, v110, v110
	v_max_f32_e32 v51, v52, v51
	v_max3_f32 v49, v49, v50, v51
	v_max_f32_e32 v50, v105, v105
	v_max_f32_e32 v51, v104, v104
	v_max_f32_e32 v50, v51, v50
	v_max_f32_e32 v51, v107, v107
	v_max_f32_e32 v52, v106, v106
	v_max_f32_e32 v51, v52, v51
	v_max3_f32 v49, v49, v50, v51
	v_max_f32_e32 v50, v41, v41
	v_max_f32_e32 v51, v40, v40
	v_max_f32_e32 v50, v51, v50
	v_max_f32_e32 v51, v43, v43
	v_max_f32_e32 v52, v42, v42
	v_max_f32_e32 v51, v52, v51
	v_max3_f32 v49, v49, v50, v51
	v_max_f32_e32 v50, v37, v37
	v_max_f32_e32 v51, v36, v36
	v_max_f32_e32 v50, v51, v50
	v_max_f32_e32 v51, v39, v39
	v_max_f32_e32 v52, v38, v38
	v_max_f32_e32 v51, v52, v51
	v_max3_f32 v49, v49, v50, v51
	v_max_f32_e32 v50, v33, v33
	v_max_f32_e32 v51, v32, v32
	v_max_f32_e32 v50, v51, v50
	v_max_f32_e32 v51, v35, v35
	v_max_f32_e32 v52, v34, v34
	v_max_f32_e32 v51, v52, v51
	v_max3_f32 v49, v49, v50, v51
	v_max_f32_e32 v50, v29, v29
	v_max_f32_e32 v51, v28, v28
	v_max_f32_e32 v50, v51, v50
	v_max_f32_e32 v51, v31, v31
	v_max_f32_e32 v52, v30, v30
	v_max_f32_e32 v51, v52, v51
	v_max3_f32 v49, v49, v50, v51
	v_max_f32_e32 v50, v25, v25
	v_max_f32_e32 v51, v24, v24
	v_max_f32_e32 v50, v51, v50
	v_max_f32_e32 v51, v27, v27
	v_max_f32_e32 v52, v26, v26
	v_max_f32_e32 v51, v52, v51
	v_max3_f32 v49, v49, v50, v51
	v_max_f32_e32 v50, v21, v21
	v_max_f32_e32 v51, v20, v20
	v_max_f32_e32 v50, v51, v50
	v_max_f32_e32 v51, v23, v23
	v_max_f32_e32 v52, v22, v22
	v_max_f32_e32 v51, v52, v51
	v_max3_f32 v49, v49, v50, v51
	v_max_f32_e32 v50, v17, v17
	v_max_f32_e32 v51, v16, v16
	v_max_f32_e32 v50, v51, v50
	v_max_f32_e32 v51, v19, v19
	v_max_f32_e32 v52, v18, v18
	v_max_f32_e32 v51, v52, v51
	v_max3_f32 v49, v49, v50, v51
	v_max_f32_e32 v50, v13, v13
	v_max_f32_e32 v51, v12, v12
	v_max_f32_e32 v50, v51, v50
	v_max_f32_e32 v51, v15, v15
	v_max_f32_e32 v52, v14, v14
	v_max_f32_e32 v51, v52, v51
	v_max3_f32 v49, v49, v50, v51
	v_max_f32_e32 v50, v9, v9
	v_max_f32_e32 v51, v8, v8
	v_max_f32_e32 v50, v51, v50
	v_max_f32_e32 v51, v11, v11
	v_max_f32_e32 v52, v10, v10
	v_max_f32_e32 v51, v52, v51
	v_max3_f32 v49, v49, v50, v51
	v_max_f32_e32 v50, v5, v5
	v_max_f32_e32 v51, v4, v4
	v_max_f32_e32 v50, v51, v50
	v_max_f32_e32 v51, v7, v7
	v_max_f32_e32 v52, v6, v6
	v_max_f32_e32 v51, v52, v51
	v_max3_f32 v49, v49, v50, v51
	v_max_f32_e32 v50, v1, v1
	v_max_f32_e32 v51, v0, v0
	v_max_f32_e32 v50, v51, v50
	v_max_f32_e32 v51, v3, v3
	v_max_f32_e32 v52, v2, v2
	v_max_f32_e32 v51, v52, v51
	v_max3_f32 v49, v49, v50, v51
	v_mbcnt_lo_u32_b32 v50, -1, 0
	v_mbcnt_hi_u32_b32 v50, -1, v50
	v_and_b32_e32 v52, 64, v50
	v_xor_b32_e32 v51, 16, v50
	v_add_u32_e32 v52, 64, v52
	v_cmp_lt_i32_e32 vcc, v51, v52
	s_nop 1
	v_cndmask_b32_e32 v51, v50, v51, vcc
	v_lshlrev_b32_e32 v51, 2, v51
	v_mov_b32_e32 v53, v49
	s_nop 1
	v_permlane16_swap_b32_e32 v53, v49
	s_waitcnt lgkmcnt(0)
	v_max_f32_e32 v53, v53, v53
	v_max_f32_e32 v49, v49, v53
	v_xor_b32_e32 v53, 32, v50
	v_cmp_lt_i32_e32 vcc, v53, v52
	s_nop 1
	v_cndmask_b32_e32 v50, v50, v53, vcc
	v_lshlrev_b32_e32 v50, 2, v50
	v_mov_b32_e32 v52, v49
	s_nop 1
	v_permlane32_swap_b32_e32 v52, v49
	s_waitcnt lgkmcnt(0)
	v_max_f32_e32 v52, v52, v52
	v_max_f32_e32 v49, v49, v52
	v_sub_f32_e32 v52, v120, v49
	v_exp_f32_e32 v52, v52
	v_sub_f32_e32 v53, v121, v49
	v_exp_f32_e32 v53, v53
	v_sub_f32_e32 v54, v122, v49
	v_exp_f32_e32 v54, v54
	v_sub_f32_e32 v55, v123, v49
	v_exp_f32_e32 v55, v55
	v_sub_f32_e32 v59, v116, v49
	v_add_f32_e32 v57, 0, v52
	v_exp_f32_e32 v59, v59
	v_sub_f32_e32 v62, v117, v49
	v_add_f32_e32 v57, v53, v57
	v_exp_f32_e32 v62, v62
	v_sub_f32_e32 v63, v118, v49
	v_add_f32_e32 v57, v54, v57
	v_exp_f32_e32 v63, v63
	v_sub_f32_e32 v64, v119, v49
	v_add_f32_e32 v57, v55, v57
	v_exp_f32_e32 v64, v64
	v_sub_f32_e32 v66, v112, v49
	v_add_f32_e32 v57, v59, v57
	v_exp_f32_e32 v66, v66
	v_sub_f32_e32 v67, v113, v49
	v_add_f32_e32 v57, v62, v57
	v_exp_f32_e32 v67, v67
	v_sub_f32_e32 v68, v114, v49
	v_add_f32_e32 v57, v63, v57
	v_exp_f32_e32 v68, v68
	v_sub_f32_e32 v69, v115, v49
	v_add_f32_e32 v57, v64, v57
	v_exp_f32_e32 v69, v69
	v_sub_f32_e32 v71, v108, v49
	v_add_f32_e32 v57, v66, v57
	v_exp_f32_e32 v71, v71
	v_sub_f32_e32 v72, v109, v49
	v_add_f32_e32 v57, v67, v57
	v_exp_f32_e32 v72, v72
	v_sub_f32_e32 v73, v110, v49
	v_add_f32_e32 v57, v68, v57
	v_exp_f32_e32 v73, v73
	v_sub_f32_e32 v74, v111, v49
	v_add_f32_e32 v57, v69, v57
	v_exp_f32_e32 v74, v74
	v_sub_f32_e32 v75, v104, v49
	v_add_f32_e32 v57, v71, v57
	v_exp_f32_e32 v75, v75
	v_sub_f32_e32 v76, v105, v49
	v_add_f32_e32 v57, v72, v57
	v_exp_f32_e32 v76, v76
	v_sub_f32_e32 v77, v106, v49
	v_add_f32_e32 v57, v73, v57
	v_exp_f32_e32 v77, v77
	v_sub_f32_e32 v78, v107, v49
	v_add_f32_e32 v57, v74, v57
	v_exp_f32_e32 v78, v78
	v_sub_f32_e32 v40, v40, v49
	v_add_f32_e32 v57, v75, v57
	v_exp_f32_e32 v40, v40
	v_sub_f32_e32 v41, v41, v49
	v_add_f32_e32 v57, v76, v57
	v_exp_f32_e32 v41, v41
	v_sub_f32_e32 v42, v42, v49
	v_add_f32_e32 v57, v77, v57
	v_exp_f32_e32 v42, v42
	v_sub_f32_e32 v43, v43, v49
	v_add_f32_e32 v57, v78, v57
	v_exp_f32_e32 v43, v43
	v_sub_f32_e32 v36, v36, v49
	v_add_f32_e32 v57, v40, v57
	v_exp_f32_e32 v36, v36
	v_sub_f32_e32 v37, v37, v49
	v_add_f32_e32 v57, v41, v57
	v_exp_f32_e32 v37, v37
	v_sub_f32_e32 v38, v38, v49
	v_add_f32_e32 v57, v42, v57
	v_exp_f32_e32 v38, v38
	v_sub_f32_e32 v39, v39, v49
	v_add_f32_e32 v57, v43, v57
	v_exp_f32_e32 v39, v39
	v_sub_f32_e32 v32, v32, v49
	v_add_f32_e32 v57, v36, v57
	v_exp_f32_e32 v32, v32
	v_sub_f32_e32 v33, v33, v49
	v_add_f32_e32 v57, v37, v57
	v_exp_f32_e32 v33, v33
	v_sub_f32_e32 v34, v34, v49
	v_add_f32_e32 v57, v38, v57
	v_exp_f32_e32 v34, v34
	v_sub_f32_e32 v35, v35, v49
	v_add_f32_e32 v57, v39, v57
	v_exp_f32_e32 v35, v35
	v_sub_f32_e32 v28, v28, v49
	v_add_f32_e32 v57, v32, v57
	v_exp_f32_e32 v79, v28
	v_sub_f32_e32 v28, v29, v49
	v_add_f32_e32 v57, v33, v57
	v_exp_f32_e32 v80, v28
	v_sub_f32_e32 v28, v30, v49
	v_add_f32_e32 v57, v34, v57
	v_exp_f32_e32 v81, v28
	v_sub_f32_e32 v28, v31, v49
	v_add_f32_e32 v57, v35, v57
	v_exp_f32_e32 v82, v28
	v_sub_f32_e32 v24, v24, v49
	v_add_f32_e32 v28, v79, v57
	v_exp_f32_e32 v57, v24
	v_sub_f32_e32 v24, v25, v49
	v_add_f32_e32 v28, v80, v28
	v_exp_f32_e32 v83, v24
	v_sub_f32_e32 v24, v26, v49
	v_add_f32_e32 v28, v81, v28
	v_exp_f32_e32 v84, v24
	v_sub_f32_e32 v24, v27, v49
	v_add_f32_e32 v28, v82, v28
	v_exp_f32_e32 v85, v24
	v_sub_f32_e32 v20, v20, v49
	v_add_f32_e32 v24, v57, v28
	v_exp_f32_e32 v86, v20
	v_sub_f32_e32 v20, v21, v49
	v_add_f32_e32 v24, v83, v24
	v_exp_f32_e32 v87, v20
	v_sub_f32_e32 v20, v22, v49
	v_add_f32_e32 v24, v84, v24
	v_exp_f32_e32 v88, v20
	v_sub_f32_e32 v20, v23, v49
	v_add_f32_e32 v24, v85, v24
	v_exp_f32_e32 v89, v20
	v_sub_f32_e32 v16, v16, v49
	v_add_f32_e32 v20, v86, v24
	v_exp_f32_e32 v90, v16
	v_sub_f32_e32 v16, v17, v49
	v_add_f32_e32 v20, v87, v20
	v_exp_f32_e32 v91, v16
	v_sub_f32_e32 v16, v18, v49
	v_add_f32_e32 v20, v88, v20
	v_exp_f32_e32 v92, v16
	v_sub_f32_e32 v16, v19, v49
	v_add_f32_e32 v20, v89, v20
	v_exp_f32_e32 v93, v16
	v_sub_f32_e32 v12, v12, v49
	v_add_f32_e32 v16, v90, v20
	v_exp_f32_e32 v94, v12
	v_sub_f32_e32 v12, v13, v49
	v_add_f32_e32 v16, v91, v16
	v_exp_f32_e32 v95, v12
	v_sub_f32_e32 v12, v14, v49
	v_add_f32_e32 v16, v92, v16
	v_exp_f32_e32 v96, v12
	v_sub_f32_e32 v12, v15, v49
	v_add_f32_e32 v16, v93, v16
	v_exp_f32_e32 v97, v12
	v_sub_f32_e32 v8, v8, v49
	v_add_f32_e32 v12, v94, v16
	v_exp_f32_e32 v98, v8
	v_sub_f32_e32 v8, v9, v49
	v_add_f32_e32 v12, v95, v12
	v_exp_f32_e32 v99, v8
	v_sub_f32_e32 v8, v10, v49
	v_add_f32_e32 v12, v96, v12
	v_exp_f32_e32 v100, v8
	v_sub_f32_e32 v8, v11, v49
	v_add_f32_e32 v12, v97, v12
	v_exp_f32_e32 v11, v8
	v_sub_f32_e32 v4, v4, v49
	v_add_f32_e32 v8, v98, v12
	v_exp_f32_e32 v101, v4
	v_sub_f32_e32 v4, v5, v49
	v_add_f32_e32 v8, v99, v8
	v_exp_f32_e32 v102, v4
	v_sub_f32_e32 v4, v6, v49
	v_add_f32_e32 v8, v100, v8
	v_exp_f32_e32 v103, v4
	v_sub_f32_e32 v4, v7, v49
	v_add_f32_e32 v8, v11, v8
	v_exp_f32_e32 v104, v4
	v_sub_f32_e32 v0, v0, v49
	v_add_f32_e32 v4, v101, v8
	v_exp_f32_e32 v105, v0
	v_sub_f32_e32 v0, v1, v49
	v_add_f32_e32 v4, v102, v4
	v_exp_f32_e32 v106, v0
	v_sub_f32_e32 v0, v2, v49
	v_add_f32_e32 v4, v103, v4
	v_exp_f32_e32 v107, v0
	v_sub_f32_e32 v0, v3, v49
	v_add_f32_e32 v4, v104, v4
	v_exp_f32_e32 v3, v0
	v_add_f32_e32 v0, v105, v4
	v_add_f32_e32 v0, v106, v0
	v_add_f32_e32 v0, v107, v0
	v_add_f32_e32 v0, v3, v0
	v_mov_b32_e32 v1, v0
	s_nop 1
	v_permlane16_swap_b32_e32 v1, v0
	v_cvt_pk_bf16_f32 v28, v52, v53
	v_cvt_pk_bf16_f32 v29, v54, v55
	v_cvt_pk_bf16_f32 v30, v59, v62
	v_cvt_pk_bf16_f32 v31, v63, v64
	s_waitcnt lgkmcnt(0)
	v_add_f32_e32 v0, v0, v1
	v_mov_b32_e32 v1, v0
	s_nop 1
	v_permlane32_swap_b32_e32 v1, v0
	v_cvt_pk_bf16_f32 v20, v66, v67
	v_cvt_pk_bf16_f32 v21, v68, v69
	v_cvt_pk_bf16_f32 v22, v71, v72
	v_cvt_pk_bf16_f32 v23, v73, v74
	s_waitcnt lgkmcnt(0)
	v_add_f32_e32 v49, v0, v1
	v_cvt_pk_bf16_f32 v24, v75, v76
	v_cvt_pk_bf16_f32 v25, v77, v78
	v_cvt_pk_bf16_f32 v26, v40, v41
	v_cvt_pk_bf16_f32 v27, v42, v43
	v_cvt_pk_bf16_f32 v16, v36, v37
	v_cvt_pk_bf16_f32 v17, v38, v39
	v_cvt_pk_bf16_f32 v18, v32, v33
	v_cvt_pk_bf16_f32 v19, v34, v35
	v_cvt_pk_bf16_f32 v12, v79, v80
	v_cvt_pk_bf16_f32 v13, v81, v82
	v_cvt_pk_bf16_f32 v14, v57, v83
	v_cvt_pk_bf16_f32 v15, v84, v85
	v_cvt_pk_bf16_f32 v4, v86, v87
	v_cvt_pk_bf16_f32 v5, v88, v89
	v_cvt_pk_bf16_f32 v6, v90, v91
	v_cvt_pk_bf16_f32 v7, v92, v93
	v_cvt_pk_bf16_f32 v8, v94, v95
	v_cvt_pk_bf16_f32 v9, v96, v97
	v_cvt_pk_bf16_f32 v10, v98, v99
	v_cvt_pk_bf16_f32 v11, v100, v11
	v_cvt_pk_bf16_f32 v0, v101, v102
	v_cvt_pk_bf16_f32 v1, v103, v104
	v_cvt_pk_bf16_f32 v2, v105, v106
	v_cvt_pk_bf16_f32 v3, v107, v3
	s_waitcnt vmcnt(0)
	s_waitcnt vmcnt(0)
	s_barrier
	v_mov_b32_e32 v64, v65
	v_div_scale_f32 v62, vcc, 1.0, v49, 1.0
	v_lshlrev_b32_e32 v54, 2, v70
	v_ashrrev_i32_e32 v55, 31, v54
	ds_read_b128 v[32:35], v64
	ds_read_b128 v[36:39], v64 offset:2048
	v_div_scale_f32 v57, s[0:1], v49, v49, 1.0
	v_rcp_f32_e32 v59, v57
	s_waitcnt lgkmcnt(0)
	v_mfma_f32_16x16x32_bf16 v[44:47], v[32:35], v[28:31], 0
	v_fma_f32 v40, -v57, v59, 1.0
	v_fmac_f32_e32 v59, v40, v59
	ds_read_b128 v[40:43], v64 offset:4096
	ds_read_b128 v[32:35], v64 offset:6144
	v_mul_f32_e32 v63, v62, v59
	v_fma_f32 v66, -v57, v63, v62
	v_fmac_f32_e32 v63, v66, v59
	v_mfma_f32_16x16x32_bf16 v[50:53], v[36:39], v[28:31], 0
	v_fma_f32 v36, -v57, v63, v62
	ds_read_b128 v[66:69], v64 offset:8192
	ds_read_b128 v[70:73], v64 offset:10240
	v_div_fmas_f32 v36, v36, v59, v63
	s_waitcnt lgkmcnt(0)
	v_mfma_f32_16x16x32_bf16 v[74:77], v[32:35], v[28:31], 0
	v_lshl_add_u64 v[34:35], v[54:55], 1, v[60:61]
	ds_read_b128 v[60:63], v64 offset:12288
	ds_read_b128 v[78:81], v64 offset:14336
	ds_read_b128 v[82:85], v64 offset:32768
	ds_read_b128 v[86:89], v64 offset:34816
	ds_read_b128 v[90:93], v64 offset:36864
	ds_read_b128 v[94:97], v64 offset:38912
	ds_read_b128 v[98:101], v64 offset:40960
	ds_read_b128 v[102:105], v64 offset:43008
	ds_read_b128 v[106:109], v64 offset:45056
	ds_read_b128 v[110:113], v64 offset:47104
	s_mov_b64 s[0:1], 0x1000000
	v_mfma_f32_16x16x32_bf16 v[38:41], v[40:43], v[28:31], 0
	v_div_fixup_f32 v36, v36, v49, 1.0
	v_lshl_add_u64 v[32:33], v[34:35], 0, s[0:1]
	v_mfma_f32_16x16x32_bf16 v[66:69], v[66:69], v[28:31], 0
	v_mfma_f32_16x16x32_bf16 v[70:73], v[70:73], v[28:31], 0
	s_waitcnt lgkmcnt(0)
	v_mfma_f32_16x16x32_bf16 v[60:63], v[60:63], v[28:31], 0
	v_mfma_f32_16x16x32_bf16 v[78:81], v[78:81], v[28:31], 0
	s_add_u32 s100, s10, 0x11e00100
	s_addc_u32 s101, s11, 0
	s_mov_b32 m0, s19
	s_nop 0
	global_load_lds_dwordx4 v241, s[100:101]
	ds_read_b128 v[114:117], v64 offset:30720
	ds_read_b128 v[118:121], v64 offset:28672
	ds_read_b128 v[122:125], v64 offset:26624
	ds_read_b128 v[126:129], v64 offset:24576
	ds_read_b128 v[130:133], v64 offset:22528
	ds_read_b128 v[134:137], v64 offset:20480
	ds_read_b128 v[138:141], v64 offset:18432
	ds_read_b128 v[142:145], v64 offset:16384
	v_mfma_f32_16x16x32_bf16 v[82:85], v[82:85], v[28:31], 0
	v_mfma_f32_16x16x32_bf16 v[86:89], v[86:89], v[28:31], 0
	v_mfma_f32_16x16x32_bf16 v[90:93], v[90:93], v[28:31], 0
	v_mfma_f32_16x16x32_bf16 v[94:97], v[94:97], v[28:31], 0
	v_mfma_f32_16x16x32_bf16 v[98:101], v[98:101], v[28:31], 0
	v_mfma_f32_16x16x32_bf16 v[102:105], v[102:105], v[28:31], 0
	v_mfma_f32_16x16x32_bf16 v[106:109], v[106:109], v[28:31], 0
	v_mfma_f32_16x16x32_bf16 v[110:113], v[110:113], v[28:31], 0
	s_add_u32 s100, s10, 0x11e08100
	s_addc_u32 s101, s11, 0
	s_mov_b32 m0, s13
	s_nop 0
	global_load_lds_dwordx4 v241, s[100:101]
	s_waitcnt lgkmcnt(0)
	v_mfma_f32_16x16x32_bf16 v[42:45], v[142:145], v[24:27], v[44:47]
	v_mfma_f32_16x16x32_bf16 v[50:53], v[138:141], v[24:27], v[50:53]
	v_mfma_f32_16x16x32_bf16 v[38:41], v[134:137], v[24:27], v[38:41]
	v_mfma_f32_16x16x32_bf16 v[74:77], v[130:133], v[24:27], v[74:77]
	v_mfma_f32_16x16x32_bf16 v[66:69], v[126:129], v[24:27], v[66:69]
	v_mfma_f32_16x16x32_bf16 v[70:73], v[122:125], v[24:27], v[70:73]
	ds_read_b128 v[122:125], v64 offset:49152
	ds_read_b128 v[126:129], v64 offset:51200
	ds_read_b128 v[130:133], v64 offset:53248
	ds_read_b128 v[134:137], v64 offset:55296
	v_mfma_f32_16x16x32_bf16 v[60:63], v[118:121], v[24:27], v[60:63]
	ds_read_b128 v[118:121], v64 offset:57344
	ds_read_b128 v[138:141], v64 offset:59392
	ds_read_b128 v[142:145], v64 offset:61440
	ds_read_b128 v[146:149], v64 offset:63488
	v_mfma_f32_16x16x32_bf16 v[78:81], v[114:117], v[24:27], v[78:81]
	s_add_u32 s100, s10, 0x11e00180
	s_addc_u32 s101, s11, 0
	s_mov_b32 m0, s12
	s_nop 0
	global_load_lds_dwordx4 v241, s[100:101]
	s_waitcnt lgkmcnt(0)
	v_mfma_f32_16x16x32_bf16 v[82:85], v[122:125], v[24:27], v[82:85]
	v_mfma_f32_16x16x32_bf16 v[86:89], v[126:129], v[24:27], v[86:89]
	v_mfma_f32_16x16x32_bf16 v[90:93], v[130:133], v[24:27], v[90:93]
	v_mfma_f32_16x16x32_bf16 v[94:97], v[134:137], v[24:27], v[94:97]
	v_mfma_f32_16x16x32_bf16 v[98:101], v[118:121], v[24:27], v[98:101]
	ds_read_b128 v[114:117], v64 offset:15360
	ds_read_b128 v[118:121], v64 offset:13312
	ds_read_b128 v[122:125], v64 offset:11264
	ds_read_b128 v[126:129], v64 offset:9216
	v_mfma_f32_16x16x32_bf16 v[102:105], v[138:141], v[24:27], v[102:105]
	v_mfma_f32_16x16x32_bf16 v[106:109], v[142:145], v[24:27], v[106:109]
	ds_read_b128 v[130:133], v64 offset:7168
	ds_read_b128 v[134:137], v64 offset:5120
	ds_read_b128 v[138:141], v64 offset:3072
	ds_read_b128 v[142:145], v64 offset:1024
	v_mfma_f32_16x16x32_bf16 v[110:113], v[146:149], v[24:27], v[110:113]
	s_add_u32 s100, s10, 0x11e08180
	s_addc_u32 s101, s11, 0
	s_mov_b32 m0, s14
	s_nop 0
	global_load_lds_dwordx4 v241, s[100:101]
	s_waitcnt lgkmcnt(0)
	v_mfma_f32_16x16x32_bf16 v[42:45], v[142:145], v[20:23], v[42:45]
	v_mfma_f32_16x16x32_bf16 v[50:53], v[138:141], v[20:23], v[50:53]
	v_mfma_f32_16x16x32_bf16 v[38:41], v[134:137], v[20:23], v[38:41]
	v_mfma_f32_16x16x32_bf16 v[74:77], v[130:133], v[20:23], v[74:77]
	v_mfma_f32_16x16x32_bf16 v[66:69], v[126:129], v[20:23], v[66:69]
	v_mfma_f32_16x16x32_bf16 v[70:73], v[122:125], v[20:23], v[70:73]
	ds_read_b128 v[122:125], v64 offset:33792
	ds_read_b128 v[126:129], v64 offset:35840
	ds_read_b128 v[130:133], v64 offset:37888
	ds_read_b128 v[134:137], v64 offset:39936
	v_mfma_f32_16x16x32_bf16 v[60:63], v[118:121], v[20:23], v[60:63]
	ds_read_b128 v[118:121], v64 offset:41984
	ds_read_b128 v[138:141], v64 offset:44032
	ds_read_b128 v[142:145], v64 offset:46080
	ds_read_b128 v[146:149], v64 offset:48128
	v_mfma_f32_16x16x32_bf16 v[78:81], v[114:117], v[20:23], v[78:81]
	s_add_u32 s100, s10, 0x11e10100
	s_addc_u32 s101, s11, 0
	s_mov_b32 m0, s15
	s_nop 0
	global_load_lds_dwordx4 v241, s[100:101]
	s_waitcnt lgkmcnt(0)
	v_mfma_f32_16x16x32_bf16 v[82:85], v[122:125], v[20:23], v[82:85]
	v_mfma_f32_16x16x32_bf16 v[86:89], v[126:129], v[20:23], v[86:89]
	v_mfma_f32_16x16x32_bf16 v[90:93], v[130:133], v[20:23], v[90:93]
	v_mfma_f32_16x16x32_bf16 v[94:97], v[134:137], v[20:23], v[94:97]
	v_mfma_f32_16x16x32_bf16 v[98:101], v[118:121], v[20:23], v[98:101]
	ds_read_b128 v[114:117], v64 offset:31744
	ds_read_b128 v[118:121], v64 offset:29696
	ds_read_b128 v[122:125], v64 offset:27648
	ds_read_b128 v[126:129], v64 offset:25600
	v_mfma_f32_16x16x32_bf16 v[102:105], v[138:141], v[20:23], v[102:105]
	v_mfma_f32_16x16x32_bf16 v[106:109], v[142:145], v[20:23], v[106:109]
	ds_read_b128 v[130:133], v64 offset:23552
	ds_read_b128 v[134:137], v64 offset:21504
	ds_read_b128 v[138:141], v64 offset:19456
	ds_read_b128 v[142:145], v64 offset:17408
	v_mfma_f32_16x16x32_bf16 v[110:113], v[146:149], v[20:23], v[110:113]
	s_add_u32 s100, s10, 0x11e18100
	s_addc_u32 s101, s11, 0
	s_mov_b32 m0, s16
	s_nop 0
	global_load_lds_dwordx4 v241, s[100:101]
	s_waitcnt lgkmcnt(0)
	v_mfma_f32_16x16x32_bf16 v[42:45], v[142:145], v[16:19], v[42:45]
	v_mfma_f32_16x16x32_bf16 v[50:53], v[138:141], v[16:19], v[50:53]
	v_mfma_f32_16x16x32_bf16 v[38:41], v[134:137], v[16:19], v[38:41]
	v_mfma_f32_16x16x32_bf16 v[74:77], v[130:133], v[16:19], v[74:77]
	v_mfma_f32_16x16x32_bf16 v[66:69], v[126:129], v[16:19], v[66:69]
	v_mfma_f32_16x16x32_bf16 v[70:73], v[122:125], v[16:19], v[70:73]
	ds_read_b128 v[122:125], v64 offset:50176
	ds_read_b128 v[126:129], v64 offset:52224
	ds_read_b128 v[130:133], v64 offset:54272
	ds_read_b128 v[134:137], v64 offset:56320
	v_mfma_f32_16x16x32_bf16 v[60:63], v[118:121], v[16:19], v[60:63]
	ds_read_b128 v[118:121], v64 offset:58368
	ds_read_b128 v[138:141], v64 offset:60416
	ds_read_b128 v[142:145], v64 offset:62464
	ds_read_b128 v[146:149], v64 offset:64512
	v_mfma_f32_16x16x32_bf16 v[78:81], v[114:117], v[16:19], v[78:81]
	s_add_u32 s100, s10, 0x11e10180
	s_addc_u32 s101, s11, 0
	s_mov_b32 m0, s17
	s_nop 0
	global_load_lds_dwordx4 v241, s[100:101]
	s_waitcnt lgkmcnt(0)
	v_mfma_f32_16x16x32_bf16 v[82:85], v[122:125], v[16:19], v[82:85]
	v_mfma_f32_16x16x32_bf16 v[86:89], v[126:129], v[16:19], v[86:89]
	v_mfma_f32_16x16x32_bf16 v[90:93], v[130:133], v[16:19], v[90:93]
	v_mfma_f32_16x16x32_bf16 v[94:97], v[134:137], v[16:19], v[94:97]
	v_mfma_f32_16x16x32_bf16 v[98:101], v[118:121], v[16:19], v[98:101]
	v_mfma_f32_16x16x32_bf16 v[102:105], v[138:141], v[16:19], v[102:105]
	v_mfma_f32_16x16x32_bf16 v[106:109], v[142:145], v[16:19], v[106:109]
	v_mfma_f32_16x16x32_bf16 v[110:113], v[146:149], v[16:19], v[110:113]
	s_add_u32 s100, s10, 0x11e18180
	s_addc_u32 s101, s11, 0
	s_mov_b32 m0, s18
	s_nop 0
	global_load_lds_dwordx4 v241, s[100:101]
	s_waitcnt vmcnt(0)
	s_waitcnt vmcnt(0)
	s_barrier
	v_mov_b32_e32 v37, v48
	ds_read_b128 v[114:117], v37
	ds_read_b128 v[118:121], v37 offset:2048
	s_waitcnt lgkmcnt(0)
	v_mfma_f32_16x16x32_bf16 v[42:45], v[114:117], v[12:15], v[42:45]
	ds_read_b128 v[114:117], v37 offset:4096
	v_mfma_f32_16x16x32_bf16 v[50:53], v[118:121], v[12:15], v[50:53]
	ds_read_b128 v[118:121], v37 offset:6144
	s_waitcnt lgkmcnt(0)
	v_mfma_f32_16x16x32_bf16 v[38:41], v[114:117], v[12:15], v[38:41]
	ds_read_b128 v[114:117], v37 offset:8192
	v_mfma_f32_16x16x32_bf16 v[74:77], v[118:121], v[12:15], v[74:77]
	ds_read_b128 v[118:121], v37 offset:10240
	s_waitcnt lgkmcnt(0)
	v_mfma_f32_16x16x32_bf16 v[66:69], v[114:117], v[12:15], v[66:69]
	ds_read_b128 v[114:117], v37 offset:12288
	ds_read_b128 v[122:125], v37 offset:14336
	v_mfma_f32_16x16x32_bf16 v[70:73], v[118:121], v[12:15], v[70:73]
	ds_read_b128 v[118:121], v37 offset:32768
	ds_read_b128 v[126:129], v37 offset:34816
	ds_read_b128 v[130:133], v37 offset:36864
	ds_read_b128 v[134:137], v37 offset:38912
	s_waitcnt lgkmcnt(0)
	v_mfma_f32_16x16x32_bf16 v[60:63], v[114:117], v[12:15], v[60:63]
	ds_read_b128 v[114:117], v37 offset:40960
	ds_read_b128 v[138:141], v37 offset:43008
	ds_read_b128 v[142:145], v37 offset:45056
	ds_read_b128 v[146:149], v37 offset:47104
	v_mfma_f32_16x16x32_bf16 v[78:81], v[122:125], v[12:15], v[78:81]
	s_add_u32 s100, s10, 0x11e20000
	s_addc_u32 s101, s11, 0
	s_mov_b32 m0, s22
	s_nop 0
	global_load_lds_dwordx4 v241, s[100:101]
	v_mfma_f32_16x16x32_bf16 v[82:85], v[118:121], v[12:15], v[82:85]
	v_mfma_f32_16x16x32_bf16 v[86:89], v[126:129], v[12:15], v[86:89]
	v_mfma_f32_16x16x32_bf16 v[90:93], v[130:133], v[12:15], v[90:93]
	v_mfma_f32_16x16x32_bf16 v[94:97], v[134:137], v[12:15], v[94:97]
	s_waitcnt lgkmcnt(0)
	v_mfma_f32_16x16x32_bf16 v[98:101], v[114:117], v[12:15], v[98:101]
	ds_read_b128 v[114:117], v37 offset:30720
	ds_read_b128 v[118:121], v37 offset:28672
	ds_read_b128 v[122:125], v37 offset:26624
	ds_read_b128 v[126:129], v37 offset:24576
	v_mfma_f32_16x16x32_bf16 v[102:105], v[138:141], v[12:15], v[102:105]
	v_mfma_f32_16x16x32_bf16 v[106:109], v[142:145], v[12:15], v[106:109]
	ds_read_b128 v[130:133], v37 offset:22528
	ds_read_b128 v[134:137], v37 offset:20480
	ds_read_b128 v[138:141], v37 offset:18432
	ds_read_b128 v[142:145], v37 offset:16384
	v_mfma_f32_16x16x32_bf16 v[110:113], v[146:149], v[12:15], v[110:113]
	s_add_u32 s100, s10, 0x11e28000
	s_addc_u32 s101, s11, 0
	s_mov_b32 m0, s21
	s_nop 0
	global_load_lds_dwordx4 v241, s[100:101]
	s_waitcnt lgkmcnt(0)
	v_mfma_f32_16x16x32_bf16 v[42:45], v[142:145], v[8:11], v[42:45]
	v_mfma_f32_16x16x32_bf16 v[50:53], v[138:141], v[8:11], v[50:53]
	v_mfma_f32_16x16x32_bf16 v[38:41], v[134:137], v[8:11], v[38:41]
	v_mfma_f32_16x16x32_bf16 v[74:77], v[130:133], v[8:11], v[74:77]
	v_mfma_f32_16x16x32_bf16 v[66:69], v[126:129], v[8:11], v[66:69]
	v_mfma_f32_16x16x32_bf16 v[70:73], v[122:125], v[8:11], v[70:73]
	ds_read_b128 v[122:125], v37 offset:49152
	ds_read_b128 v[126:129], v37 offset:51200
	ds_read_b128 v[130:133], v37 offset:53248
	ds_read_b128 v[134:137], v37 offset:55296
	v_mfma_f32_16x16x32_bf16 v[60:63], v[118:121], v[8:11], v[60:63]
	ds_read_b128 v[118:121], v37 offset:57344
	ds_read_b128 v[138:141], v37 offset:59392
	ds_read_b128 v[142:145], v37 offset:61440
	ds_read_b128 v[146:149], v37 offset:63488
	v_mfma_f32_16x16x32_bf16 v[78:81], v[114:117], v[8:11], v[78:81]
	s_add_u32 s100, s10, 0x11e20080
	s_addc_u32 s101, s11, 0
	s_mov_b32 m0, s20
	s_nop 0
	global_load_lds_dwordx4 v241, s[100:101]
	s_waitcnt lgkmcnt(0)
	v_mfma_f32_16x16x32_bf16 v[82:85], v[122:125], v[8:11], v[82:85]
	v_mfma_f32_16x16x32_bf16 v[86:89], v[126:129], v[8:11], v[86:89]
	v_mfma_f32_16x16x32_bf16 v[90:93], v[130:133], v[8:11], v[90:93]
	v_mfma_f32_16x16x32_bf16 v[94:97], v[134:137], v[8:11], v[94:97]
	v_mfma_f32_16x16x32_bf16 v[98:101], v[118:121], v[8:11], v[98:101]
	ds_read_b128 v[114:117], v37 offset:15360
	ds_read_b128 v[118:121], v37 offset:13312
	ds_read_b128 v[122:125], v37 offset:11264
	ds_read_b128 v[126:129], v37 offset:9216
	v_mfma_f32_16x16x32_bf16 v[102:105], v[138:141], v[8:11], v[102:105]
	v_mfma_f32_16x16x32_bf16 v[106:109], v[142:145], v[8:11], v[106:109]
	ds_read_b128 v[130:133], v37 offset:7168
	ds_read_b128 v[134:137], v37 offset:5120
	ds_read_b128 v[138:141], v37 offset:3072
	ds_read_b128 v[142:145], v37 offset:1024
	v_mfma_f32_16x16x32_bf16 v[110:113], v[146:149], v[8:11], v[110:113]
	s_add_u32 s100, s10, 0x11e28080
	s_addc_u32 s101, s11, 0
	s_mov_b32 m0, s23
	s_nop 0
	global_load_lds_dwordx4 v241, s[100:101]
	s_waitcnt lgkmcnt(0)
	v_mfma_f32_16x16x32_bf16 v[42:45], v[142:145], v[4:7], v[42:45]
	v_mfma_f32_16x16x32_bf16 v[50:53], v[138:141], v[4:7], v[50:53]
	v_mfma_f32_16x16x32_bf16 v[38:41], v[134:137], v[4:7], v[38:41]
	v_mfma_f32_16x16x32_bf16 v[74:77], v[130:133], v[4:7], v[74:77]
	v_mfma_f32_16x16x32_bf16 v[66:69], v[126:129], v[4:7], v[66:69]
	v_mfma_f32_16x16x32_bf16 v[70:73], v[122:125], v[4:7], v[70:73]
	ds_read_b128 v[122:125], v37 offset:33792
	ds_read_b128 v[126:129], v37 offset:35840
	ds_read_b128 v[130:133], v37 offset:37888
	ds_read_b128 v[134:137], v37 offset:39936
	v_mfma_f32_16x16x32_bf16 v[60:63], v[118:121], v[4:7], v[60:63]
	ds_read_b128 v[118:121], v37 offset:41984
	ds_read_b128 v[138:141], v37 offset:44032
	ds_read_b128 v[142:145], v37 offset:46080
	ds_read_b128 v[146:149], v37 offset:48128
	v_mfma_f32_16x16x32_bf16 v[78:81], v[114:117], v[4:7], v[78:81]
	s_add_u32 s100, s10, 0x11e30000
	s_addc_u32 s101, s11, 0
	s_mov_b32 m0, s24
	s_nop 0
	global_load_lds_dwordx4 v241, s[100:101]
	s_waitcnt lgkmcnt(0)
	v_mfma_f32_16x16x32_bf16 v[82:85], v[122:125], v[4:7], v[82:85]
	v_mfma_f32_16x16x32_bf16 v[86:89], v[126:129], v[4:7], v[86:89]
	v_mfma_f32_16x16x32_bf16 v[90:93], v[130:133], v[4:7], v[90:93]
	v_mfma_f32_16x16x32_bf16 v[94:97], v[134:137], v[4:7], v[94:97]
	v_mfma_f32_16x16x32_bf16 v[98:101], v[118:121], v[4:7], v[98:101]
	ds_read_b128 v[114:117], v37 offset:31744
	ds_read_b128 v[118:121], v37 offset:29696
	ds_read_b128 v[122:125], v37 offset:27648
	ds_read_b128 v[126:129], v37 offset:25600
	v_mfma_f32_16x16x32_bf16 v[102:105], v[138:141], v[4:7], v[102:105]
	v_mfma_f32_16x16x32_bf16 v[106:109], v[142:145], v[4:7], v[106:109]
	ds_read_b128 v[130:133], v37 offset:23552
	ds_read_b128 v[134:137], v37 offset:21504
	ds_read_b128 v[138:141], v37 offset:19456
	ds_read_b128 v[142:145], v37 offset:17408
	v_mfma_f32_16x16x32_bf16 v[110:113], v[146:149], v[4:7], v[110:113]
	s_add_u32 s100, s10, 0x11e38000
	s_addc_u32 s101, s11, 0
	s_mov_b32 m0, s25
	s_nop 0
	global_load_lds_dwordx4 v241, s[100:101]
	s_waitcnt lgkmcnt(0)
	v_mfma_f32_16x16x32_bf16 v[42:45], v[142:145], v[0:3], v[42:45]
	v_mfma_f32_16x16x32_bf16 v[50:53], v[138:141], v[0:3], v[50:53]
	v_mfma_f32_16x16x32_bf16 v[38:41], v[134:137], v[0:3], v[38:41]
	v_mfma_f32_16x16x32_bf16 v[74:77], v[130:133], v[0:3], v[74:77]
	v_mfma_f32_16x16x32_bf16 v[66:69], v[126:129], v[0:3], v[66:69]
	v_mfma_f32_16x16x32_bf16 v[70:73], v[122:125], v[0:3], v[70:73]
	ds_read_b128 v[122:125], v37 offset:50176
	ds_read_b128 v[126:129], v37 offset:52224
	ds_read_b128 v[130:133], v37 offset:54272
	ds_read_b128 v[134:137], v37 offset:56320
	v_mfma_f32_16x16x32_bf16 v[60:63], v[118:121], v[0:3], v[60:63]
	ds_read_b128 v[118:121], v37 offset:58368
	ds_read_b128 v[138:141], v37 offset:60416
	ds_read_b128 v[142:145], v37 offset:62464
	ds_read_b128 v[146:149], v37 offset:64512
	v_mfma_f32_16x16x32_bf16 v[78:81], v[114:117], v[0:3], v[78:81]
	s_add_u32 s100, s10, 0x11e30080
	s_addc_u32 s101, s11, 0
	s_mov_b32 m0, s26
	s_nop 0
	global_load_lds_dwordx4 v241, s[100:101]
	s_waitcnt lgkmcnt(0)
	v_mfma_f32_16x16x32_bf16 v[82:85], v[122:125], v[0:3], v[82:85]
	v_mfma_f32_16x16x32_bf16 v[86:89], v[126:129], v[0:3], v[86:89]
	v_mfma_f32_16x16x32_bf16 v[90:93], v[130:133], v[0:3], v[90:93]
	v_mfma_f32_16x16x32_bf16 v[94:97], v[134:137], v[0:3], v[94:97]
	v_mfma_f32_16x16x32_bf16 v[98:101], v[118:121], v[0:3], v[98:101]
	v_mfma_f32_16x16x32_bf16 v[102:105], v[138:141], v[0:3], v[102:105]
	v_mfma_f32_16x16x32_bf16 v[106:109], v[142:145], v[0:3], v[106:109]
	v_mfma_f32_16x16x32_bf16 v[110:113], v[146:149], v[0:3], v[110:113]
	s_add_u32 s100, s10, 0x11e38080
	s_addc_u32 s101, s11, 0
	s_mov_b32 m0, s27
	s_nop 0
	global_load_lds_dwordx4 v241, s[100:101]
	s_mov_b32 s0, 0x1000000
	v_add_co_u32_e32 v34, vcc, s0, v34
	v_addc_co_u32_e32 v35, vcc, 0, v35, vcc
	v_mbcnt_lo_u32_b32 v212, -1, 0
	v_mbcnt_hi_u32_b32 v212, -1, v212
	v_lshrrev_b32_e32 v212, 4, v212
	v_and_b32_e32 v212, 1, v212
	v_mul_u32_u24_e32 v212, 24, v212
	v_mov_b32_e32 v213, 0
	v_lshl_add_u64 v[214:215], v[32:33], 0, v[212:213]
	v_mul_f32_e32 v200, v36, v42
	v_mul_f32_e32 v204, v36, v43
	v_cvt_pk_bf16_f32 v200, v200, v204
	v_mul_f32_e32 v201, v36, v44
	v_mul_f32_e32 v204, v36, v45
	v_cvt_pk_bf16_f32 v201, v201, v204
	v_mul_f32_e32 v202, v36, v50
	v_mul_f32_e32 v204, v36, v51
	v_cvt_pk_bf16_f32 v202, v202, v204
	v_mul_f32_e32 v203, v36, v52
	v_mul_f32_e32 v204, v36, v53
	v_cvt_pk_bf16_f32 v203, v203, v204
	s_nop 1
	v_permlane16_swap_b32_e32 v200, v202
	v_permlane16_swap_b32_e32 v201, v203
	global_store_dwordx4 v[214:215], v[200:203], off offset:0
	v_mul_f32_e32 v206, v36, v38
	v_mul_f32_e32 v210, v36, v39
	v_cvt_pk_bf16_f32 v206, v206, v210
	v_mul_f32_e32 v207, v36, v40
	v_mul_f32_e32 v210, v36, v41
	v_cvt_pk_bf16_f32 v207, v207, v210
	v_mul_f32_e32 v208, v36, v74
	v_mul_f32_e32 v210, v36, v75
	v_cvt_pk_bf16_f32 v208, v208, v210
	v_mul_f32_e32 v209, v36, v76
	v_mul_f32_e32 v210, v36, v77
	v_cvt_pk_bf16_f32 v209, v209, v210
	s_nop 1
	v_permlane16_swap_b32_e32 v206, v208
	v_permlane16_swap_b32_e32 v207, v209
	global_store_dwordx4 v[214:215], v[206:209], off offset:64
	v_mul_f32_e32 v200, v36, v66
	v_mul_f32_e32 v204, v36, v67
	v_cvt_pk_bf16_f32 v200, v200, v204
	v_mul_f32_e32 v201, v36, v68
	v_mul_f32_e32 v204, v36, v69
	v_cvt_pk_bf16_f32 v201, v201, v204
	v_mul_f32_e32 v202, v36, v70
	v_mul_f32_e32 v204, v36, v71
	v_cvt_pk_bf16_f32 v202, v202, v204
	v_mul_f32_e32 v203, v36, v72
	v_mul_f32_e32 v204, v36, v73
	v_cvt_pk_bf16_f32 v203, v203, v204
	s_nop 1
	v_permlane16_swap_b32_e32 v200, v202
	v_permlane16_swap_b32_e32 v201, v203
	global_store_dwordx4 v[214:215], v[200:203], off offset:128
	v_mul_f32_e32 v206, v36, v60
	v_mul_f32_e32 v210, v36, v61
	v_cvt_pk_bf16_f32 v206, v206, v210
	v_mul_f32_e32 v207, v36, v62
	v_mul_f32_e32 v210, v36, v63
	v_cvt_pk_bf16_f32 v207, v207, v210
	v_mul_f32_e32 v208, v36, v78
	v_mul_f32_e32 v210, v36, v79
	v_cvt_pk_bf16_f32 v208, v208, v210
	v_mul_f32_e32 v209, v36, v80
	v_mul_f32_e32 v210, v36, v81
	v_cvt_pk_bf16_f32 v209, v209, v210
	s_nop 1
	v_permlane16_swap_b32_e32 v206, v208
	v_permlane16_swap_b32_e32 v207, v209
	global_store_dwordx4 v[214:215], v[206:209], off offset:192
	v_mul_f32_e32 v200, v36, v82
	v_mul_f32_e32 v204, v36, v83
	v_cvt_pk_bf16_f32 v200, v200, v204
	v_mul_f32_e32 v201, v36, v84
	v_mul_f32_e32 v204, v36, v85
	v_cvt_pk_bf16_f32 v201, v201, v204
	v_mul_f32_e32 v202, v36, v86
	v_mul_f32_e32 v204, v36, v87
	v_cvt_pk_bf16_f32 v202, v202, v204
	v_mul_f32_e32 v203, v36, v88
	v_mul_f32_e32 v204, v36, v89
	v_cvt_pk_bf16_f32 v203, v203, v204
	s_nop 1
	v_permlane16_swap_b32_e32 v200, v202
	v_permlane16_swap_b32_e32 v201, v203
	global_store_dwordx4 v[214:215], v[200:203], off offset:256
	v_mul_f32_e32 v206, v36, v90
	v_mul_f32_e32 v210, v36, v91
	v_cvt_pk_bf16_f32 v206, v206, v210
	v_mul_f32_e32 v207, v36, v92
	v_mul_f32_e32 v210, v36, v93
	v_cvt_pk_bf16_f32 v207, v207, v210
	v_mul_f32_e32 v208, v36, v94
	v_mul_f32_e32 v210, v36, v95
	v_cvt_pk_bf16_f32 v208, v208, v210
	v_mul_f32_e32 v209, v36, v96
	v_mul_f32_e32 v210, v36, v97
	v_cvt_pk_bf16_f32 v209, v209, v210
	s_nop 1
	v_permlane16_swap_b32_e32 v206, v208
	v_permlane16_swap_b32_e32 v207, v209
	global_store_dwordx4 v[214:215], v[206:209], off offset:320
	v_mul_f32_e32 v200, v36, v98
	v_mul_f32_e32 v204, v36, v99
	v_cvt_pk_bf16_f32 v200, v200, v204
	v_mul_f32_e32 v201, v36, v100
	v_mul_f32_e32 v204, v36, v101
	v_cvt_pk_bf16_f32 v201, v201, v204
	v_mul_f32_e32 v202, v36, v102
	v_mul_f32_e32 v204, v36, v103
	v_cvt_pk_bf16_f32 v202, v202, v204
	v_mul_f32_e32 v203, v36, v104
	v_mul_f32_e32 v204, v36, v105
	v_cvt_pk_bf16_f32 v203, v203, v204
	s_nop 1
	v_permlane16_swap_b32_e32 v200, v202
	v_permlane16_swap_b32_e32 v201, v203
	global_store_dwordx4 v[214:215], v[200:203], off offset:384
	v_mul_f32_e32 v206, v36, v106
	v_mul_f32_e32 v210, v36, v107
	v_cvt_pk_bf16_f32 v206, v206, v210
	v_mul_f32_e32 v207, v36, v108
	v_mul_f32_e32 v210, v36, v109
	v_cvt_pk_bf16_f32 v207, v207, v210
	v_mul_f32_e32 v208, v36, v110
	v_mul_f32_e32 v210, v36, v111
	v_cvt_pk_bf16_f32 v208, v208, v210
	v_mul_f32_e32 v209, v36, v112
	v_mul_f32_e32 v210, v36, v113
	v_cvt_pk_bf16_f32 v209, v209, v210
	s_nop 1
	v_permlane16_swap_b32_e32 v206, v208
	v_permlane16_swap_b32_e32 v207, v209
	global_store_dwordx4 v[214:215], v[206:209], off offset:448
	s_waitcnt vmcnt(8)
	s_waitcnt vmcnt(8)
	s_barrier
	ds_read_b128 v[38:41], v65
	ds_read_b128 v[42:45], v65 offset:2048
	ds_read_b128 v[50:53], v65 offset:4096
	ds_read_b128 v[54:57], v65 offset:6144
	ds_read_b128 v[58:61], v65 offset:8192
	ds_read_b128 v[66:69], v65 offset:10240
	ds_read_b128 v[70:73], v65 offset:12288
	ds_read_b128 v[74:77], v65 offset:14336
	ds_read_b128 v[78:81], v65 offset:32768
	ds_read_b128 v[82:85], v65 offset:34816
	ds_read_b128 v[86:89], v65 offset:36864
	ds_read_b128 v[90:93], v65 offset:38912
	ds_read_b128 v[94:97], v65 offset:40960
	ds_read_b128 v[98:101], v65 offset:43008
	ds_read_b128 v[102:105], v65 offset:45056
	ds_read_b128 v[106:109], v65 offset:47104
	s_waitcnt lgkmcnt(0)
	v_mfma_f32_16x16x32_bf16 v[38:41], v[38:41], v[28:31], 0
	v_mfma_f32_16x16x32_bf16 v[42:45], v[42:45], v[28:31], 0
	v_mfma_f32_16x16x32_bf16 v[50:53], v[50:53], v[28:31], 0
	v_mfma_f32_16x16x32_bf16 v[54:57], v[54:57], v[28:31], 0
	v_mfma_f32_16x16x32_bf16 v[58:61], v[58:61], v[28:31], 0
	v_mfma_f32_16x16x32_bf16 v[66:69], v[66:69], v[28:31], 0
	v_mfma_f32_16x16x32_bf16 v[70:73], v[70:73], v[28:31], 0
	v_mfma_f32_16x16x32_bf16 v[74:77], v[74:77], v[28:31], 0
	s_add_u32 s100, s10, 0x11e20100
	s_addc_u32 s101, s11, 0
	s_mov_b32 m0, s19
	s_nop 0
	global_load_lds_dwordx4 v241, s[100:101]
	ds_read_b128 v[110:113], v65 offset:30720
	ds_read_b128 v[114:117], v65 offset:28672
	ds_read_b128 v[118:121], v65 offset:26624
	ds_read_b128 v[122:125], v65 offset:24576
	ds_read_b128 v[126:129], v65 offset:22528
	ds_read_b128 v[130:133], v65 offset:20480
	ds_read_b128 v[134:137], v65 offset:18432
	ds_read_b128 v[138:141], v65 offset:16384
	v_mfma_f32_16x16x32_bf16 v[78:81], v[78:81], v[28:31], 0
	v_mfma_f32_16x16x32_bf16 v[82:85], v[82:85], v[28:31], 0
	v_mfma_f32_16x16x32_bf16 v[86:89], v[86:89], v[28:31], 0
	v_mfma_f32_16x16x32_bf16 v[90:93], v[90:93], v[28:31], 0
	v_mfma_f32_16x16x32_bf16 v[94:97], v[94:97], v[28:31], 0
	v_mfma_f32_16x16x32_bf16 v[98:101], v[98:101], v[28:31], 0
	v_mfma_f32_16x16x32_bf16 v[102:105], v[102:105], v[28:31], 0
	v_mfma_f32_16x16x32_bf16 v[28:31], v[106:109], v[28:31], 0
	s_add_u32 s100, s10, 0x11e28100
	s_addc_u32 s101, s11, 0
	s_mov_b32 m0, s13
	s_nop 0
	global_load_lds_dwordx4 v241, s[100:101]
	s_waitcnt lgkmcnt(0)
	v_mfma_f32_16x16x32_bf16 v[38:41], v[138:141], v[24:27], v[38:41]
	v_mfma_f32_16x16x32_bf16 v[42:45], v[134:137], v[24:27], v[42:45]
	v_mfma_f32_16x16x32_bf16 v[50:53], v[130:133], v[24:27], v[50:53]
	v_mfma_f32_16x16x32_bf16 v[54:57], v[126:129], v[24:27], v[54:57]
	v_mfma_f32_16x16x32_bf16 v[58:61], v[122:125], v[24:27], v[58:61]
	v_mfma_f32_16x16x32_bf16 v[66:69], v[118:121], v[24:27], v[66:69]
	ds_read_b128 v[106:109], v65 offset:49152
	ds_read_b128 v[118:121], v65 offset:51200
	ds_read_b128 v[122:125], v65 offset:53248
	ds_read_b128 v[126:129], v65 offset:55296
	v_mfma_f32_16x16x32_bf16 v[70:73], v[114:117], v[24:27], v[70:73]
	ds_read_b128 v[114:117], v65 offset:57344
	ds_read_b128 v[130:133], v65 offset:59392
	ds_read_b128 v[134:137], v65 offset:61440
	ds_read_b128 v[138:141], v65 offset:63488
	v_mfma_f32_16x16x32_bf16 v[74:77], v[110:113], v[24:27], v[74:77]
	s_add_u32 s100, s10, 0x11e20180
	s_addc_u32 s101, s11, 0
	s_mov_b32 m0, s12
	s_nop 0
	global_load_lds_dwordx4 v241, s[100:101]
	s_waitcnt lgkmcnt(0)
	v_mfma_f32_16x16x32_bf16 v[78:81], v[106:109], v[24:27], v[78:81]
	v_mfma_f32_16x16x32_bf16 v[82:85], v[118:121], v[24:27], v[82:85]
	v_mfma_f32_16x16x32_bf16 v[86:89], v[122:125], v[24:27], v[86:89]
	v_mfma_f32_16x16x32_bf16 v[90:93], v[126:129], v[24:27], v[90:93]
	v_mfma_f32_16x16x32_bf16 v[94:97], v[114:117], v[24:27], v[94:97]
	ds_read_b128 v[106:109], v65 offset:15360
	ds_read_b128 v[110:113], v65 offset:13312
	ds_read_b128 v[114:117], v65 offset:11264
	ds_read_b128 v[118:121], v65 offset:9216
	v_mfma_f32_16x16x32_bf16 v[98:101], v[130:133], v[24:27], v[98:101]
	v_mfma_f32_16x16x32_bf16 v[102:105], v[134:137], v[24:27], v[102:105]
	ds_read_b128 v[122:125], v65 offset:7168
	ds_read_b128 v[126:129], v65 offset:5120
	ds_read_b128 v[130:133], v65 offset:3072
	ds_read_b128 v[134:137], v65 offset:1024
	v_mfma_f32_16x16x32_bf16 v[24:27], v[138:141], v[24:27], v[28:31]
	s_add_u32 s100, s10, 0x11e28180
	s_addc_u32 s101, s11, 0
	s_mov_b32 m0, s14
	s_nop 0
	global_load_lds_dwordx4 v241, s[100:101]
	s_waitcnt lgkmcnt(0)
	v_mfma_f32_16x16x32_bf16 v[28:31], v[134:137], v[20:23], v[38:41]
	v_mfma_f32_16x16x32_bf16 v[38:41], v[130:133], v[20:23], v[42:45]
	v_mfma_f32_16x16x32_bf16 v[42:45], v[126:129], v[20:23], v[50:53]
	v_mfma_f32_16x16x32_bf16 v[50:53], v[122:125], v[20:23], v[54:57]
	v_mfma_f32_16x16x32_bf16 v[54:57], v[118:121], v[20:23], v[58:61]
	v_mfma_f32_16x16x32_bf16 v[58:61], v[114:117], v[20:23], v[66:69]
	s_nop 2
	ds_read_b128 v[66:69], v65 offset:33792
	ds_read_b128 v[114:117], v65 offset:35840
	ds_read_b128 v[118:121], v65 offset:37888
	ds_read_b128 v[122:125], v65 offset:39936
	v_mfma_f32_16x16x32_bf16 v[70:73], v[110:113], v[20:23], v[70:73]
	ds_read_b128 v[110:113], v65 offset:41984
	ds_read_b128 v[126:129], v65 offset:44032
	ds_read_b128 v[130:133], v65 offset:46080
	ds_read_b128 v[134:137], v65 offset:48128
	v_mfma_f32_16x16x32_bf16 v[74:77], v[106:109], v[20:23], v[74:77]
	s_add_u32 s100, s10, 0x11e30100
	s_addc_u32 s101, s11, 0
	s_mov_b32 m0, s15
	s_nop 0
	global_load_lds_dwordx4 v241, s[100:101]
	s_waitcnt lgkmcnt(0)
	v_mfma_f32_16x16x32_bf16 v[66:69], v[66:69], v[20:23], v[78:81]
	v_mfma_f32_16x16x32_bf16 v[78:81], v[114:117], v[20:23], v[82:85]
	v_mfma_f32_16x16x32_bf16 v[82:85], v[118:121], v[20:23], v[86:89]
	v_mfma_f32_16x16x32_bf16 v[86:89], v[122:125], v[20:23], v[90:93]
	v_mfma_f32_16x16x32_bf16 v[90:93], v[110:113], v[20:23], v[94:97]
	v_mfma_f32_16x16x32_bf16 v[94:97], v[126:129], v[20:23], v[98:101]
	s_nop 2
	ds_read_b128 v[98:101], v65 offset:31744
	ds_read_b128 v[106:109], v65 offset:29696
	ds_read_b128 v[110:113], v65 offset:27648
	ds_read_b128 v[114:117], v65 offset:25600
	v_mfma_f32_16x16x32_bf16 v[102:105], v[130:133], v[20:23], v[102:105]
	ds_read_b128 v[118:121], v65 offset:23552
	ds_read_b128 v[122:125], v65 offset:21504
	ds_read_b128 v[126:129], v65 offset:19456
	ds_read_b128 v[130:133], v65 offset:17408
	v_mfma_f32_16x16x32_bf16 v[20:23], v[134:137], v[20:23], v[24:27]
	s_add_u32 s100, s10, 0x11e38100
	s_addc_u32 s101, s11, 0
	s_mov_b32 m0, s16
	s_nop 0
	global_load_lds_dwordx4 v241, s[100:101]
	s_waitcnt lgkmcnt(0)
	v_mfma_f32_16x16x32_bf16 v[24:27], v[130:133], v[16:19], v[28:31]
	v_mfma_f32_16x16x32_bf16 v[28:31], v[126:129], v[16:19], v[38:41]
	v_mfma_f32_16x16x32_bf16 v[38:41], v[122:125], v[16:19], v[42:45]
	v_mfma_f32_16x16x32_bf16 v[42:45], v[118:121], v[16:19], v[50:53]
	v_mfma_f32_16x16x32_bf16 v[50:53], v[114:117], v[16:19], v[54:57]
	v_mfma_f32_16x16x32_bf16 v[54:57], v[110:113], v[16:19], v[58:61]
	s_nop 2
	ds_read_b128 v[58:61], v65 offset:50176
	ds_read_b128 v[110:113], v65 offset:52224
	ds_read_b128 v[114:117], v65 offset:54272
	ds_read_b128 v[118:121], v65 offset:56320
	v_mfma_f32_16x16x32_bf16 v[70:73], v[106:109], v[16:19], v[70:73]
	ds_read_b128 v[106:109], v65 offset:58368
	ds_read_b128 v[122:125], v65 offset:60416
	ds_read_b128 v[126:129], v65 offset:62464
	ds_read_b128 v[62:65], v65 offset:64512
	v_mfma_f32_16x16x32_bf16 v[74:77], v[98:101], v[16:19], v[74:77]
	s_add_u32 s100, s10, 0x11e30180
	s_addc_u32 s101, s11, 0
	s_mov_b32 m0, s17
	s_nop 0
	global_load_lds_dwordx4 v241, s[100:101]
	s_waitcnt lgkmcnt(0)
	v_mfma_f32_16x16x32_bf16 v[58:61], v[58:61], v[16:19], v[66:69]
	v_mfma_f32_16x16x32_bf16 v[66:69], v[110:113], v[16:19], v[78:81]
	v_mfma_f32_16x16x32_bf16 v[78:81], v[114:117], v[16:19], v[82:85]
	v_mfma_f32_16x16x32_bf16 v[82:85], v[118:121], v[16:19], v[86:89]
	v_mfma_f32_16x16x32_bf16 v[86:89], v[106:109], v[16:19], v[90:93]
	v_mfma_f32_16x16x32_bf16 v[90:93], v[122:125], v[16:19], v[94:97]
	v_mfma_f32_16x16x32_bf16 v[94:97], v[126:129], v[16:19], v[102:105]
	v_mfma_f32_16x16x32_bf16 v[16:19], v[62:65], v[16:19], v[20:23]
	s_add_u32 s100, s10, 0x11e38180
	s_addc_u32 s101, s11, 0
	s_mov_b32 m0, s18
	s_nop 0
	global_load_lds_dwordx4 v241, s[100:101]
	s_waitcnt vmcnt(0)
	s_waitcnt vmcnt(0)
	s_barrier
	s_nop 0
	ds_read_b128 v[20:23], v48
	ds_read_b128 v[62:65], v48 offset:2048
	s_waitcnt lgkmcnt(1)
	v_mfma_f32_16x16x32_bf16 v[20:23], v[20:23], v[12:15], v[24:27]
	s_nop 2
	ds_read_b128 v[24:27], v48 offset:4096
	s_waitcnt lgkmcnt(1)
	v_mfma_f32_16x16x32_bf16 v[28:31], v[62:65], v[12:15], v[28:31]
	ds_read_b128 v[62:65], v48 offset:6144
	s_waitcnt lgkmcnt(1)
	v_mfma_f32_16x16x32_bf16 v[24:27], v[24:27], v[12:15], v[38:41]
	s_nop 2
	ds_read_b128 v[38:41], v48 offset:8192
	s_waitcnt lgkmcnt(1)
	v_mfma_f32_16x16x32_bf16 v[42:45], v[62:65], v[12:15], v[42:45]
	ds_read_b128 v[62:65], v48 offset:10240
	s_waitcnt lgkmcnt(1)
	v_mfma_f32_16x16x32_bf16 v[38:41], v[38:41], v[12:15], v[50:53]
	s_nop 2
	ds_read_b128 v[50:53], v48 offset:12288
	ds_read_b128 v[98:101], v48 offset:14336
	s_waitcnt lgkmcnt(2)
	v_mfma_f32_16x16x32_bf16 v[54:57], v[62:65], v[12:15], v[54:57]
	ds_read_b128 v[62:65], v48 offset:32768
	ds_read_b128 v[102:105], v48 offset:34816
	ds_read_b128 v[106:109], v48 offset:36864
	ds_read_b128 v[110:113], v48 offset:38912
	s_waitcnt lgkmcnt(5)
	v_mfma_f32_16x16x32_bf16 v[50:53], v[50:53], v[12:15], v[70:73]
	s_nop 2
	ds_read_b128 v[70:73], v48 offset:40960
	ds_read_b128 v[114:117], v48 offset:43008
	ds_read_b128 v[118:121], v48 offset:45056
	ds_read_b128 v[122:125], v48 offset:47104
	s_waitcnt lgkmcnt(8)
	v_mfma_f32_16x16x32_bf16 v[74:77], v[98:101], v[12:15], v[74:77]
	s_waitcnt lgkmcnt(7)
	v_mfma_f32_16x16x32_bf16 v[58:61], v[62:65], v[12:15], v[58:61]
	s_waitcnt lgkmcnt(6)
	v_mfma_f32_16x16x32_bf16 v[62:65], v[102:105], v[12:15], v[66:69]
	s_waitcnt lgkmcnt(5)
	v_mfma_f32_16x16x32_bf16 v[66:69], v[106:109], v[12:15], v[78:81]
	s_waitcnt lgkmcnt(4)
	v_mfma_f32_16x16x32_bf16 v[78:81], v[110:113], v[12:15], v[82:85]
	s_waitcnt lgkmcnt(3)
	v_mfma_f32_16x16x32_bf16 v[70:73], v[70:73], v[12:15], v[86:89]
	s_waitcnt lgkmcnt(2)
	v_mfma_f32_16x16x32_bf16 v[82:85], v[114:117], v[12:15], v[90:93]
	s_nop 0
	ds_read_b128 v[86:89], v48 offset:30720
	s_nop 0
	ds_read_b128 v[90:93], v48 offset:28672
	ds_read_b128 v[98:101], v48 offset:26624
	ds_read_b128 v[102:105], v48 offset:24576
	s_waitcnt lgkmcnt(5)
	v_mfma_f32_16x16x32_bf16 v[94:97], v[118:121], v[12:15], v[94:97]
	ds_read_b128 v[106:109], v48 offset:22528
	ds_read_b128 v[110:113], v48 offset:20480
	ds_read_b128 v[114:117], v48 offset:18432
	ds_read_b128 v[118:121], v48 offset:16384
	s_waitcnt lgkmcnt(8)
	v_mfma_f32_16x16x32_bf16 v[12:15], v[122:125], v[12:15], v[16:19]
	s_waitcnt lgkmcnt(0)
	v_mfma_f32_16x16x32_bf16 v[16:19], v[118:121], v[8:11], v[20:23]
	v_mfma_f32_16x16x32_bf16 v[20:23], v[114:117], v[8:11], v[28:31]
	v_mfma_f32_16x16x32_bf16 v[24:27], v[110:113], v[8:11], v[24:27]
	v_mfma_f32_16x16x32_bf16 v[28:31], v[106:109], v[8:11], v[42:45]
	v_mfma_f32_16x16x32_bf16 v[38:41], v[102:105], v[8:11], v[38:41]
	v_mfma_f32_16x16x32_bf16 v[42:45], v[98:101], v[8:11], v[54:57]
	s_nop 2
	ds_read_b128 v[54:57], v48 offset:49152
	ds_read_b128 v[98:101], v48 offset:51200
	ds_read_b128 v[102:105], v48 offset:53248
	ds_read_b128 v[106:109], v48 offset:55296
	v_mfma_f32_16x16x32_bf16 v[50:53], v[90:93], v[8:11], v[50:53]
	ds_read_b128 v[90:93], v48 offset:57344
	ds_read_b128 v[110:113], v48 offset:59392
	ds_read_b128 v[114:117], v48 offset:61440
	ds_read_b128 v[118:121], v48 offset:63488
	v_mfma_f32_16x16x32_bf16 v[74:77], v[86:89], v[8:11], v[74:77]
	s_waitcnt lgkmcnt(7)
	v_mfma_f32_16x16x32_bf16 v[54:57], v[54:57], v[8:11], v[58:61]
	s_waitcnt lgkmcnt(6)
	v_mfma_f32_16x16x32_bf16 v[58:61], v[98:101], v[8:11], v[62:65]
	s_waitcnt lgkmcnt(5)
	v_mfma_f32_16x16x32_bf16 v[62:65], v[102:105], v[8:11], v[66:69]
	s_waitcnt lgkmcnt(4)
	v_mfma_f32_16x16x32_bf16 v[66:69], v[106:109], v[8:11], v[78:81]
	s_waitcnt lgkmcnt(3)
	v_mfma_f32_16x16x32_bf16 v[70:73], v[90:93], v[8:11], v[70:73]
	s_waitcnt lgkmcnt(2)
	v_mfma_f32_16x16x32_bf16 v[78:81], v[110:113], v[8:11], v[82:85]
	s_nop 2
	ds_read_b128 v[82:85], v48 offset:15360
	ds_read_b128 v[86:89], v48 offset:13312
	ds_read_b128 v[90:93], v48 offset:11264
	ds_read_b128 v[98:101], v48 offset:9216
	s_waitcnt lgkmcnt(5)
	v_mfma_f32_16x16x32_bf16 v[94:97], v[114:117], v[8:11], v[94:97]
	ds_read_b128 v[102:105], v48 offset:7168
	ds_read_b128 v[106:109], v48 offset:5120
	ds_read_b128 v[110:113], v48 offset:3072
	ds_read_b128 v[114:117], v48 offset:1024
	s_waitcnt lgkmcnt(8)
	v_mfma_f32_16x16x32_bf16 v[8:11], v[118:121], v[8:11], v[12:15]
	s_waitcnt lgkmcnt(0)
	v_mfma_f32_16x16x32_bf16 v[12:15], v[114:117], v[4:7], v[16:19]
	v_mfma_f32_16x16x32_bf16 v[16:19], v[110:113], v[4:7], v[20:23]
	v_mfma_f32_16x16x32_bf16 v[20:23], v[106:109], v[4:7], v[24:27]
	v_mfma_f32_16x16x32_bf16 v[24:27], v[102:105], v[4:7], v[28:31]
	v_mfma_f32_16x16x32_bf16 v[28:31], v[98:101], v[4:7], v[38:41]
	v_mfma_f32_16x16x32_bf16 v[38:41], v[90:93], v[4:7], v[42:45]
	s_nop 2
	ds_read_b128 v[42:45], v48 offset:33792
	ds_read_b128 v[90:93], v48 offset:35840
	ds_read_b128 v[98:101], v48 offset:37888
	ds_read_b128 v[102:105], v48 offset:39936
	v_mfma_f32_16x16x32_bf16 v[50:53], v[86:89], v[4:7], v[50:53]
	ds_read_b128 v[86:89], v48 offset:41984
	ds_read_b128 v[106:109], v48 offset:44032
	ds_read_b128 v[110:113], v48 offset:46080
	ds_read_b128 v[114:117], v48 offset:48128
	v_mfma_f32_16x16x32_bf16 v[74:77], v[82:85], v[4:7], v[74:77]
	s_waitcnt lgkmcnt(7)
	v_mfma_f32_16x16x32_bf16 v[42:45], v[42:45], v[4:7], v[54:57]
	s_waitcnt lgkmcnt(6)
	v_mfma_f32_16x16x32_bf16 v[54:57], v[90:93], v[4:7], v[58:61]
	s_waitcnt lgkmcnt(5)
	v_mfma_f32_16x16x32_bf16 v[58:61], v[98:101], v[4:7], v[62:65]
	s_waitcnt lgkmcnt(4)
	v_mfma_f32_16x16x32_bf16 v[62:65], v[102:105], v[4:7], v[66:69]
	s_waitcnt lgkmcnt(3)
	v_mfma_f32_16x16x32_bf16 v[66:69], v[86:89], v[4:7], v[70:73]
	s_waitcnt lgkmcnt(2)
	v_mfma_f32_16x16x32_bf16 v[70:73], v[106:109], v[4:7], v[78:81]
	s_nop 2
	ds_read_b128 v[78:81], v48 offset:31744
	ds_read_b128 v[82:85], v48 offset:29696
	ds_read_b128 v[86:89], v48 offset:27648
	ds_read_b128 v[90:93], v48 offset:25600
	s_waitcnt lgkmcnt(5)
	v_mfma_f32_16x16x32_bf16 v[94:97], v[110:113], v[4:7], v[94:97]
	ds_read_b128 v[98:101], v48 offset:23552
	ds_read_b128 v[102:105], v48 offset:21504
	ds_read_b128 v[106:109], v48 offset:19456
	ds_read_b128 v[110:113], v48 offset:17408
	s_waitcnt lgkmcnt(8)
	v_mfma_f32_16x16x32_bf16 v[4:7], v[114:117], v[4:7], v[8:11]
	s_waitcnt lgkmcnt(0)
	v_mfma_f32_16x16x32_bf16 v[8:11], v[110:113], v[0:3], v[12:15]
	v_mfma_f32_16x16x32_bf16 v[12:15], v[106:109], v[0:3], v[16:19]
	v_mfma_f32_16x16x32_bf16 v[16:19], v[102:105], v[0:3], v[20:23]
	v_mfma_f32_16x16x32_bf16 v[20:23], v[98:101], v[0:3], v[24:27]
	v_mfma_f32_16x16x32_bf16 v[24:27], v[90:93], v[0:3], v[28:31]
	v_mfma_f32_16x16x32_bf16 v[28:31], v[86:89], v[0:3], v[38:41]
	s_nop 2
	ds_read_b128 v[38:41], v48 offset:50176
	ds_read_b128 v[86:89], v48 offset:52224
	ds_read_b128 v[90:93], v48 offset:54272
	ds_read_b128 v[98:101], v48 offset:56320
	v_mfma_f32_16x16x32_bf16 v[50:53], v[82:85], v[0:3], v[50:53]
	ds_read_b128 v[82:85], v48 offset:58368
	ds_read_b128 v[102:105], v48 offset:60416
	ds_read_b128 v[106:109], v48 offset:62464
	ds_read_b128 v[46:49], v48 offset:64512
	v_mfma_f32_16x16x32_bf16 v[74:77], v[78:81], v[0:3], v[74:77]
	s_waitcnt lgkmcnt(7)
	v_mfma_f32_16x16x32_bf16 v[38:41], v[38:41], v[0:3], v[42:45]
	s_waitcnt lgkmcnt(6)
	v_mfma_f32_16x16x32_bf16 v[42:45], v[86:89], v[0:3], v[54:57]
	s_waitcnt lgkmcnt(5)
	v_mfma_f32_16x16x32_bf16 v[54:57], v[90:93], v[0:3], v[58:61]
	s_waitcnt lgkmcnt(4)
	v_mfma_f32_16x16x32_bf16 v[58:61], v[98:101], v[0:3], v[62:65]
	s_waitcnt lgkmcnt(3)
	v_mfma_f32_16x16x32_bf16 v[62:65], v[82:85], v[0:3], v[66:69]
	s_waitcnt lgkmcnt(2)
	v_mfma_f32_16x16x32_bf16 v[66:69], v[102:105], v[0:3], v[70:73]
	s_waitcnt lgkmcnt(1)
	v_mfma_f32_16x16x32_bf16 v[70:73], v[106:109], v[0:3], v[94:97]
	s_waitcnt lgkmcnt(0)
	v_mfma_f32_16x16x32_bf16 v[0:3], v[46:49], v[0:3], v[4:7]
	s_nop 2
	v_mul_f32_e32 v200, v36, v8
	v_mul_f32_e32 v204, v36, v9
	v_cvt_pk_bf16_f32 v200, v200, v204
	v_mul_f32_e32 v201, v36, v10
	v_mul_f32_e32 v204, v36, v11
	v_cvt_pk_bf16_f32 v201, v201, v204
	v_mul_f32_e32 v202, v36, v12
	v_mul_f32_e32 v204, v36, v13
	v_cvt_pk_bf16_f32 v202, v202, v204
	v_mul_f32_e32 v203, v36, v14
	v_mul_f32_e32 v204, v36, v15
	v_cvt_pk_bf16_f32 v203, v203, v204
	s_nop 1
	v_permlane16_swap_b32_e32 v200, v202
	v_permlane16_swap_b32_e32 v201, v203
	global_store_dwordx4 v[214:215], v[200:203], off offset:512
	v_mul_f32_e32 v206, v36, v16
	v_mul_f32_e32 v210, v36, v17
	v_cvt_pk_bf16_f32 v206, v206, v210
	v_mul_f32_e32 v207, v36, v18
	v_mul_f32_e32 v210, v36, v19
	v_cvt_pk_bf16_f32 v207, v207, v210
	v_mul_f32_e32 v208, v36, v20
	v_mul_f32_e32 v210, v36, v21
	v_cvt_pk_bf16_f32 v208, v208, v210
	v_mul_f32_e32 v209, v36, v22
	v_mul_f32_e32 v210, v36, v23
	v_cvt_pk_bf16_f32 v209, v209, v210
	s_nop 1
	v_permlane16_swap_b32_e32 v206, v208
	v_permlane16_swap_b32_e32 v207, v209
	global_store_dwordx4 v[214:215], v[206:209], off offset:576
	v_mul_f32_e32 v200, v36, v24
	v_mul_f32_e32 v204, v36, v25
	v_cvt_pk_bf16_f32 v200, v200, v204
	v_mul_f32_e32 v201, v36, v26
	v_mul_f32_e32 v204, v36, v27
	v_cvt_pk_bf16_f32 v201, v201, v204
	v_mul_f32_e32 v202, v36, v28
	v_mul_f32_e32 v204, v36, v29
	v_cvt_pk_bf16_f32 v202, v202, v204
	v_mul_f32_e32 v203, v36, v30
	v_mul_f32_e32 v204, v36, v31
	v_cvt_pk_bf16_f32 v203, v203, v204
	s_nop 1
	v_permlane16_swap_b32_e32 v200, v202
	v_permlane16_swap_b32_e32 v201, v203
	global_store_dwordx4 v[214:215], v[200:203], off offset:640
	v_mul_f32_e32 v206, v36, v50
	v_mul_f32_e32 v210, v36, v51
	v_cvt_pk_bf16_f32 v206, v206, v210
	v_mul_f32_e32 v207, v36, v52
	v_mul_f32_e32 v210, v36, v53
	v_cvt_pk_bf16_f32 v207, v207, v210
	v_mul_f32_e32 v208, v36, v74
	v_mul_f32_e32 v210, v36, v75
	v_cvt_pk_bf16_f32 v208, v208, v210
	v_mul_f32_e32 v209, v36, v76
	v_mul_f32_e32 v210, v36, v77
	v_cvt_pk_bf16_f32 v209, v209, v210
	s_nop 1
	v_permlane16_swap_b32_e32 v206, v208
	v_permlane16_swap_b32_e32 v207, v209
	global_store_dwordx4 v[214:215], v[206:209], off offset:704
	v_mul_f32_e32 v200, v36, v38
	v_mul_f32_e32 v204, v36, v39
	v_cvt_pk_bf16_f32 v200, v200, v204
	v_mul_f32_e32 v201, v36, v40
	v_mul_f32_e32 v204, v36, v41
	v_cvt_pk_bf16_f32 v201, v201, v204
	v_mul_f32_e32 v202, v36, v42
	v_mul_f32_e32 v204, v36, v43
	v_cvt_pk_bf16_f32 v202, v202, v204
	v_mul_f32_e32 v203, v36, v44
	v_mul_f32_e32 v204, v36, v45
	v_cvt_pk_bf16_f32 v203, v203, v204
	s_nop 1
	v_permlane16_swap_b32_e32 v200, v202
	v_permlane16_swap_b32_e32 v201, v203
	global_store_dwordx4 v[214:215], v[200:203], off offset:768
	v_mul_f32_e32 v206, v36, v54
	v_mul_f32_e32 v210, v36, v55
	v_cvt_pk_bf16_f32 v206, v206, v210
	v_mul_f32_e32 v207, v36, v56
	v_mul_f32_e32 v210, v36, v57
	v_cvt_pk_bf16_f32 v207, v207, v210
	v_mul_f32_e32 v208, v36, v58
	v_mul_f32_e32 v210, v36, v59
	v_cvt_pk_bf16_f32 v208, v208, v210
	v_mul_f32_e32 v209, v36, v60
	v_mul_f32_e32 v210, v36, v61
	v_cvt_pk_bf16_f32 v209, v209, v210
	s_nop 1
	v_permlane16_swap_b32_e32 v206, v208
	v_permlane16_swap_b32_e32 v207, v209
	global_store_dwordx4 v[214:215], v[206:209], off offset:832
	v_mul_f32_e32 v200, v36, v62
	v_mul_f32_e32 v204, v36, v63
	v_cvt_pk_bf16_f32 v200, v200, v204
	v_mul_f32_e32 v201, v36, v64
	v_mul_f32_e32 v204, v36, v65
	v_cvt_pk_bf16_f32 v201, v201, v204
	v_mul_f32_e32 v202, v36, v66
	v_mul_f32_e32 v204, v36, v67
	v_cvt_pk_bf16_f32 v202, v202, v204
	v_mul_f32_e32 v203, v36, v68
	v_mul_f32_e32 v204, v36, v69
	v_cvt_pk_bf16_f32 v203, v203, v204
	s_nop 1
	v_permlane16_swap_b32_e32 v200, v202
	v_permlane16_swap_b32_e32 v201, v203
	global_store_dwordx4 v[214:215], v[200:203], off offset:896
	v_mul_f32_e32 v206, v36, v70
	v_mul_f32_e32 v210, v36, v71
	v_cvt_pk_bf16_f32 v206, v206, v210
	v_mul_f32_e32 v207, v36, v72
	v_mul_f32_e32 v210, v36, v73
	v_cvt_pk_bf16_f32 v207, v207, v210
	v_mul_f32_e32 v208, v36, v0
	v_mul_f32_e32 v210, v36, v1
	v_cvt_pk_bf16_f32 v208, v208, v210
	v_mul_f32_e32 v209, v36, v2
	v_mul_f32_e32 v210, v36, v3
	v_cvt_pk_bf16_f32 v209, v209, v210
	s_nop 1
	v_permlane16_swap_b32_e32 v206, v208
	v_permlane16_swap_b32_e32 v207, v209
	global_store_dwordx4 v[214:215], v[206:209], off offset:960
	s_waitcnt vmcnt(0)
	s_barrier
